# K-loops: MFMA issue order within each 8-group changed to a snake so consecutive MFMAs share one operand
# speedup vs baseline: 1.0034x; 1.0034x over previous
.LBB0_153:
	ds_read_b128 v[0:3], v145
	ds_read_b128 v[4:7], v145 offset:1024
	ds_read_b128 v[8:11], v145 offset:2048
	ds_read_b128 v[12:15], v145 offset:3072
	ds_read_b128 v[16:19], v146
	ds_read_b128 v[20:23], v146 offset:1024
	ds_read_b128 v[24:27], v146 offset:2048
	ds_read_b128 v[28:31], v146 offset:3072
	s_ashr_i32 s37, s36, 31
	s_lshl_b64 s[46:47], s[36:37], 17
	s_add_u32 s46, s44, s46
	s_addc_u32 s47, s45, s47
	s_and_b64 s[48:49], s[4:5], exec
	s_cselect_b32 s59, s47, s53
	s_cselect_b32 s58, s46, s52
	s_ashr_i32 s35, s34, 31
	s_lshl_b64 s[48:49], s[34:35], 17
	s_add_u32 s48, s60, s48
	s_addc_u32 s49, s61, s49
	s_and_b64 s[56:57], s[4:5], exec
	s_cselect_b32 s57, s49, s55
	s_cselect_b32 s56, s48, s54
	s_add_u32 s80, s52, 0x10080
	s_addc_u32 s81, s53, 0
	s_add_i32 s83, s51, 0xc000
	v_lshl_add_u64 v[64:65], s[80:81], 0, v[128:129]
	s_mov_b32 m0, s83
	s_add_i32 s35, s51, 0xe000
	ds_read_b128 v[32:35], v147
	ds_read_b128 v[36:39], v147 offset:1024
	ds_read_b128 v[40:43], v147 offset:2048
	ds_read_b128 v[44:47], v147 offset:3072
	ds_read_b128 v[48:51], v147 offset:4096
	ds_read_b128 v[52:55], v147 offset:5120
	ds_read_b128 v[56:59], v147 offset:6144
	ds_read_b128 v[60:63], v147 offset:7168
	global_load_lds_dwordx4 v[64:65], off
	v_lshl_add_u64 v[64:65], s[80:81], 0, v[132:133]
	s_mov_b32 m0, s35
	s_nop 0
	global_load_lds_dwordx4 v[64:65], off
	s_waitcnt vmcnt(8)
	s_waitcnt lgkmcnt(0)
	s_barrier
	s_setprio 1
	v_mfma_f32_16x16x32_bf16 v[64:67], v[0:3], v[32:35], 0
	v_mfma_f32_16x16x32_bf16 v[68:71], v[8:11], v[32:35], 0
	v_mfma_f32_16x16x32_bf16 v[72:75], v[0:3], v[40:43], 0
	v_mfma_f32_16x16x32_bf16 v[76:79], v[8:11], v[40:43], 0
	v_mfma_f32_16x16x32_bf16 v[80:83], v[0:3], v[48:51], 0
	v_mfma_f32_16x16x32_bf16 v[84:87], v[8:11], v[48:51], 0
	v_mfma_f32_16x16x32_bf16 v[88:91], v[0:3], v[56:59], 0
	v_mfma_f32_16x16x32_bf16 v[92:95], v[8:11], v[56:59], 0
	v_mfma_f32_16x16x32_bf16 v[64:67], v[4:7], v[36:39], v[64:67]
	v_mfma_f32_16x16x32_bf16 v[68:71], v[12:15], v[36:39], v[68:71]
	v_mfma_f32_16x16x32_bf16 v[72:75], v[4:7], v[44:47], v[72:75]
	v_mfma_f32_16x16x32_bf16 v[76:79], v[12:15], v[44:47], v[76:79]
	v_mfma_f32_16x16x32_bf16 v[80:83], v[4:7], v[52:55], v[80:83]
	v_mfma_f32_16x16x32_bf16 v[84:87], v[12:15], v[52:55], v[84:87]
	v_mfma_f32_16x16x32_bf16 v[88:91], v[4:7], v[60:63], v[88:91]
	v_mfma_f32_16x16x32_bf16 v[92:95], v[12:15], v[60:63], v[92:95]
	v_mfma_f32_16x16x32_bf16 v[96:99], v[16:19], v[32:35], 0
	v_mfma_f32_16x16x32_bf16 v[32:35], v[24:27], v[32:35], 0
	v_mfma_f32_16x16x32_bf16 v[96:99], v[20:23], v[36:39], v[96:99]
	v_mfma_f32_16x16x32_bf16 v[32:35], v[28:31], v[36:39], v[32:35]
	v_mfma_f32_16x16x32_bf16 v[36:39], v[16:19], v[40:43], 0
	v_mfma_f32_16x16x32_bf16 v[40:43], v[24:27], v[40:43], 0
	v_mfma_f32_16x16x32_bf16 v[36:39], v[20:23], v[44:47], v[36:39]
	v_mfma_f32_16x16x32_bf16 v[40:43], v[28:31], v[44:47], v[40:43]
	v_mfma_f32_16x16x32_bf16 v[44:47], v[16:19], v[48:51], 0
	v_mfma_f32_16x16x32_bf16 v[48:51], v[24:27], v[48:51], 0
	v_mfma_f32_16x16x32_bf16 v[44:47], v[20:23], v[52:55], v[44:47]
	v_mfma_f32_16x16x32_bf16 v[48:51], v[28:31], v[52:55], v[48:51]
	v_mfma_f32_16x16x32_bf16 v[52:55], v[16:19], v[56:59], 0
	v_mfma_f32_16x16x32_bf16 v[56:59], v[24:27], v[56:59], 0
	v_mfma_f32_16x16x32_bf16 v[52:55], v[20:23], v[60:63], v[52:55]
	v_mfma_f32_16x16x32_bf16 v[56:59], v[28:31], v[60:63], v[56:59]
	s_setprio 0
	s_barrier
	s_add_i32 s81, s72, s62
	v_lshl_add_u64 v[140:141], s[54:55], 0, v[130:131]
	s_add_i32 s37, s81, 0x2000
	v_lshl_add_u64 v[148:149], v[140:141], 0, s[18:19]
	s_mov_b32 m0, s81
	v_lshl_add_u64 v[212:213], s[54:55], 0, v[134:135]
	s_add_u32 s84, s54, 0x10100
	ds_read_b128 v[60:63], v147 offset:16384
	ds_read_b128 v[100:103], v147 offset:17408
	ds_read_b128 v[104:107], v147 offset:18432
	ds_read_b128 v[108:111], v147 offset:19456
	ds_read_b128 v[112:115], v147 offset:20480
	ds_read_b128 v[116:119], v147 offset:21504
	ds_read_b128 v[120:123], v147 offset:22528
	ds_read_b128 v[124:127], v147 offset:23552
	global_load_lds_dwordx4 v[148:149], off
	v_lshl_add_u64 v[148:149], v[212:213], 0, s[18:19]
	s_mov_b32 m0, s37
	s_addc_u32 s85, s55, 0
	s_add_i32 s79, s73, s62
	global_load_lds_dwordx4 v[148:149], off
	v_lshl_add_u64 v[148:149], s[84:85], 0, v[130:131]
	s_mov_b32 m0, s79
	s_add_i32 s80, s79, 0x2000
	global_load_lds_dwordx4 v[148:149], off
	v_lshl_add_u64 v[148:149], s[84:85], 0, v[134:135]
	s_mov_b32 m0, s80
	v_lshl_add_u64 v[214:215], s[52:53], 0, v[128:129]
	global_load_lds_dwordx4 v[148:149], off
	v_lshl_add_u64 v[148:149], v[214:215], 0, s[18:19]
	s_mov_b32 m0, s51
	v_lshl_add_u64 v[216:217], s[52:53], 0, v[132:133]
	global_load_lds_dwordx4 v[148:149], off
	v_lshl_add_u64 v[148:149], v[216:217], 0, s[18:19]
	s_mov_b32 m0, s63
	s_nop 0
	global_load_lds_dwordx4 v[148:149], off
	s_waitcnt vmcnt(8)
	s_waitcnt lgkmcnt(0)
	s_barrier
	s_setprio 1
	v_mfma_f32_16x16x32_bf16 v[148:151], v[0:3], v[60:63], 0
	v_mfma_f32_16x16x32_bf16 v[156:159], v[0:3], v[104:107], 0
	v_mfma_f32_16x16x32_bf16 v[164:167], v[0:3], v[112:115], 0
	v_mfma_f32_16x16x32_bf16 v[0:3], v[0:3], v[120:123], 0
	v_mfma_f32_16x16x32_bf16 v[148:151], v[4:7], v[100:103], v[148:151]
	v_mfma_f32_16x16x32_bf16 v[156:159], v[4:7], v[108:111], v[156:159]
	v_mfma_f32_16x16x32_bf16 v[164:167], v[4:7], v[116:119], v[164:167]
	v_mfma_f32_16x16x32_bf16 v[0:3], v[4:7], v[124:127], v[0:3]
	v_mfma_f32_16x16x32_bf16 v[4:7], v[8:11], v[120:123], 0
	v_mfma_f32_16x16x32_bf16 v[152:155], v[8:11], v[60:63], 0
	v_mfma_f32_16x16x32_bf16 v[160:163], v[8:11], v[104:107], 0
	v_mfma_f32_16x16x32_bf16 v[168:171], v[8:11], v[112:115], 0
	v_mfma_f32_16x16x32_bf16 v[4:7], v[12:15], v[124:127], v[4:7]
	v_mfma_f32_16x16x32_bf16 v[152:155], v[12:15], v[100:103], v[152:155]
	v_mfma_f32_16x16x32_bf16 v[160:163], v[12:15], v[108:111], v[160:163]
	v_mfma_f32_16x16x32_bf16 v[168:171], v[12:15], v[116:119], v[168:171]
	v_mfma_f32_16x16x32_bf16 v[8:11], v[16:19], v[60:63], 0
	v_mfma_f32_16x16x32_bf16 v[12:15], v[24:27], v[60:63], 0
	v_mfma_f32_16x16x32_bf16 v[8:11], v[20:23], v[100:103], v[8:11]
	v_mfma_f32_16x16x32_bf16 v[12:15], v[28:31], v[100:103], v[12:15]
	v_mfma_f32_16x16x32_bf16 v[60:63], v[16:19], v[104:107], 0
	v_mfma_f32_16x16x32_bf16 v[100:103], v[24:27], v[104:107], 0
	v_mfma_f32_16x16x32_bf16 v[104:107], v[16:19], v[112:115], 0
	v_mfma_f32_16x16x32_bf16 v[16:19], v[16:19], v[120:123], 0
	v_mfma_f32_16x16x32_bf16 v[60:63], v[20:23], v[108:111], v[60:63]
	v_mfma_f32_16x16x32_bf16 v[100:103], v[28:31], v[108:111], v[100:103]
	v_mfma_f32_16x16x32_bf16 v[104:107], v[20:23], v[116:119], v[104:107]
	v_mfma_f32_16x16x32_bf16 v[108:111], v[24:27], v[112:115], 0
	v_mfma_f32_16x16x32_bf16 v[16:19], v[20:23], v[124:127], v[16:19]
	v_mfma_f32_16x16x32_bf16 v[20:23], v[24:27], v[120:123], 0
	v_mfma_f32_16x16x32_bf16 v[108:111], v[28:31], v[116:119], v[108:111]
	v_mfma_f32_16x16x32_bf16 v[20:23], v[28:31], v[124:127], v[20:23]
	s_setprio 0
	s_barrier
	s_add_i32 s82, 0, 0x18000
	s_add_i32 s88, 0, 0x1c000
	v_add_u32_e32 v228, s82, v143
	v_add_u32_e32 v236, s88, v143
	ds_read_b128 v[24:27], v228
	ds_read_b128 v[28:31], v228 offset:1024
	ds_read_b128 v[112:115], v228 offset:2048
	ds_read_b128 v[116:119], v228 offset:3072
	ds_read_b128 v[120:123], v236
	ds_read_b128 v[124:127], v236 offset:1024
	ds_read_b128 v[172:175], v236 offset:2048
	ds_read_b128 v[176:179], v236 offset:3072
	s_add_u32 s84, s52, 0x10100
	s_addc_u32 s85, s53, 0
	s_mov_b32 m0, s64
	v_lshl_add_u64 v[218:219], s[84:85], 0, v[128:129]
	ds_read_b128 v[180:183], v147 offset:32768
	ds_read_b128 v[184:187], v147 offset:33792
	ds_read_b128 v[188:191], v147 offset:34816
	ds_read_b128 v[192:195], v147 offset:35840
	ds_read_b128 v[196:199], v147 offset:36864
	ds_read_b128 v[200:203], v147 offset:37888
	ds_read_b128 v[204:207], v147 offset:38912
	ds_read_b128 v[208:211], v147 offset:39936
	global_load_lds_dwordx4 v[218:219], off
	v_lshl_add_u64 v[218:219], s[84:85], 0, v[132:133]
	s_mov_b32 m0, s65
	s_nop 0
	global_load_lds_dwordx4 v[218:219], off
	s_waitcnt vmcnt(8)
	s_waitcnt lgkmcnt(0)
	s_barrier
	s_setprio 1
	v_mfma_f32_16x16x32_bf16 v[64:67], v[24:27], v[180:183], v[64:67]
	v_mfma_f32_16x16x32_bf16 v[72:75], v[24:27], v[188:191], v[72:75]
	v_mfma_f32_16x16x32_bf16 v[80:83], v[24:27], v[196:199], v[80:83]
	v_mfma_f32_16x16x32_bf16 v[88:91], v[24:27], v[204:207], v[88:91]
	v_mfma_f32_16x16x32_bf16 v[92:95], v[112:115], v[204:207], v[92:95]
	v_mfma_f32_16x16x32_bf16 v[84:87], v[112:115], v[196:199], v[84:87]
	v_mfma_f32_16x16x32_bf16 v[76:79], v[112:115], v[188:191], v[76:79]
	v_mfma_f32_16x16x32_bf16 v[68:71], v[112:115], v[180:183], v[68:71]
	v_mfma_f32_16x16x32_bf16 v[64:67], v[28:31], v[184:187], v[64:67]
	v_mfma_f32_16x16x32_bf16 v[72:75], v[28:31], v[192:195], v[72:75]
	v_mfma_f32_16x16x32_bf16 v[80:83], v[28:31], v[200:203], v[80:83]
	v_mfma_f32_16x16x32_bf16 v[88:91], v[28:31], v[208:211], v[88:91]
	v_mfma_f32_16x16x32_bf16 v[92:95], v[116:119], v[208:211], v[92:95]
	v_mfma_f32_16x16x32_bf16 v[84:87], v[116:119], v[200:203], v[84:87]
	v_mfma_f32_16x16x32_bf16 v[76:79], v[116:119], v[192:195], v[76:79]
	v_mfma_f32_16x16x32_bf16 v[68:71], v[116:119], v[184:187], v[68:71]
	v_mfma_f32_16x16x32_bf16 v[96:99], v[120:123], v[180:183], v[96:99]
	v_mfma_f32_16x16x32_bf16 v[36:39], v[120:123], v[188:191], v[36:39]
	v_mfma_f32_16x16x32_bf16 v[44:47], v[120:123], v[196:199], v[44:47]
	v_mfma_f32_16x16x32_bf16 v[52:55], v[120:123], v[204:207], v[52:55]
	v_mfma_f32_16x16x32_bf16 v[56:59], v[172:175], v[204:207], v[56:59]
	v_mfma_f32_16x16x32_bf16 v[48:51], v[172:175], v[196:199], v[48:51]
	v_mfma_f32_16x16x32_bf16 v[40:43], v[172:175], v[188:191], v[40:43]
	v_mfma_f32_16x16x32_bf16 v[32:35], v[172:175], v[180:183], v[32:35]
	v_mfma_f32_16x16x32_bf16 v[96:99], v[124:127], v[184:187], v[96:99]
	v_mfma_f32_16x16x32_bf16 v[36:39], v[124:127], v[192:195], v[36:39]
	v_mfma_f32_16x16x32_bf16 v[44:47], v[124:127], v[200:203], v[44:47]
	v_mfma_f32_16x16x32_bf16 v[52:55], v[124:127], v[208:211], v[52:55]
	v_mfma_f32_16x16x32_bf16 v[56:59], v[176:179], v[208:211], v[56:59]
	v_mfma_f32_16x16x32_bf16 v[48:51], v[176:179], v[200:203], v[48:51]
	v_mfma_f32_16x16x32_bf16 v[40:43], v[176:179], v[192:195], v[40:43]
	v_mfma_f32_16x16x32_bf16 v[32:35], v[176:179], v[184:187], v[32:35]
	s_setprio 0
	s_barrier
	s_add_i32 s84, s82, s62
	s_add_i32 s82, s84, 0x2000
	v_lshl_add_u64 v[140:141], v[140:141], 0, s[20:21]
	s_mov_b32 m0, s84
	s_add_u32 s86, s54, 0x10180
	ds_read_b128 v[180:183], v147 offset:49152
	ds_read_b128 v[184:187], v147 offset:50176
	ds_read_b128 v[188:191], v147 offset:51200
	ds_read_b128 v[192:195], v147 offset:52224
	ds_read_b128 v[196:199], v147 offset:53248
	ds_read_b128 v[200:203], v147 offset:54272
	ds_read_b128 v[204:207], v147 offset:55296
	ds_read_b128 v[208:211], v147 offset:56320
	global_load_lds_dwordx4 v[140:141], off
	v_lshl_add_u64 v[140:141], v[212:213], 0, s[20:21]
	s_mov_b32 m0, s82
	s_addc_u32 s87, s55, 0
	s_add_i32 s54, s88, s62
	global_load_lds_dwordx4 v[140:141], off
	v_lshl_add_u64 v[140:141], s[86:87], 0, v[130:131]
	s_mov_b32 m0, s54
	s_add_i32 s55, s54, 0x2000
	global_load_lds_dwordx4 v[140:141], off
	v_lshl_add_u64 v[140:141], s[86:87], 0, v[134:135]
	s_mov_b32 m0, s55
	s_nop 0
	global_load_lds_dwordx4 v[140:141], off
	v_lshl_add_u64 v[140:141], v[214:215], 0, s[20:21]
	s_mov_b32 m0, s66
	s_nop 0
	global_load_lds_dwordx4 v[140:141], off
	v_lshl_add_u64 v[140:141], v[216:217], 0, s[20:21]
	s_mov_b32 m0, s67
	s_nop 0
	global_load_lds_dwordx4 v[140:141], off
	s_waitcnt vmcnt(8)
	s_waitcnt lgkmcnt(0)
	s_barrier
	s_setprio 1
	v_mfma_f32_16x16x32_bf16 v[0:3], v[24:27], v[204:207], v[0:3]
	v_mfma_f32_16x16x32_bf16 v[148:151], v[24:27], v[180:183], v[148:151]
	v_mfma_f32_16x16x32_bf16 v[156:159], v[24:27], v[188:191], v[156:159]
	v_mfma_f32_16x16x32_bf16 v[164:167], v[24:27], v[196:199], v[164:167]
	v_mfma_f32_16x16x32_bf16 v[168:171], v[112:115], v[196:199], v[168:171]
	v_mfma_f32_16x16x32_bf16 v[160:163], v[112:115], v[188:191], v[160:163]
	v_mfma_f32_16x16x32_bf16 v[152:155], v[112:115], v[180:183], v[152:155]
	v_mfma_f32_16x16x32_bf16 v[4:7], v[112:115], v[204:207], v[4:7]
	v_mfma_f32_16x16x32_bf16 v[0:3], v[28:31], v[208:211], v[0:3]
	v_mfma_f32_16x16x32_bf16 v[148:151], v[28:31], v[184:187], v[148:151]
	v_mfma_f32_16x16x32_bf16 v[156:159], v[28:31], v[192:195], v[156:159]
	v_mfma_f32_16x16x32_bf16 v[164:167], v[28:31], v[200:203], v[164:167]
	v_mfma_f32_16x16x32_bf16 v[168:171], v[116:119], v[200:203], v[168:171]
	v_mfma_f32_16x16x32_bf16 v[160:163], v[116:119], v[192:195], v[160:163]
	v_mfma_f32_16x16x32_bf16 v[152:155], v[116:119], v[184:187], v[152:155]
	v_mfma_f32_16x16x32_bf16 v[4:7], v[116:119], v[208:211], v[4:7]
	v_mfma_f32_16x16x32_bf16 v[8:11], v[120:123], v[180:183], v[8:11]
	v_mfma_f32_16x16x32_bf16 v[12:15], v[172:175], v[180:183], v[12:15]
	v_mfma_f32_16x16x32_bf16 v[24:27], v[120:123], v[188:191], v[60:63]
	v_mfma_f32_16x16x32_bf16 v[28:31], v[172:175], v[188:191], v[100:103]
	v_mfma_f32_16x16x32_bf16 v[60:63], v[120:123], v[196:199], v[104:107]
	v_mfma_f32_16x16x32_bf16 v[100:103], v[172:175], v[196:199], v[108:111]
	v_mfma_f32_16x16x32_bf16 v[16:19], v[120:123], v[204:207], v[16:19]
	v_mfma_f32_16x16x32_bf16 v[20:23], v[172:175], v[204:207], v[20:23]
	v_mfma_f32_16x16x32_bf16 v[8:11], v[124:127], v[184:187], v[8:11]
	v_mfma_f32_16x16x32_bf16 v[12:15], v[176:179], v[184:187], v[12:15]
	v_mfma_f32_16x16x32_bf16 v[24:27], v[124:127], v[192:195], v[24:27]
	v_mfma_f32_16x16x32_bf16 v[28:31], v[176:179], v[192:195], v[28:31]
	v_mfma_f32_16x16x32_bf16 v[60:63], v[124:127], v[200:203], v[60:63]
	v_mfma_f32_16x16x32_bf16 v[100:103], v[176:179], v[200:203], v[100:103]
	v_mfma_f32_16x16x32_bf16 v[16:19], v[124:127], v[208:211], v[16:19]
	v_mfma_f32_16x16x32_bf16 v[20:23], v[176:179], v[208:211], v[20:23]
	s_setprio 0
	s_barrier
	ds_read_b128 v[104:107], v145
	ds_read_b128 v[108:111], v145 offset:1024
	ds_read_b128 v[112:115], v145 offset:2048
	ds_read_b128 v[116:119], v145 offset:3072
	ds_read_b128 v[120:123], v146
	ds_read_b128 v[124:127], v146 offset:1024
	ds_read_b128 v[172:175], v146 offset:2048
	ds_read_b128 v[176:179], v146 offset:3072
	s_add_u32 s52, s52, 0x10180
	s_addc_u32 s53, s53, 0
	s_mov_b32 m0, s83
	v_lshl_add_u64 v[140:141], s[52:53], 0, v[128:129]
	ds_read_b128 v[180:183], v147
	ds_read_b128 v[184:187], v147 offset:1024
	ds_read_b128 v[188:191], v147 offset:2048
	ds_read_b128 v[192:195], v147 offset:3072
	ds_read_b128 v[196:199], v147 offset:4096
	ds_read_b128 v[200:203], v147 offset:5120
	ds_read_b128 v[204:207], v147 offset:6144
	ds_read_b128 v[208:211], v147 offset:7168
	global_load_lds_dwordx4 v[140:141], off
	v_lshl_add_u64 v[140:141], s[52:53], 0, v[132:133]
	s_mov_b32 m0, s35
	s_nop 0
	global_load_lds_dwordx4 v[140:141], off
	s_waitcnt vmcnt(8)
	s_waitcnt lgkmcnt(0)
	s_barrier
	s_setprio 1
	v_mfma_f32_16x16x32_bf16 v[88:91], v[104:107], v[204:207], v[88:91]
	v_mfma_f32_16x16x32_bf16 v[64:67], v[104:107], v[180:183], v[64:67]
	v_mfma_f32_16x16x32_bf16 v[68:71], v[112:115], v[180:183], v[68:71]
	v_mfma_f32_16x16x32_bf16 v[72:75], v[104:107], v[188:191], v[72:75]
	v_mfma_f32_16x16x32_bf16 v[76:79], v[112:115], v[188:191], v[76:79]
	v_mfma_f32_16x16x32_bf16 v[80:83], v[104:107], v[196:199], v[80:83]
	v_mfma_f32_16x16x32_bf16 v[84:87], v[112:115], v[196:199], v[84:87]
	v_mfma_f32_16x16x32_bf16 v[212:215], v[108:111], v[208:211], v[88:91]
	v_mfma_f32_16x16x32_bf16 v[88:91], v[112:115], v[204:207], v[92:95]
	v_mfma_f32_16x16x32_bf16 v[64:67], v[108:111], v[184:187], v[64:67]
	v_mfma_f32_16x16x32_bf16 v[68:71], v[116:119], v[184:187], v[68:71]
	v_mfma_f32_16x16x32_bf16 v[72:75], v[108:111], v[192:195], v[72:75]
	v_mfma_f32_16x16x32_bf16 v[76:79], v[116:119], v[192:195], v[76:79]
	v_mfma_f32_16x16x32_bf16 v[80:83], v[108:111], v[200:203], v[80:83]
	v_mfma_f32_16x16x32_bf16 v[84:87], v[116:119], v[200:203], v[84:87]
	v_mfma_f32_16x16x32_bf16 v[92:95], v[116:119], v[208:211], v[88:91]
	v_mfma_f32_16x16x32_bf16 v[48:51], v[172:175], v[196:199], v[48:51]
	v_mfma_f32_16x16x32_bf16 v[88:91], v[120:123], v[180:183], v[96:99]
	v_mfma_f32_16x16x32_bf16 v[32:35], v[172:175], v[180:183], v[32:35]
	v_mfma_f32_16x16x32_bf16 v[36:39], v[120:123], v[188:191], v[36:39]
	v_mfma_f32_16x16x32_bf16 v[40:43], v[172:175], v[188:191], v[40:43]
	v_mfma_f32_16x16x32_bf16 v[44:47], v[120:123], v[196:199], v[44:47]
	v_mfma_f32_16x16x32_bf16 v[180:183], v[176:179], v[200:203], v[48:51]
	v_mfma_f32_16x16x32_bf16 v[48:51], v[120:123], v[204:207], v[52:55]
	v_mfma_f32_16x16x32_bf16 v[32:35], v[176:179], v[184:187], v[32:35]
	v_mfma_f32_16x16x32_bf16 v[36:39], v[124:127], v[192:195], v[36:39]
	v_mfma_f32_16x16x32_bf16 v[40:43], v[176:179], v[192:195], v[40:43]
	v_mfma_f32_16x16x32_bf16 v[44:47], v[124:127], v[200:203], v[44:47]
	v_mfma_f32_16x16x32_bf16 v[52:55], v[124:127], v[208:211], v[48:51]
	v_mfma_f32_16x16x32_bf16 v[48:51], v[172:175], v[204:207], v[56:59]
	v_mfma_f32_16x16x32_bf16 v[220:223], v[124:127], v[184:187], v[88:91]
	v_mfma_f32_16x16x32_bf16 v[184:187], v[176:179], v[208:211], v[48:51]
	s_setprio 0
	s_barrier
	s_mov_b32 m0, s81
	v_lshl_add_u64 v[140:141], s[56:57], 0, v[130:131]
	s_add_u32 s52, s56, 0x10000
	s_nop 0
	ds_read_b128 v[48:51], v147 offset:16384
	ds_read_b128 v[56:59], v147 offset:17408
	ds_read_b128 v[88:91], v147 offset:18432
	ds_read_b128 v[96:99], v147 offset:19456
	ds_read_b128 v[188:191], v147 offset:20480
	ds_read_b128 v[192:195], v147 offset:21504
	ds_read_b128 v[196:199], v147 offset:22528
	ds_read_b128 v[200:203], v147 offset:23552
	global_load_lds_dwordx4 v[140:141], off
	v_lshl_add_u64 v[252:253], s[56:57], 0, v[134:135]
	s_mov_b32 m0, s37
	s_addc_u32 s53, s57, 0
	global_load_lds_dwordx4 v[252:253], off
	v_lshl_add_u64 v[204:205], s[52:53], 0, v[130:131]
	s_mov_b32 m0, s79
	v_lshl_add_u64 v[136:137], s[58:59], 0, v[128:129]
	global_load_lds_dwordx4 v[204:205], off
	v_lshl_add_u64 v[204:205], s[52:53], 0, v[134:135]
	s_mov_b32 m0, s80
	v_lshl_add_u64 v[138:139], s[58:59], 0, v[132:133]
	global_load_lds_dwordx4 v[204:205], off
	s_mov_b32 m0, s51
	s_nop 0
	global_load_lds_dwordx4 v[136:137], off
	s_mov_b32 m0, s63
	s_nop 0
	global_load_lds_dwordx4 v[138:139], off
	s_waitcnt vmcnt(8)
	s_waitcnt lgkmcnt(0)
	s_barrier
	s_setprio 1
	v_mfma_f32_16x16x32_bf16 v[0:3], v[104:107], v[196:199], v[0:3]
	v_mfma_f32_16x16x32_bf16 v[148:151], v[104:107], v[48:51], v[148:151]
	v_mfma_f32_16x16x32_bf16 v[156:159], v[104:107], v[88:91], v[156:159]
	v_mfma_f32_16x16x32_bf16 v[164:167], v[104:107], v[188:191], v[164:167]
	v_mfma_f32_16x16x32_bf16 v[168:171], v[112:115], v[188:191], v[168:171]
	v_mfma_f32_16x16x32_bf16 v[160:163], v[112:115], v[88:91], v[160:163]
	v_mfma_f32_16x16x32_bf16 v[152:155], v[112:115], v[48:51], v[152:155]
	v_mfma_f32_16x16x32_bf16 v[4:7], v[112:115], v[196:199], v[4:7]
	v_mfma_f32_16x16x32_bf16 v[0:3], v[108:111], v[200:203], v[0:3]
	v_mfma_f32_16x16x32_bf16 v[148:151], v[108:111], v[56:59], v[148:151]
	v_mfma_f32_16x16x32_bf16 v[156:159], v[108:111], v[96:99], v[156:159]
	v_mfma_f32_16x16x32_bf16 v[164:167], v[108:111], v[192:195], v[164:167]
	v_mfma_f32_16x16x32_bf16 v[168:171], v[116:119], v[192:195], v[168:171]
	v_mfma_f32_16x16x32_bf16 v[160:163], v[116:119], v[96:99], v[160:163]
	v_mfma_f32_16x16x32_bf16 v[152:155], v[116:119], v[56:59], v[152:155]
	v_mfma_f32_16x16x32_bf16 v[4:7], v[116:119], v[200:203], v[4:7]
	v_mfma_f32_16x16x32_bf16 v[12:15], v[172:175], v[48:51], v[12:15]
	v_mfma_f32_16x16x32_bf16 v[204:207], v[176:179], v[56:59], v[12:15]
	v_mfma_f32_16x16x32_bf16 v[12:15], v[120:123], v[88:91], v[24:27]
	v_mfma_f32_16x16x32_bf16 v[24:27], v[124:127], v[96:99], v[12:15]
	v_mfma_f32_16x16x32_bf16 v[12:15], v[172:175], v[88:91], v[28:31]
	v_mfma_f32_16x16x32_bf16 v[208:211], v[176:179], v[96:99], v[12:15]
	v_mfma_f32_16x16x32_bf16 v[12:15], v[120:123], v[188:191], v[60:63]
	v_mfma_f32_16x16x32_bf16 v[224:227], v[124:127], v[192:195], v[12:15]
	v_mfma_f32_16x16x32_bf16 v[12:15], v[172:175], v[188:191], v[100:103]
	v_mfma_f32_16x16x32_bf16 v[8:11], v[120:123], v[48:51], v[8:11]
	v_mfma_f32_16x16x32_bf16 v[188:191], v[176:179], v[192:195], v[12:15]
	v_mfma_f32_16x16x32_bf16 v[12:15], v[120:123], v[196:199], v[16:19]
	v_mfma_f32_16x16x32_bf16 v[8:11], v[124:127], v[56:59], v[8:11]
	v_mfma_f32_16x16x32_bf16 v[192:195], v[124:127], v[200:203], v[12:15]
	v_mfma_f32_16x16x32_bf16 v[12:15], v[172:175], v[196:199], v[20:23]
	v_mfma_f32_16x16x32_bf16 v[172:175], v[176:179], v[200:203], v[12:15]
	s_setprio 0
	s_barrier
	s_nop 4
	ds_read_b128 v[12:15], v228
	ds_read_b128 v[16:19], v228 offset:1024
	ds_read_b128 v[176:179], v228 offset:2048
	ds_read_b128 v[196:199], v228 offset:3072
	ds_read_b128 v[200:203], v236
	ds_read_b128 v[228:231], v236 offset:1024
	ds_read_b128 v[232:235], v236 offset:2048
	ds_read_b128 v[236:239], v236 offset:3072
	s_add_u32 s52, s58, 0x10000
	s_addc_u32 s53, s59, 0
	s_mov_b32 m0, s64
	v_lshl_add_u64 v[48:49], s[52:53], 0, v[128:129]
	ds_read_b128 v[20:23], v147 offset:32768
	ds_read_b128 v[28:31], v147 offset:33792
	ds_read_b128 v[60:63], v147 offset:34816
	ds_read_b128 v[100:103], v147 offset:35840
	ds_read_b128 v[240:243], v147 offset:36864
	ds_read_b128 v[244:247], v147 offset:37888
	ds_read_b128 v[248:251], v147 offset:38912
	ds_read_b128 v[216:219], v147 offset:39936
	global_load_lds_dwordx4 v[48:49], off
	v_lshl_add_u64 v[48:49], s[52:53], 0, v[132:133]
	s_mov_b32 m0, s65
	s_nop 0
	global_load_lds_dwordx4 v[48:49], off
	s_waitcnt vmcnt(8)
	s_waitcnt lgkmcnt(0)
	s_barrier
	s_setprio 1
	v_mfma_f32_16x16x32_bf16 v[48:51], v[12:15], v[20:23], v[64:67]
	v_mfma_f32_16x16x32_bf16 v[120:123], v[16:19], v[28:31], v[48:51]
	v_mfma_f32_16x16x32_bf16 v[48:51], v[176:179], v[20:23], v[68:71]
	v_mfma_f32_16x16x32_bf16 v[112:115], v[196:199], v[28:31], v[48:51]
	v_mfma_f32_16x16x32_bf16 v[48:51], v[12:15], v[60:63], v[72:75]
	v_mfma_f32_16x16x32_bf16 v[104:107], v[16:19], v[100:103], v[48:51]
	v_mfma_f32_16x16x32_bf16 v[48:51], v[176:179], v[60:63], v[76:79]
	v_mfma_f32_16x16x32_bf16 v[96:99], v[196:199], v[100:103], v[48:51]
	v_mfma_f32_16x16x32_bf16 v[48:51], v[12:15], v[240:243], v[80:83]
	v_mfma_f32_16x16x32_bf16 v[88:91], v[16:19], v[244:247], v[48:51]
	v_mfma_f32_16x16x32_bf16 v[48:51], v[176:179], v[240:243], v[84:87]
	v_mfma_f32_16x16x32_bf16 v[80:83], v[196:199], v[244:247], v[48:51]
	v_mfma_f32_16x16x32_bf16 v[48:51], v[12:15], v[248:251], v[212:215]
	v_mfma_f32_16x16x32_bf16 v[56:59], v[16:19], v[216:219], v[48:51]
	v_mfma_f32_16x16x32_bf16 v[48:51], v[176:179], v[248:251], v[92:95]
	v_mfma_f32_16x16x32_bf16 v[48:51], v[196:199], v[216:219], v[48:51]
	v_mfma_f32_16x16x32_bf16 v[64:67], v[200:203], v[20:23], v[220:223]
	v_mfma_f32_16x16x32_bf16 v[20:23], v[232:235], v[20:23], v[32:35]
	v_mfma_f32_16x16x32_bf16 v[116:119], v[236:239], v[28:31], v[20:23]
	v_mfma_f32_16x16x32_bf16 v[20:23], v[200:203], v[60:63], v[36:39]
	v_mfma_f32_16x16x32_bf16 v[108:111], v[228:231], v[100:103], v[20:23]
	v_mfma_f32_16x16x32_bf16 v[20:23], v[232:235], v[60:63], v[40:43]
	v_mfma_f32_16x16x32_bf16 v[100:103], v[236:239], v[100:103], v[20:23]
	v_mfma_f32_16x16x32_bf16 v[20:23], v[200:203], v[240:243], v[44:47]
	v_mfma_f32_16x16x32_bf16 v[92:95], v[228:231], v[244:247], v[20:23]
	v_mfma_f32_16x16x32_bf16 v[20:23], v[232:235], v[240:243], v[180:183]
	v_mfma_f32_16x16x32_bf16 v[84:87], v[236:239], v[244:247], v[20:23]
	v_mfma_f32_16x16x32_bf16 v[20:23], v[200:203], v[248:251], v[52:55]
	v_mfma_f32_16x16x32_bf16 v[60:63], v[228:231], v[216:219], v[20:23]
	v_mfma_f32_16x16x32_bf16 v[20:23], v[232:235], v[248:251], v[184:187]
	v_mfma_f32_16x16x32_bf16 v[124:127], v[228:231], v[28:31], v[64:67]
	v_mfma_f32_16x16x32_bf16 v[52:55], v[236:239], v[216:219], v[20:23]
	s_setprio 0
	s_barrier
	s_mov_b32 m0, s84
	s_nop 2
	v_lshl_add_u64 v[20:21], v[140:141], 0, s[12:13]
	s_add_u32 s52, s56, 0x10080
	ds_read_b128 v[32:35], v147 offset:49152
	ds_read_b128 v[40:43], v147 offset:50176
	ds_read_b128 v[180:183], v147 offset:51200
	ds_read_b128 v[184:187], v147 offset:52224
	ds_read_b128 v[212:215], v147 offset:53248
	ds_read_b128 v[216:219], v147 offset:54272
	ds_read_b128 v[220:223], v147 offset:55296
	ds_read_b128 v[240:243], v147 offset:56320
	global_load_lds_dwordx4 v[20:21], off
	v_lshl_add_u64 v[20:21], v[252:253], 0, s[12:13]
	s_mov_b32 m0, s82
	s_addc_u32 s53, s57, 0
	global_load_lds_dwordx4 v[20:21], off
	v_lshl_add_u64 v[20:21], s[52:53], 0, v[130:131]
	s_mov_b32 m0, s54
	s_nop 0
	global_load_lds_dwordx4 v[20:21], off
	v_lshl_add_u64 v[20:21], s[52:53], 0, v[134:135]
	s_mov_b32 m0, s55
	s_nop 0
	global_load_lds_dwordx4 v[20:21], off
	v_lshl_add_u64 v[20:21], v[136:137], 0, s[12:13]
	s_mov_b32 m0, s66
	s_nop 0
	global_load_lds_dwordx4 v[20:21], off
	v_lshl_add_u64 v[20:21], v[138:139], 0, s[12:13]
	s_mov_b32 m0, s67
	s_nop 0
	global_load_lds_dwordx4 v[20:21], off
	s_waitcnt vmcnt(8)
	s_waitcnt lgkmcnt(0)
	s_barrier
	s_setprio 1
	v_mfma_f32_16x16x32_bf16 v[20:23], v[12:15], v[32:35], v[148:151]
	v_mfma_f32_16x16x32_bf16 v[76:79], v[16:19], v[40:43], v[20:23]
	v_mfma_f32_16x16x32_bf16 v[20:23], v[176:179], v[32:35], v[152:155]
	v_mfma_f32_16x16x32_bf16 v[68:71], v[196:199], v[40:43], v[20:23]
	v_mfma_f32_16x16x32_bf16 v[20:23], v[12:15], v[180:183], v[156:159]
	v_mfma_f32_16x16x32_bf16 v[44:47], v[16:19], v[184:187], v[20:23]
	v_mfma_f32_16x16x32_bf16 v[20:23], v[176:179], v[180:183], v[160:163]
	v_mfma_f32_16x16x32_bf16 v[36:39], v[196:199], v[184:187], v[20:23]
	v_mfma_f32_16x16x32_bf16 v[20:23], v[12:15], v[212:215], v[164:167]
	v_mfma_f32_16x16x32_bf16 v[0:3], v[12:15], v[220:223], v[0:3]
	v_mfma_f32_16x16x32_bf16 v[28:31], v[16:19], v[216:219], v[20:23]
	v_mfma_f32_16x16x32_bf16 v[20:23], v[176:179], v[212:215], v[168:171]
	v_mfma_f32_16x16x32_bf16 v[12:15], v[16:19], v[240:243], v[0:3]
	v_mfma_f32_16x16x32_bf16 v[0:3], v[176:179], v[220:223], v[4:7]
	v_mfma_f32_16x16x32_bf16 v[20:23], v[196:199], v[216:219], v[20:23]
	v_mfma_f32_16x16x32_bf16 v[4:7], v[196:199], v[240:243], v[0:3]
	v_mfma_f32_16x16x32_bf16 v[0:3], v[200:203], v[32:35], v[8:11]
	v_mfma_f32_16x16x32_bf16 v[72:75], v[228:231], v[40:43], v[0:3]
	v_mfma_f32_16x16x32_bf16 v[0:3], v[232:235], v[32:35], v[204:207]
	v_mfma_f32_16x16x32_bf16 v[64:67], v[236:239], v[40:43], v[0:3]
	v_mfma_f32_16x16x32_bf16 v[0:3], v[200:203], v[180:183], v[24:27]
	v_mfma_f32_16x16x32_bf16 v[40:43], v[228:231], v[184:187], v[0:3]
	v_mfma_f32_16x16x32_bf16 v[0:3], v[232:235], v[180:183], v[208:211]
	v_mfma_f32_16x16x32_bf16 v[32:35], v[236:239], v[184:187], v[0:3]
	v_mfma_f32_16x16x32_bf16 v[0:3], v[200:203], v[212:215], v[224:227]
	v_mfma_f32_16x16x32_bf16 v[24:27], v[228:231], v[216:219], v[0:3]
	v_mfma_f32_16x16x32_bf16 v[0:3], v[232:235], v[212:215], v[188:191]
	v_mfma_f32_16x16x32_bf16 v[16:19], v[236:239], v[216:219], v[0:3]
	v_mfma_f32_16x16x32_bf16 v[0:3], v[200:203], v[220:223], v[192:195]
	v_mfma_f32_16x16x32_bf16 v[8:11], v[228:231], v[240:243], v[0:3]
	v_mfma_f32_16x16x32_bf16 v[0:3], v[232:235], v[220:223], v[172:175]
	v_mfma_f32_16x16x32_bf16 v[0:3], v[236:239], v[240:243], v[0:3]
	s_setprio 0
	s_barrier
	s_andn2_b64 vcc, exec, s[14:15]
	s_cbranch_vccnz .LBB0_155
	s_barrier

.LBB0_178:
	ds_read_b128 v[148:151], v157
	ds_read_b128 v[162:165], v157 offset:1024
	ds_read_b128 v[166:169], v157 offset:2048
	ds_read_b128 v[170:173], v157 offset:3072
	ds_read_b128 v[174:177], v158
	ds_read_b128 v[178:181], v158 offset:1024
	ds_read_b128 v[182:185], v158 offset:2048
	ds_read_b128 v[186:189], v158 offset:3072
	s_add_u32 s48, s46, 0xfff80080
	s_addc_u32 s49, s47, -1
	s_cmp_eq_u32 s72, 28
	s_cselect_b32 s51, s31, s49
	s_cselect_b32 s50, s66, s48
	s_cselect_b32 s49, s27, s71
	s_cselect_b32 s48, s67, s70
	v_lshl_add_u64 v[152:153], s[46:47], 0, v[142:143]
	s_add_i32 m0, s13, 0xc000
	ds_read_b128 v[190:193], v159
	ds_read_b128 v[194:197], v159 offset:1024
	ds_read_b128 v[198:201], v159 offset:2048
	ds_read_b128 v[202:205], v159 offset:3072
	ds_read_b128 v[206:209], v159 offset:4096
	ds_read_b128 v[210:213], v159 offset:5120
	ds_read_b128 v[214:217], v159 offset:6144
	ds_read_b128 v[218:221], v159 offset:7168
	global_load_lds_dwordx4 v[152:153], off
	v_lshl_add_u64 v[152:153], s[46:47], 0, v[140:141]
	s_add_i32 m0, s13, 0xe000
	s_nop 0
	global_load_lds_dwordx4 v[152:153], off
	s_waitcnt vmcnt(8)
	s_waitcnt lgkmcnt(0)
	s_barrier
	s_setprio 1
	v_mfma_f32_16x16x32_bf16 v[124:127], v[148:151], v[190:193], v[124:127]
	v_mfma_f32_16x16x32_bf16 v[108:111], v[148:151], v[198:201], v[108:111]
	v_mfma_f32_16x16x32_bf16 v[92:95], v[148:151], v[206:209], v[92:95]
	v_mfma_f32_16x16x32_bf16 v[76:79], v[148:151], v[214:217], v[76:79]
	v_mfma_f32_16x16x32_bf16 v[72:75], v[166:169], v[214:217], v[72:75]
	v_mfma_f32_16x16x32_bf16 v[88:91], v[166:169], v[206:209], v[88:91]
	v_mfma_f32_16x16x32_bf16 v[104:107], v[166:169], v[198:201], v[104:107]
	v_mfma_f32_16x16x32_bf16 v[120:123], v[166:169], v[190:193], v[120:123]
	v_mfma_f32_16x16x32_bf16 v[124:127], v[162:165], v[194:197], v[124:127]
	v_mfma_f32_16x16x32_bf16 v[108:111], v[162:165], v[202:205], v[108:111]
	v_mfma_f32_16x16x32_bf16 v[92:95], v[162:165], v[210:213], v[92:95]
	v_mfma_f32_16x16x32_bf16 v[76:79], v[162:165], v[218:221], v[76:79]
	v_mfma_f32_16x16x32_bf16 v[72:75], v[170:173], v[218:221], v[72:75]
	v_mfma_f32_16x16x32_bf16 v[88:91], v[170:173], v[210:213], v[88:91]
	v_mfma_f32_16x16x32_bf16 v[104:107], v[170:173], v[202:205], v[104:107]
	v_mfma_f32_16x16x32_bf16 v[120:123], v[170:173], v[194:197], v[120:123]
	v_mfma_f32_16x16x32_bf16 v[116:119], v[174:177], v[190:193], v[116:119]
	v_mfma_f32_16x16x32_bf16 v[100:103], v[174:177], v[198:201], v[100:103]
	v_mfma_f32_16x16x32_bf16 v[84:87], v[174:177], v[206:209], v[84:87]
	v_mfma_f32_16x16x32_bf16 v[68:71], v[174:177], v[214:217], v[68:71]
	v_mfma_f32_16x16x32_bf16 v[64:67], v[182:185], v[214:217], v[64:67]
	v_mfma_f32_16x16x32_bf16 v[80:83], v[182:185], v[206:209], v[80:83]
	v_mfma_f32_16x16x32_bf16 v[96:99], v[182:185], v[198:201], v[96:99]
	v_mfma_f32_16x16x32_bf16 v[112:115], v[182:185], v[190:193], v[112:115]
	v_mfma_f32_16x16x32_bf16 v[116:119], v[178:181], v[194:197], v[116:119]
	v_mfma_f32_16x16x32_bf16 v[100:103], v[178:181], v[202:205], v[100:103]
	v_mfma_f32_16x16x32_bf16 v[84:87], v[178:181], v[210:213], v[84:87]
	v_mfma_f32_16x16x32_bf16 v[68:71], v[178:181], v[218:221], v[68:71]
	v_mfma_f32_16x16x32_bf16 v[64:67], v[186:189], v[218:221], v[64:67]
	v_mfma_f32_16x16x32_bf16 v[80:83], v[186:189], v[210:213], v[80:83]
	v_mfma_f32_16x16x32_bf16 v[96:99], v[186:189], v[202:205], v[96:99]
	v_mfma_f32_16x16x32_bf16 v[112:115], v[186:189], v[194:197], v[112:115]
	s_setprio 0
	s_barrier
	s_add_i32 s73, s62, s52
	v_lshl_add_u64 v[152:153], s[48:49], 0, v[130:131]
	s_mov_b32 m0, s73
	ds_read_b128 v[190:193], v159 offset:16384
	ds_read_b128 v[194:197], v159 offset:17408
	ds_read_b128 v[198:201], v159 offset:18432
	ds_read_b128 v[202:205], v159 offset:19456
	ds_read_b128 v[206:209], v159 offset:20480
	ds_read_b128 v[210:213], v159 offset:21504
	ds_read_b128 v[214:217], v159 offset:22528
	ds_read_b128 v[218:221], v159 offset:23552
	global_load_lds_dwordx4 v[152:153], off
	s_add_i32 m0, s73, 0x2000
	s_add_u32 s74, s48, 0x80000
	v_lshl_add_u64 v[222:223], s[48:49], 0, v[134:135]
	s_addc_u32 s75, s49, 0
	s_add_i32 s73, s63, s52
	global_load_lds_dwordx4 v[222:223], off
	v_lshl_add_u64 v[224:225], s[74:75], 0, v[130:131]
	s_mov_b32 m0, s73
	v_lshl_add_u64 v[226:227], s[50:51], 0, v[132:133]
	global_load_lds_dwordx4 v[224:225], off
	v_lshl_add_u64 v[224:225], s[74:75], 0, v[134:135]
	s_add_i32 m0, s73, 0x2000
	s_nop 0
	global_load_lds_dwordx4 v[224:225], off
	v_lshl_add_u64 v[224:225], s[50:51], 0, v[128:129]
	s_mov_b32 m0, s13
	s_nop 0
	global_load_lds_dwordx4 v[224:225], off
	s_mov_b32 m0, s53
	s_nop 0
	global_load_lds_dwordx4 v[226:227], off
	s_waitcnt vmcnt(8)
	s_waitcnt lgkmcnt(0)
	s_barrier
	s_setprio 1
	v_mfma_f32_16x16x32_bf16 v[60:63], v[148:151], v[190:193], v[60:63]
	v_mfma_f32_16x16x32_bf16 v[44:47], v[148:151], v[198:201], v[44:47]
	v_mfma_f32_16x16x32_bf16 v[28:31], v[148:151], v[206:209], v[28:31]
	v_mfma_f32_16x16x32_bf16 v[12:15], v[148:151], v[214:217], v[12:15]
	v_mfma_f32_16x16x32_bf16 v[8:11], v[166:169], v[214:217], v[8:11]
	v_mfma_f32_16x16x32_bf16 v[24:27], v[166:169], v[206:209], v[24:27]
	v_mfma_f32_16x16x32_bf16 v[40:43], v[166:169], v[198:201], v[40:43]
	v_mfma_f32_16x16x32_bf16 v[56:59], v[166:169], v[190:193], v[56:59]
	v_mfma_f32_16x16x32_bf16 v[60:63], v[162:165], v[194:197], v[60:63]
	v_mfma_f32_16x16x32_bf16 v[44:47], v[162:165], v[202:205], v[44:47]
	v_mfma_f32_16x16x32_bf16 v[28:31], v[162:165], v[210:213], v[28:31]
	v_mfma_f32_16x16x32_bf16 v[12:15], v[162:165], v[218:221], v[12:15]
	v_mfma_f32_16x16x32_bf16 v[8:11], v[170:173], v[218:221], v[8:11]
	v_mfma_f32_16x16x32_bf16 v[24:27], v[170:173], v[210:213], v[24:27]
	v_mfma_f32_16x16x32_bf16 v[40:43], v[170:173], v[202:205], v[40:43]
	v_mfma_f32_16x16x32_bf16 v[56:59], v[170:173], v[194:197], v[56:59]
	v_mfma_f32_16x16x32_bf16 v[52:55], v[174:177], v[190:193], v[52:55]
	v_mfma_f32_16x16x32_bf16 v[36:39], v[174:177], v[198:201], v[36:39]
	v_mfma_f32_16x16x32_bf16 v[20:23], v[174:177], v[206:209], v[20:23]
	v_mfma_f32_16x16x32_bf16 v[4:7], v[174:177], v[214:217], v[4:7]
	v_mfma_f32_16x16x32_bf16 v[0:3], v[182:185], v[214:217], v[0:3]
	v_mfma_f32_16x16x32_bf16 v[16:19], v[182:185], v[206:209], v[16:19]
	v_mfma_f32_16x16x32_bf16 v[32:35], v[182:185], v[198:201], v[32:35]
	v_mfma_f32_16x16x32_bf16 v[48:51], v[182:185], v[190:193], v[48:51]
	v_mfma_f32_16x16x32_bf16 v[52:55], v[178:181], v[194:197], v[52:55]
	v_mfma_f32_16x16x32_bf16 v[36:39], v[178:181], v[202:205], v[36:39]
	v_mfma_f32_16x16x32_bf16 v[20:23], v[178:181], v[210:213], v[20:23]
	v_mfma_f32_16x16x32_bf16 v[4:7], v[178:181], v[218:221], v[4:7]
	v_mfma_f32_16x16x32_bf16 v[0:3], v[186:189], v[218:221], v[0:3]
	v_mfma_f32_16x16x32_bf16 v[16:19], v[186:189], v[210:213], v[16:19]
	v_mfma_f32_16x16x32_bf16 v[32:35], v[186:189], v[202:205], v[32:35]
	v_mfma_f32_16x16x32_bf16 v[48:51], v[186:189], v[194:197], v[48:51]
	s_setprio 0
	s_barrier
	s_add_i32 s73, 0, 0x18000
	v_add_u32_e32 v137, s73, v155
	s_add_i32 s74, 0, 0x1c000
	ds_read_b128 v[148:151], v137
	ds_read_b128 v[162:165], v137 offset:1024
	ds_read_b128 v[166:169], v137 offset:2048
	ds_read_b128 v[170:173], v137 offset:3072
	v_add_u32_e32 v137, s74, v155
	ds_read_b128 v[174:177], v137
	ds_read_b128 v[178:181], v137 offset:1024
	ds_read_b128 v[182:185], v137 offset:2048
	ds_read_b128 v[186:189], v137 offset:3072
	s_add_u32 s50, s50, 0x80000
	s_addc_u32 s51, s51, 0
	s_mov_b32 m0, s54
	v_lshl_add_u64 v[228:229], s[50:51], 0, v[128:129]
	ds_read_b128 v[190:193], v159 offset:32768
	ds_read_b128 v[194:197], v159 offset:33792
	ds_read_b128 v[198:201], v159 offset:34816
	ds_read_b128 v[202:205], v159 offset:35840
	ds_read_b128 v[206:209], v159 offset:36864
	ds_read_b128 v[210:213], v159 offset:37888
	ds_read_b128 v[214:217], v159 offset:38912
	ds_read_b128 v[218:221], v159 offset:39936
	global_load_lds_dwordx4 v[228:229], off
	v_lshl_add_u64 v[228:229], s[50:51], 0, v[132:133]
	s_mov_b32 m0, s55
	s_nop 0
	global_load_lds_dwordx4 v[228:229], off
	s_waitcnt vmcnt(8)
	s_waitcnt lgkmcnt(0)
	s_barrier
	s_setprio 1
	v_mfma_f32_16x16x32_bf16 v[124:127], v[148:151], v[190:193], v[124:127]
	v_mfma_f32_16x16x32_bf16 v[108:111], v[148:151], v[198:201], v[108:111]
	v_mfma_f32_16x16x32_bf16 v[92:95], v[148:151], v[206:209], v[92:95]
	v_mfma_f32_16x16x32_bf16 v[76:79], v[148:151], v[214:217], v[76:79]
	v_mfma_f32_16x16x32_bf16 v[72:75], v[166:169], v[214:217], v[72:75]
	v_mfma_f32_16x16x32_bf16 v[88:91], v[166:169], v[206:209], v[88:91]
	v_mfma_f32_16x16x32_bf16 v[104:107], v[166:169], v[198:201], v[104:107]
	v_mfma_f32_16x16x32_bf16 v[120:123], v[166:169], v[190:193], v[120:123]
	v_mfma_f32_16x16x32_bf16 v[124:127], v[162:165], v[194:197], v[124:127]
	v_mfma_f32_16x16x32_bf16 v[108:111], v[162:165], v[202:205], v[108:111]
	v_mfma_f32_16x16x32_bf16 v[92:95], v[162:165], v[210:213], v[92:95]
	v_mfma_f32_16x16x32_bf16 v[76:79], v[162:165], v[218:221], v[76:79]
	v_mfma_f32_16x16x32_bf16 v[72:75], v[170:173], v[218:221], v[72:75]
	v_mfma_f32_16x16x32_bf16 v[88:91], v[170:173], v[210:213], v[88:91]
	v_mfma_f32_16x16x32_bf16 v[104:107], v[170:173], v[202:205], v[104:107]
	v_mfma_f32_16x16x32_bf16 v[120:123], v[170:173], v[194:197], v[120:123]
	v_mfma_f32_16x16x32_bf16 v[116:119], v[174:177], v[190:193], v[116:119]
	v_mfma_f32_16x16x32_bf16 v[100:103], v[174:177], v[198:201], v[100:103]
	v_mfma_f32_16x16x32_bf16 v[84:87], v[174:177], v[206:209], v[84:87]
	v_mfma_f32_16x16x32_bf16 v[68:71], v[174:177], v[214:217], v[68:71]
	v_mfma_f32_16x16x32_bf16 v[64:67], v[182:185], v[214:217], v[64:67]
	v_mfma_f32_16x16x32_bf16 v[80:83], v[182:185], v[206:209], v[80:83]
	v_mfma_f32_16x16x32_bf16 v[96:99], v[182:185], v[198:201], v[96:99]
	v_mfma_f32_16x16x32_bf16 v[112:115], v[182:185], v[190:193], v[112:115]
	v_mfma_f32_16x16x32_bf16 v[116:119], v[178:181], v[194:197], v[116:119]
	v_mfma_f32_16x16x32_bf16 v[100:103], v[178:181], v[202:205], v[100:103]
	v_mfma_f32_16x16x32_bf16 v[84:87], v[178:181], v[210:213], v[84:87]
	v_mfma_f32_16x16x32_bf16 v[68:71], v[178:181], v[218:221], v[68:71]
	v_mfma_f32_16x16x32_bf16 v[64:67], v[186:189], v[218:221], v[64:67]
	v_mfma_f32_16x16x32_bf16 v[80:83], v[186:189], v[210:213], v[80:83]
	v_mfma_f32_16x16x32_bf16 v[96:99], v[186:189], v[202:205], v[96:99]
	v_mfma_f32_16x16x32_bf16 v[112:115], v[186:189], v[194:197], v[112:115]
	s_setprio 0
	s_barrier
	s_add_i32 s50, s73, s52
	v_lshl_add_u64 v[152:153], v[152:153], 0, s[22:23]
	s_mov_b32 m0, s50
	ds_read_b128 v[190:193], v159 offset:49152
	ds_read_b128 v[194:197], v159 offset:50176
	ds_read_b128 v[198:201], v159 offset:51200
	ds_read_b128 v[202:205], v159 offset:52224
	ds_read_b128 v[206:209], v159 offset:53248
	ds_read_b128 v[210:213], v159 offset:54272
	ds_read_b128 v[214:217], v159 offset:55296
	ds_read_b128 v[218:221], v159 offset:56320
	global_load_lds_dwordx4 v[152:153], off
	s_add_i32 m0, s50, 0x2000
	s_add_u32 s48, s48, 0x80080
	v_lshl_add_u64 v[152:153], v[222:223], 0, s[22:23]
	s_addc_u32 s49, s49, 0
	s_add_i32 s50, s74, s52
	global_load_lds_dwordx4 v[152:153], off
	v_lshl_add_u64 v[152:153], s[48:49], 0, v[130:131]
	s_mov_b32 m0, s50
	s_nop 0
	global_load_lds_dwordx4 v[152:153], off
	v_lshl_add_u64 v[152:153], s[48:49], 0, v[134:135]
	s_add_i32 m0, s50, 0x2000
	s_nop 0
	global_load_lds_dwordx4 v[152:153], off
	v_lshl_add_u64 v[152:153], v[224:225], 0, s[22:23]
	s_mov_b32 m0, s57
	s_nop 0
	global_load_lds_dwordx4 v[152:153], off
	v_lshl_add_u64 v[152:153], v[226:227], 0, s[22:23]
	s_mov_b32 m0, s58
	s_nop 0
	global_load_lds_dwordx4 v[152:153], off
	s_waitcnt vmcnt(8)
	s_waitcnt lgkmcnt(0)
	s_barrier
	s_setprio 1
	v_mfma_f32_16x16x32_bf16 v[60:63], v[148:151], v[190:193], v[60:63]
	v_mfma_f32_16x16x32_bf16 v[44:47], v[148:151], v[198:201], v[44:47]
	v_mfma_f32_16x16x32_bf16 v[28:31], v[148:151], v[206:209], v[28:31]
	v_mfma_f32_16x16x32_bf16 v[12:15], v[148:151], v[214:217], v[12:15]
	v_mfma_f32_16x16x32_bf16 v[8:11], v[166:169], v[214:217], v[8:11]
	v_mfma_f32_16x16x32_bf16 v[24:27], v[166:169], v[206:209], v[24:27]
	v_mfma_f32_16x16x32_bf16 v[40:43], v[166:169], v[198:201], v[40:43]
	v_mfma_f32_16x16x32_bf16 v[56:59], v[166:169], v[190:193], v[56:59]
	v_mfma_f32_16x16x32_bf16 v[60:63], v[162:165], v[194:197], v[60:63]
	v_mfma_f32_16x16x32_bf16 v[44:47], v[162:165], v[202:205], v[44:47]
	v_mfma_f32_16x16x32_bf16 v[28:31], v[162:165], v[210:213], v[28:31]
	v_mfma_f32_16x16x32_bf16 v[12:15], v[162:165], v[218:221], v[12:15]
	v_mfma_f32_16x16x32_bf16 v[8:11], v[170:173], v[218:221], v[8:11]
	v_mfma_f32_16x16x32_bf16 v[24:27], v[170:173], v[210:213], v[24:27]
	v_mfma_f32_16x16x32_bf16 v[40:43], v[170:173], v[202:205], v[40:43]
	v_mfma_f32_16x16x32_bf16 v[56:59], v[170:173], v[194:197], v[56:59]
	v_mfma_f32_16x16x32_bf16 v[52:55], v[174:177], v[190:193], v[52:55]
	v_mfma_f32_16x16x32_bf16 v[36:39], v[174:177], v[198:201], v[36:39]
	v_mfma_f32_16x16x32_bf16 v[20:23], v[174:177], v[206:209], v[20:23]
	v_mfma_f32_16x16x32_bf16 v[4:7], v[174:177], v[214:217], v[4:7]
	v_mfma_f32_16x16x32_bf16 v[0:3], v[182:185], v[214:217], v[0:3]
	v_mfma_f32_16x16x32_bf16 v[16:19], v[182:185], v[206:209], v[16:19]
	v_mfma_f32_16x16x32_bf16 v[32:35], v[182:185], v[198:201], v[32:35]
	v_mfma_f32_16x16x32_bf16 v[48:51], v[182:185], v[190:193], v[48:51]
	v_mfma_f32_16x16x32_bf16 v[52:55], v[178:181], v[194:197], v[52:55]
	v_mfma_f32_16x16x32_bf16 v[36:39], v[178:181], v[202:205], v[36:39]
	v_mfma_f32_16x16x32_bf16 v[20:23], v[178:181], v[210:213], v[20:23]
	v_mfma_f32_16x16x32_bf16 v[4:7], v[178:181], v[218:221], v[4:7]
	v_mfma_f32_16x16x32_bf16 v[0:3], v[186:189], v[218:221], v[0:3]
	v_mfma_f32_16x16x32_bf16 v[16:19], v[186:189], v[210:213], v[16:19]
	v_mfma_f32_16x16x32_bf16 v[32:35], v[186:189], v[202:205], v[32:35]
	v_mfma_f32_16x16x32_bf16 v[48:51], v[186:189], v[194:197], v[48:51]
	s_setprio 0
	s_barrier
	s_add_i32 s72, s72, 2
	s_add_u32 s70, s70, 0x100
	s_addc_u32 s71, s71, 0
	s_add_u32 s46, s46, 0x100
	s_addc_u32 s47, s47, 0
	s_cmp_gt_u32 s72, 29
	s_cbranch_scc0 .LBB0_178
	s_and_b64 vcc, exec, s[24:25]
	s_cbranch_vccz .LBB0_181
	s_barrier

.LBB0_337:
	ds_read_b128 v[144:147], v151
	ds_read_b128 v[156:159], v151 offset:1024
	ds_read_b128 v[160:163], v151 offset:2048
	ds_read_b128 v[164:167], v151 offset:3072
	ds_read_b128 v[168:171], v152
	ds_read_b128 v[172:175], v152 offset:1024
	ds_read_b128 v[176:179], v152 offset:2048
	ds_read_b128 v[180:183], v152 offset:3072
	s_add_u32 s50, s48, 0xfff80080
	s_addc_u32 s51, s49, -1
	s_cmp_eq_u32 s75, 28
	s_cselect_b32 s53, s31, s51
	s_cselect_b32 s52, s47, s50
	s_cselect_b32 s51, s27, s74
	s_cselect_b32 s50, s71, s72
	v_lshl_add_u64 v[216:217], s[48:49], 0, v[138:139]
	s_add_i32 m0, s57, 0xc000
	ds_read_b128 v[184:187], v153
	ds_read_b128 v[188:191], v153 offset:1024
	ds_read_b128 v[192:195], v153 offset:2048
	ds_read_b128 v[196:199], v153 offset:3072
	ds_read_b128 v[200:203], v153 offset:4096
	ds_read_b128 v[204:207], v153 offset:5120
	ds_read_b128 v[208:211], v153 offset:6144
	ds_read_b128 v[212:215], v153 offset:7168
	global_load_lds_dwordx4 v[216:217], off
	v_lshl_add_u64 v[216:217], s[48:49], 0, v[136:137]
	s_add_i32 m0, s57, 0xe000
	s_nop 0
	global_load_lds_dwordx4 v[216:217], off
	s_waitcnt vmcnt(8)
	s_waitcnt lgkmcnt(0)
	s_barrier
	s_setprio 1
	v_mfma_f32_16x16x32_bf16 v[124:127], v[144:147], v[184:187], v[124:127]
	v_mfma_f32_16x16x32_bf16 v[108:111], v[144:147], v[192:195], v[108:111]
	v_mfma_f32_16x16x32_bf16 v[92:95], v[144:147], v[200:203], v[92:95]
	v_mfma_f32_16x16x32_bf16 v[76:79], v[144:147], v[208:211], v[76:79]
	v_mfma_f32_16x16x32_bf16 v[72:75], v[160:163], v[208:211], v[72:75]
	v_mfma_f32_16x16x32_bf16 v[88:91], v[160:163], v[200:203], v[88:91]
	v_mfma_f32_16x16x32_bf16 v[104:107], v[160:163], v[192:195], v[104:107]
	v_mfma_f32_16x16x32_bf16 v[120:123], v[160:163], v[184:187], v[120:123]
	v_mfma_f32_16x16x32_bf16 v[124:127], v[156:159], v[188:191], v[124:127]
	v_mfma_f32_16x16x32_bf16 v[108:111], v[156:159], v[196:199], v[108:111]
	v_mfma_f32_16x16x32_bf16 v[92:95], v[156:159], v[204:207], v[92:95]
	v_mfma_f32_16x16x32_bf16 v[76:79], v[156:159], v[212:215], v[76:79]
	v_mfma_f32_16x16x32_bf16 v[72:75], v[164:167], v[212:215], v[72:75]
	v_mfma_f32_16x16x32_bf16 v[88:91], v[164:167], v[204:207], v[88:91]
	v_mfma_f32_16x16x32_bf16 v[104:107], v[164:167], v[196:199], v[104:107]
	v_mfma_f32_16x16x32_bf16 v[120:123], v[164:167], v[188:191], v[120:123]
	v_mfma_f32_16x16x32_bf16 v[116:119], v[168:171], v[184:187], v[116:119]
	v_mfma_f32_16x16x32_bf16 v[100:103], v[168:171], v[192:195], v[100:103]
	v_mfma_f32_16x16x32_bf16 v[84:87], v[168:171], v[200:203], v[84:87]
	v_mfma_f32_16x16x32_bf16 v[68:71], v[168:171], v[208:211], v[68:71]
	v_mfma_f32_16x16x32_bf16 v[64:67], v[176:179], v[208:211], v[64:67]
	v_mfma_f32_16x16x32_bf16 v[80:83], v[176:179], v[200:203], v[80:83]
	v_mfma_f32_16x16x32_bf16 v[96:99], v[176:179], v[192:195], v[96:99]
	v_mfma_f32_16x16x32_bf16 v[112:115], v[176:179], v[184:187], v[112:115]
	v_mfma_f32_16x16x32_bf16 v[116:119], v[172:175], v[188:191], v[116:119]
	v_mfma_f32_16x16x32_bf16 v[100:103], v[172:175], v[196:199], v[100:103]
	v_mfma_f32_16x16x32_bf16 v[84:87], v[172:175], v[204:207], v[84:87]
	v_mfma_f32_16x16x32_bf16 v[68:71], v[172:175], v[212:215], v[68:71]
	v_mfma_f32_16x16x32_bf16 v[64:67], v[180:183], v[212:215], v[64:67]
	v_mfma_f32_16x16x32_bf16 v[80:83], v[180:183], v[204:207], v[80:83]
	v_mfma_f32_16x16x32_bf16 v[96:99], v[180:183], v[196:199], v[96:99]
	v_mfma_f32_16x16x32_bf16 v[112:115], v[180:183], v[188:191], v[112:115]
	s_setprio 0
	s_barrier
	s_add_i32 s76, s66, s56
	v_lshl_add_u64 v[216:217], s[50:51], 0, v[130:131]
	s_mov_b32 m0, s76
	ds_read_b128 v[184:187], v153 offset:16384
	ds_read_b128 v[188:191], v153 offset:17408
	ds_read_b128 v[192:195], v153 offset:18432
	ds_read_b128 v[196:199], v153 offset:19456
	ds_read_b128 v[200:203], v153 offset:20480
	ds_read_b128 v[204:207], v153 offset:21504
	ds_read_b128 v[208:211], v153 offset:22528
	ds_read_b128 v[212:215], v153 offset:23552
	global_load_lds_dwordx4 v[216:217], off
	s_add_i32 m0, s76, 0x2000
	s_add_u32 s76, s50, 0x80000
	v_lshl_add_u64 v[218:219], s[50:51], 0, v[134:135]
	s_addc_u32 s77, s51, 0
	s_add_i32 s78, s67, s56
	global_load_lds_dwordx4 v[218:219], off
	v_lshl_add_u64 v[220:221], s[76:77], 0, v[130:131]
	s_mov_b32 m0, s78
	v_lshl_add_u64 v[222:223], s[52:53], 0, v[132:133]
	global_load_lds_dwordx4 v[220:221], off
	v_lshl_add_u64 v[220:221], s[76:77], 0, v[134:135]
	s_add_i32 m0, s78, 0x2000
	s_nop 0
	global_load_lds_dwordx4 v[220:221], off
	v_lshl_add_u64 v[220:221], s[52:53], 0, v[128:129]
	s_mov_b32 m0, s57
	s_nop 0
	global_load_lds_dwordx4 v[220:221], off
	s_mov_b32 m0, s58
	s_nop 0
	global_load_lds_dwordx4 v[222:223], off
	s_waitcnt vmcnt(8)
	s_waitcnt lgkmcnt(0)
	s_barrier
	s_setprio 1
	v_mfma_f32_16x16x32_bf16 v[60:63], v[144:147], v[184:187], v[60:63]
	v_mfma_f32_16x16x32_bf16 v[44:47], v[144:147], v[192:195], v[44:47]
	v_mfma_f32_16x16x32_bf16 v[28:31], v[144:147], v[200:203], v[28:31]
	v_mfma_f32_16x16x32_bf16 v[12:15], v[144:147], v[208:211], v[12:15]
	v_mfma_f32_16x16x32_bf16 v[8:11], v[160:163], v[208:211], v[8:11]
	v_mfma_f32_16x16x32_bf16 v[24:27], v[160:163], v[200:203], v[24:27]
	v_mfma_f32_16x16x32_bf16 v[40:43], v[160:163], v[192:195], v[40:43]
	v_mfma_f32_16x16x32_bf16 v[56:59], v[160:163], v[184:187], v[56:59]
	v_mfma_f32_16x16x32_bf16 v[60:63], v[156:159], v[188:191], v[60:63]
	v_mfma_f32_16x16x32_bf16 v[44:47], v[156:159], v[196:199], v[44:47]
	v_mfma_f32_16x16x32_bf16 v[28:31], v[156:159], v[204:207], v[28:31]
	v_mfma_f32_16x16x32_bf16 v[12:15], v[156:159], v[212:215], v[12:15]
	v_mfma_f32_16x16x32_bf16 v[8:11], v[164:167], v[212:215], v[8:11]
	v_mfma_f32_16x16x32_bf16 v[24:27], v[164:167], v[204:207], v[24:27]
	v_mfma_f32_16x16x32_bf16 v[40:43], v[164:167], v[196:199], v[40:43]
	v_mfma_f32_16x16x32_bf16 v[56:59], v[164:167], v[188:191], v[56:59]
	v_mfma_f32_16x16x32_bf16 v[52:55], v[168:171], v[184:187], v[52:55]
	v_mfma_f32_16x16x32_bf16 v[36:39], v[168:171], v[192:195], v[36:39]
	v_mfma_f32_16x16x32_bf16 v[20:23], v[168:171], v[200:203], v[20:23]
	v_mfma_f32_16x16x32_bf16 v[4:7], v[168:171], v[208:211], v[4:7]
	v_mfma_f32_16x16x32_bf16 v[0:3], v[176:179], v[208:211], v[0:3]
	v_mfma_f32_16x16x32_bf16 v[16:19], v[176:179], v[200:203], v[16:19]
	v_mfma_f32_16x16x32_bf16 v[32:35], v[176:179], v[192:195], v[32:35]
	v_mfma_f32_16x16x32_bf16 v[48:51], v[176:179], v[184:187], v[48:51]
	v_mfma_f32_16x16x32_bf16 v[52:55], v[172:175], v[188:191], v[52:55]
	v_mfma_f32_16x16x32_bf16 v[36:39], v[172:175], v[196:199], v[36:39]
	v_mfma_f32_16x16x32_bf16 v[20:23], v[172:175], v[204:207], v[20:23]
	v_mfma_f32_16x16x32_bf16 v[4:7], v[172:175], v[212:215], v[4:7]
	v_mfma_f32_16x16x32_bf16 v[0:3], v[180:183], v[212:215], v[0:3]
	v_mfma_f32_16x16x32_bf16 v[16:19], v[180:183], v[204:207], v[16:19]
	v_mfma_f32_16x16x32_bf16 v[32:35], v[180:183], v[196:199], v[32:35]
	v_mfma_f32_16x16x32_bf16 v[48:51], v[180:183], v[188:191], v[48:51]
	s_setprio 0
	s_barrier
	s_add_i32 s76, 0, 0x18000
	v_add_u32_e32 v155, s76, v149
	s_add_i32 s77, 0, 0x1c000
	ds_read_b128 v[144:147], v155
	ds_read_b128 v[156:159], v155 offset:1024
	ds_read_b128 v[160:163], v155 offset:2048
	ds_read_b128 v[164:167], v155 offset:3072
	v_add_u32_e32 v155, s77, v149
	ds_read_b128 v[168:171], v155
	ds_read_b128 v[172:175], v155 offset:1024
	ds_read_b128 v[176:179], v155 offset:2048
	ds_read_b128 v[180:183], v155 offset:3072
	s_add_u32 s52, s52, 0x80000
	s_addc_u32 s53, s53, 0
	s_mov_b32 m0, s59
	v_lshl_add_u64 v[224:225], s[52:53], 0, v[128:129]
	ds_read_b128 v[184:187], v153 offset:32768
	ds_read_b128 v[188:191], v153 offset:33792
	ds_read_b128 v[192:195], v153 offset:34816
	ds_read_b128 v[196:199], v153 offset:35840
	ds_read_b128 v[200:203], v153 offset:36864
	ds_read_b128 v[204:207], v153 offset:37888
	ds_read_b128 v[208:211], v153 offset:38912
	ds_read_b128 v[212:215], v153 offset:39936
	global_load_lds_dwordx4 v[224:225], off
	v_lshl_add_u64 v[224:225], s[52:53], 0, v[132:133]
	s_mov_b32 m0, s60
	s_nop 0
	global_load_lds_dwordx4 v[224:225], off
	s_waitcnt vmcnt(8)
	s_waitcnt lgkmcnt(0)
	s_barrier
	s_setprio 1
	v_mfma_f32_16x16x32_bf16 v[124:127], v[144:147], v[184:187], v[124:127]
	v_mfma_f32_16x16x32_bf16 v[108:111], v[144:147], v[192:195], v[108:111]
	v_mfma_f32_16x16x32_bf16 v[92:95], v[144:147], v[200:203], v[92:95]
	v_mfma_f32_16x16x32_bf16 v[76:79], v[144:147], v[208:211], v[76:79]
	v_mfma_f32_16x16x32_bf16 v[72:75], v[160:163], v[208:211], v[72:75]
	v_mfma_f32_16x16x32_bf16 v[88:91], v[160:163], v[200:203], v[88:91]
	v_mfma_f32_16x16x32_bf16 v[104:107], v[160:163], v[192:195], v[104:107]
	v_mfma_f32_16x16x32_bf16 v[120:123], v[160:163], v[184:187], v[120:123]
	v_mfma_f32_16x16x32_bf16 v[124:127], v[156:159], v[188:191], v[124:127]
	v_mfma_f32_16x16x32_bf16 v[108:111], v[156:159], v[196:199], v[108:111]
	v_mfma_f32_16x16x32_bf16 v[92:95], v[156:159], v[204:207], v[92:95]
	v_mfma_f32_16x16x32_bf16 v[76:79], v[156:159], v[212:215], v[76:79]
	v_mfma_f32_16x16x32_bf16 v[72:75], v[164:167], v[212:215], v[72:75]
	v_mfma_f32_16x16x32_bf16 v[88:91], v[164:167], v[204:207], v[88:91]
	v_mfma_f32_16x16x32_bf16 v[104:107], v[164:167], v[196:199], v[104:107]
	v_mfma_f32_16x16x32_bf16 v[120:123], v[164:167], v[188:191], v[120:123]
	v_mfma_f32_16x16x32_bf16 v[116:119], v[168:171], v[184:187], v[116:119]
	v_mfma_f32_16x16x32_bf16 v[100:103], v[168:171], v[192:195], v[100:103]
	v_mfma_f32_16x16x32_bf16 v[84:87], v[168:171], v[200:203], v[84:87]
	v_mfma_f32_16x16x32_bf16 v[68:71], v[168:171], v[208:211], v[68:71]
	v_mfma_f32_16x16x32_bf16 v[64:67], v[176:179], v[208:211], v[64:67]
	v_mfma_f32_16x16x32_bf16 v[80:83], v[176:179], v[200:203], v[80:83]
	v_mfma_f32_16x16x32_bf16 v[96:99], v[176:179], v[192:195], v[96:99]
	v_mfma_f32_16x16x32_bf16 v[112:115], v[176:179], v[184:187], v[112:115]
	v_mfma_f32_16x16x32_bf16 v[116:119], v[172:175], v[188:191], v[116:119]
	v_mfma_f32_16x16x32_bf16 v[100:103], v[172:175], v[196:199], v[100:103]
	v_mfma_f32_16x16x32_bf16 v[84:87], v[172:175], v[204:207], v[84:87]
	v_mfma_f32_16x16x32_bf16 v[68:71], v[172:175], v[212:215], v[68:71]
	v_mfma_f32_16x16x32_bf16 v[64:67], v[180:183], v[212:215], v[64:67]
	v_mfma_f32_16x16x32_bf16 v[80:83], v[180:183], v[204:207], v[80:83]
	v_mfma_f32_16x16x32_bf16 v[96:99], v[180:183], v[196:199], v[96:99]
	v_mfma_f32_16x16x32_bf16 v[112:115], v[180:183], v[188:191], v[112:115]
	s_setprio 0
	s_barrier
	s_add_i32 s52, s76, s56
	v_lshl_add_u64 v[216:217], v[216:217], 0, s[22:23]
	s_mov_b32 m0, s52
	ds_read_b128 v[184:187], v153 offset:49152
	ds_read_b128 v[188:191], v153 offset:50176
	ds_read_b128 v[192:195], v153 offset:51200
	ds_read_b128 v[196:199], v153 offset:52224
	ds_read_b128 v[200:203], v153 offset:53248
	ds_read_b128 v[204:207], v153 offset:54272
	ds_read_b128 v[208:211], v153 offset:55296
	ds_read_b128 v[212:215], v153 offset:56320
	global_load_lds_dwordx4 v[216:217], off
	s_add_i32 m0, s52, 0x2000
	s_add_u32 s50, s50, 0x80080
	v_lshl_add_u64 v[216:217], v[218:219], 0, s[22:23]
	s_addc_u32 s51, s51, 0
	s_add_i32 s52, s77, s56
	global_load_lds_dwordx4 v[216:217], off
	v_lshl_add_u64 v[216:217], s[50:51], 0, v[130:131]
	s_mov_b32 m0, s52
	s_nop 0
	global_load_lds_dwordx4 v[216:217], off
	v_lshl_add_u64 v[216:217], s[50:51], 0, v[134:135]
	s_add_i32 m0, s52, 0x2000
	s_nop 0
	global_load_lds_dwordx4 v[216:217], off
	v_lshl_add_u64 v[216:217], v[220:221], 0, s[22:23]
	s_mov_b32 m0, s62
	s_nop 0
	global_load_lds_dwordx4 v[216:217], off
	v_lshl_add_u64 v[216:217], v[222:223], 0, s[22:23]
	s_mov_b32 m0, s63
	s_nop 0
	global_load_lds_dwordx4 v[216:217], off
	s_waitcnt vmcnt(8)
	s_waitcnt lgkmcnt(0)
	s_barrier
	s_setprio 1
	v_mfma_f32_16x16x32_bf16 v[60:63], v[144:147], v[184:187], v[60:63]
	v_mfma_f32_16x16x32_bf16 v[44:47], v[144:147], v[192:195], v[44:47]
	v_mfma_f32_16x16x32_bf16 v[28:31], v[144:147], v[200:203], v[28:31]
	v_mfma_f32_16x16x32_bf16 v[12:15], v[144:147], v[208:211], v[12:15]
	v_mfma_f32_16x16x32_bf16 v[8:11], v[160:163], v[208:211], v[8:11]
	v_mfma_f32_16x16x32_bf16 v[24:27], v[160:163], v[200:203], v[24:27]
	v_mfma_f32_16x16x32_bf16 v[40:43], v[160:163], v[192:195], v[40:43]
	v_mfma_f32_16x16x32_bf16 v[56:59], v[160:163], v[184:187], v[56:59]
	v_mfma_f32_16x16x32_bf16 v[60:63], v[156:159], v[188:191], v[60:63]
	v_mfma_f32_16x16x32_bf16 v[44:47], v[156:159], v[196:199], v[44:47]
	v_mfma_f32_16x16x32_bf16 v[28:31], v[156:159], v[204:207], v[28:31]
	v_mfma_f32_16x16x32_bf16 v[12:15], v[156:159], v[212:215], v[12:15]
	v_mfma_f32_16x16x32_bf16 v[8:11], v[164:167], v[212:215], v[8:11]
	v_mfma_f32_16x16x32_bf16 v[24:27], v[164:167], v[204:207], v[24:27]
	v_mfma_f32_16x16x32_bf16 v[40:43], v[164:167], v[196:199], v[40:43]
	v_mfma_f32_16x16x32_bf16 v[56:59], v[164:167], v[188:191], v[56:59]
	v_mfma_f32_16x16x32_bf16 v[52:55], v[168:171], v[184:187], v[52:55]
	v_mfma_f32_16x16x32_bf16 v[36:39], v[168:171], v[192:195], v[36:39]
	v_mfma_f32_16x16x32_bf16 v[20:23], v[168:171], v[200:203], v[20:23]
	v_mfma_f32_16x16x32_bf16 v[4:7], v[168:171], v[208:211], v[4:7]
	v_mfma_f32_16x16x32_bf16 v[0:3], v[176:179], v[208:211], v[0:3]
	v_mfma_f32_16x16x32_bf16 v[16:19], v[176:179], v[200:203], v[16:19]
	v_mfma_f32_16x16x32_bf16 v[32:35], v[176:179], v[192:195], v[32:35]
	v_mfma_f32_16x16x32_bf16 v[48:51], v[176:179], v[184:187], v[48:51]
	v_mfma_f32_16x16x32_bf16 v[52:55], v[172:175], v[188:191], v[52:55]
	v_mfma_f32_16x16x32_bf16 v[36:39], v[172:175], v[196:199], v[36:39]
	v_mfma_f32_16x16x32_bf16 v[20:23], v[172:175], v[204:207], v[20:23]
	v_mfma_f32_16x16x32_bf16 v[4:7], v[172:175], v[212:215], v[4:7]
	v_mfma_f32_16x16x32_bf16 v[0:3], v[180:183], v[212:215], v[0:3]
	v_mfma_f32_16x16x32_bf16 v[16:19], v[180:183], v[204:207], v[16:19]
	v_mfma_f32_16x16x32_bf16 v[32:35], v[180:183], v[196:199], v[32:35]
	v_mfma_f32_16x16x32_bf16 v[48:51], v[180:183], v[188:191], v[48:51]
	s_setprio 0
	s_barrier
	s_add_i32 s75, s75, 2
	s_add_u32 s72, s72, 0x100
	s_addc_u32 s74, s74, 0
	s_add_u32 s48, s48, 0x100
	s_addc_u32 s49, s49, 0
	s_cmp_gt_u32 s75, 29
	s_cbranch_scc0 .LBB0_337
	s_and_b64 vcc, exec, s[24:25]
	s_cbranch_vccz .LBB0_340
	s_barrier

.LBB0_435:
	ds_read_b128 v[148:151], v222
	ds_read_b128 v[152:155], v222 offset:1024
	ds_read_b128 v[156:159], v222 offset:2048
	ds_read_b128 v[160:163], v222 offset:3072
	ds_read_b128 v[132:135], v223
	ds_read_b128 v[136:139], v223 offset:1024
	ds_read_b128 v[140:143], v223 offset:2048
	ds_read_b128 v[144:147], v223 offset:3072
	s_add_u32 s10, s54, 0xfff80080
	s_addc_u32 s11, s55, -1
	s_cmp_eq_u32 s84, 28
	s_cselect_b32 s59, s25, s11
	s_cselect_b32 s58, s46, s10
	s_cselect_b32 s57, s23, s83
	s_cselect_b32 s56, s47, s82
	v_lshl_add_u64 v[2:3], s[54:55], 0, v[208:209]
	s_add_i32 m0, s37, 0xc000
	s_waitcnt lgkmcnt(0)
	ds_read_b128 v[164:167], v224
	ds_read_b128 v[168:171], v224 offset:1024
	ds_read_b128 v[172:175], v224 offset:2048
	ds_read_b128 v[176:179], v224 offset:3072
	ds_read_b128 v[180:183], v224 offset:4096
	ds_read_b128 v[184:187], v224 offset:5120
	ds_read_b128 v[188:191], v224 offset:6144
	ds_read_b128 v[192:195], v224 offset:7168
	global_load_lds_dwordx4 v[2:3], off
	v_lshl_add_u64 v[2:3], s[54:55], 0, v[206:207]
	s_add_i32 m0, s37, 0xe000
	s_nop 0
	global_load_lds_dwordx4 v[2:3], off
	s_waitcnt vmcnt(8)
	s_waitcnt lgkmcnt(0)
	s_barrier
	s_setprio 1
	v_mfma_f32_16x16x32_bf16 v[120:123], v[148:151], v[164:167], v[120:123]
	v_mfma_f32_16x16x32_bf16 v[104:107], v[148:151], v[172:175], v[104:107]
	v_mfma_f32_16x16x32_bf16 v[88:91], v[148:151], v[180:183], v[88:91]
	v_mfma_f32_16x16x32_bf16 v[76:79], v[148:151], v[188:191], v[76:79]
	v_mfma_f32_16x16x32_bf16 v[72:75], v[156:159], v[188:191], v[72:75]
	v_mfma_f32_16x16x32_bf16 v[84:87], v[156:159], v[180:183], v[84:87]
	v_mfma_f32_16x16x32_bf16 v[100:103], v[156:159], v[172:175], v[100:103]
	v_mfma_f32_16x16x32_bf16 v[116:119], v[156:159], v[164:167], v[116:119]
	v_mfma_f32_16x16x32_bf16 v[120:123], v[152:155], v[168:171], v[120:123]
	v_mfma_f32_16x16x32_bf16 v[104:107], v[152:155], v[176:179], v[104:107]
	v_mfma_f32_16x16x32_bf16 v[88:91], v[152:155], v[184:187], v[88:91]
	v_mfma_f32_16x16x32_bf16 v[76:79], v[152:155], v[192:195], v[76:79]
	v_mfma_f32_16x16x32_bf16 v[72:75], v[160:163], v[192:195], v[72:75]
	v_mfma_f32_16x16x32_bf16 v[84:87], v[160:163], v[184:187], v[84:87]
	v_mfma_f32_16x16x32_bf16 v[100:103], v[160:163], v[176:179], v[100:103]
	v_mfma_f32_16x16x32_bf16 v[116:119], v[160:163], v[168:171], v[116:119]
	v_mfma_f32_16x16x32_bf16 v[128:131], v[132:135], v[164:167], v[128:131]
	v_mfma_f32_16x16x32_bf16 v[112:115], v[132:135], v[172:175], v[112:115]
	v_mfma_f32_16x16x32_bf16 v[96:99], v[132:135], v[180:183], v[96:99]
	v_mfma_f32_16x16x32_bf16 v[80:83], v[132:135], v[188:191], v[80:83]
	v_mfma_f32_16x16x32_bf16 v[68:71], v[140:143], v[188:191], v[68:71]
	v_mfma_f32_16x16x32_bf16 v[92:95], v[140:143], v[180:183], v[92:95]
	v_mfma_f32_16x16x32_bf16 v[108:111], v[140:143], v[172:175], v[108:111]
	v_mfma_f32_16x16x32_bf16 v[124:127], v[140:143], v[164:167], v[124:127]
	v_mfma_f32_16x16x32_bf16 v[128:131], v[136:139], v[168:171], v[128:131]
	v_mfma_f32_16x16x32_bf16 v[112:115], v[136:139], v[176:179], v[112:115]
	v_mfma_f32_16x16x32_bf16 v[96:99], v[136:139], v[184:187], v[96:99]
	v_mfma_f32_16x16x32_bf16 v[80:83], v[136:139], v[192:195], v[80:83]
	v_mfma_f32_16x16x32_bf16 v[68:71], v[144:147], v[192:195], v[68:71]
	v_mfma_f32_16x16x32_bf16 v[92:95], v[144:147], v[184:187], v[92:95]
	v_mfma_f32_16x16x32_bf16 v[108:111], v[144:147], v[176:179], v[108:111]
	v_mfma_f32_16x16x32_bf16 v[124:127], v[144:147], v[168:171], v[124:127]
	s_setprio 0
	s_barrier
	s_add_i32 s10, s67, s48
	v_lshl_add_u64 v[2:3], s[56:57], 0, v[198:199]
	s_mov_b32 m0, s10
	ds_read_b128 v[188:191], v224 offset:16384
	ds_read_b128 v[192:195], v224 offset:17408
	ds_read_b128 v[180:183], v224 offset:18432
	ds_read_b128 v[184:187], v224 offset:19456
	ds_read_b128 v[172:175], v224 offset:20480
	ds_read_b128 v[176:179], v224 offset:21504
	ds_read_b128 v[164:167], v224 offset:22528
	ds_read_b128 v[168:171], v224 offset:23552
	global_load_lds_dwordx4 v[2:3], off
	s_add_i32 m0, s10, 0x2000
	s_add_u32 s10, s56, 0x80000
	v_lshl_add_u64 v[212:213], s[56:57], 0, v[202:203]
	s_addc_u32 s11, s57, 0
	s_add_i32 s78, s70, s48
	global_load_lds_dwordx4 v[212:213], off
	v_lshl_add_u64 v[214:215], s[10:11], 0, v[198:199]
	s_mov_b32 m0, s78
	v_lshl_add_u64 v[216:217], s[58:59], 0, v[200:201]
	global_load_lds_dwordx4 v[214:215], off
	v_lshl_add_u64 v[214:215], s[10:11], 0, v[202:203]
	s_add_i32 m0, s78, 0x2000
	v_cmp_ne_u32_e64 s[10:11], 1, v227
	global_load_lds_dwordx4 v[214:215], off
	v_lshl_add_u64 v[214:215], s[58:59], 0, v[196:197]
	s_mov_b32 m0, s37
	s_andn2_b64 vcc, exec, s[52:53]
	global_load_lds_dwordx4 v[214:215], off
	s_mov_b32 m0, s60
	s_nop 0
	global_load_lds_dwordx4 v[216:217], off
	s_waitcnt vmcnt(8)
	s_waitcnt lgkmcnt(0)
	s_barrier
	s_cbranch_vccnz .LBB0_437
	s_setprio 1
	v_mfma_f32_16x16x32_bf16 v[56:59], v[148:151], v[188:191], v[56:59]
	v_mfma_f32_16x16x32_bf16 v[40:43], v[148:151], v[180:183], v[40:43]
	v_mfma_f32_16x16x32_bf16 v[24:27], v[148:151], v[172:175], v[24:27]
	v_mfma_f32_16x16x32_bf16 v[8:11], v[148:151], v[164:167], v[8:11]
	v_mfma_f32_16x16x32_bf16 v[4:7], v[156:159], v[164:167], v[4:7]
	v_mfma_f32_16x16x32_bf16 v[20:23], v[156:159], v[172:175], v[20:23]
	v_mfma_f32_16x16x32_bf16 v[36:39], v[156:159], v[180:183], v[36:39]
	v_mfma_f32_16x16x32_bf16 v[52:55], v[156:159], v[188:191], v[52:55]
	v_mfma_f32_16x16x32_bf16 v[56:59], v[152:155], v[192:195], v[56:59]
	v_mfma_f32_16x16x32_bf16 v[40:43], v[152:155], v[184:187], v[40:43]
	v_mfma_f32_16x16x32_bf16 v[24:27], v[152:155], v[176:179], v[24:27]
	v_mfma_f32_16x16x32_bf16 v[8:11], v[152:155], v[168:171], v[8:11]
	v_mfma_f32_16x16x32_bf16 v[4:7], v[160:163], v[168:171], v[4:7]
	v_mfma_f32_16x16x32_bf16 v[20:23], v[160:163], v[176:179], v[20:23]
	v_mfma_f32_16x16x32_bf16 v[36:39], v[160:163], v[184:187], v[36:39]
	v_mfma_f32_16x16x32_bf16 v[52:55], v[160:163], v[192:195], v[52:55]
	v_mfma_f32_16x16x32_bf16 v[64:67], v[132:135], v[188:191], v[64:67]
	v_mfma_f32_16x16x32_bf16 v[48:51], v[132:135], v[180:183], v[48:51]
	v_mfma_f32_16x16x32_bf16 v[32:35], v[132:135], v[172:175], v[32:35]
	v_mfma_f32_16x16x32_bf16 v[16:19], v[132:135], v[164:167], v[16:19]
	v_mfma_f32_16x16x32_bf16 v[12:15], v[140:143], v[164:167], v[12:15]
	v_mfma_f32_16x16x32_bf16 v[28:31], v[140:143], v[172:175], v[28:31]
	v_mfma_f32_16x16x32_bf16 v[44:47], v[140:143], v[180:183], v[44:47]
	v_mfma_f32_16x16x32_bf16 v[60:63], v[140:143], v[188:191], v[60:63]
	v_mfma_f32_16x16x32_bf16 v[64:67], v[136:139], v[192:195], v[64:67]
	v_mfma_f32_16x16x32_bf16 v[48:51], v[136:139], v[184:187], v[48:51]
	v_mfma_f32_16x16x32_bf16 v[32:35], v[136:139], v[176:179], v[32:35]
	v_mfma_f32_16x16x32_bf16 v[16:19], v[136:139], v[168:171], v[16:19]
	v_mfma_f32_16x16x32_bf16 v[12:15], v[144:147], v[168:171], v[12:15]
	v_mfma_f32_16x16x32_bf16 v[28:31], v[144:147], v[176:179], v[28:31]
	v_mfma_f32_16x16x32_bf16 v[44:47], v[144:147], v[184:187], v[44:47]
	v_mfma_f32_16x16x32_bf16 v[60:63], v[144:147], v[192:195], v[60:63]
	s_setprio 0
.LBB0_437:
	s_barrier
	s_add_i32 s78, 0, 0x18000
	v_add_u32_e32 v1, s78, v220
	s_add_i32 s79, 0, 0x1c000
	ds_read_b128 v[148:151], v1
	ds_read_b128 v[152:155], v1 offset:1024
	ds_read_b128 v[156:159], v1 offset:2048
	ds_read_b128 v[160:163], v1 offset:3072
	v_add_u32_e32 v1, s79, v220
	ds_read_b128 v[132:135], v1
	ds_read_b128 v[136:139], v1 offset:1024
	ds_read_b128 v[140:143], v1 offset:2048
	ds_read_b128 v[144:147], v1 offset:3072
	s_add_u32 s58, s58, 0x80000
	s_addc_u32 s59, s59, 0
	s_mov_b32 m0, s61
	v_lshl_add_u64 v[228:229], s[58:59], 0, v[196:197]
	s_waitcnt lgkmcnt(0)
	ds_read_b128 v[164:167], v224 offset:32768
	ds_read_b128 v[168:171], v224 offset:33792
	ds_read_b128 v[172:175], v224 offset:34816
	ds_read_b128 v[176:179], v224 offset:35840
	ds_read_b128 v[180:183], v224 offset:36864
	ds_read_b128 v[184:187], v224 offset:37888
	ds_read_b128 v[188:191], v224 offset:38912
	ds_read_b128 v[192:195], v224 offset:39936
	global_load_lds_dwordx4 v[228:229], off
	v_lshl_add_u64 v[228:229], s[58:59], 0, v[200:201]
	s_mov_b32 m0, s62
	s_nop 0
	global_load_lds_dwordx4 v[228:229], off
	s_waitcnt vmcnt(8)
	s_waitcnt lgkmcnt(0)
	s_barrier
	s_setprio 1
	v_mfma_f32_16x16x32_bf16 v[120:123], v[148:151], v[164:167], v[120:123]
	v_mfma_f32_16x16x32_bf16 v[104:107], v[148:151], v[172:175], v[104:107]
	v_mfma_f32_16x16x32_bf16 v[88:91], v[148:151], v[180:183], v[88:91]
	v_mfma_f32_16x16x32_bf16 v[76:79], v[148:151], v[188:191], v[76:79]
	v_mfma_f32_16x16x32_bf16 v[72:75], v[156:159], v[188:191], v[72:75]
	v_mfma_f32_16x16x32_bf16 v[84:87], v[156:159], v[180:183], v[84:87]
	v_mfma_f32_16x16x32_bf16 v[100:103], v[156:159], v[172:175], v[100:103]
	v_mfma_f32_16x16x32_bf16 v[116:119], v[156:159], v[164:167], v[116:119]
	v_mfma_f32_16x16x32_bf16 v[120:123], v[152:155], v[168:171], v[120:123]
	v_mfma_f32_16x16x32_bf16 v[104:107], v[152:155], v[176:179], v[104:107]
	v_mfma_f32_16x16x32_bf16 v[88:91], v[152:155], v[184:187], v[88:91]
	v_mfma_f32_16x16x32_bf16 v[76:79], v[152:155], v[192:195], v[76:79]
	v_mfma_f32_16x16x32_bf16 v[72:75], v[160:163], v[192:195], v[72:75]
	v_mfma_f32_16x16x32_bf16 v[84:87], v[160:163], v[184:187], v[84:87]
	v_mfma_f32_16x16x32_bf16 v[100:103], v[160:163], v[176:179], v[100:103]
	v_mfma_f32_16x16x32_bf16 v[116:119], v[160:163], v[168:171], v[116:119]
	v_mfma_f32_16x16x32_bf16 v[128:131], v[132:135], v[164:167], v[128:131]
	v_mfma_f32_16x16x32_bf16 v[112:115], v[132:135], v[172:175], v[112:115]
	v_mfma_f32_16x16x32_bf16 v[96:99], v[132:135], v[180:183], v[96:99]
	v_mfma_f32_16x16x32_bf16 v[80:83], v[132:135], v[188:191], v[80:83]
	v_mfma_f32_16x16x32_bf16 v[68:71], v[140:143], v[188:191], v[68:71]
	v_mfma_f32_16x16x32_bf16 v[92:95], v[140:143], v[180:183], v[92:95]
	v_mfma_f32_16x16x32_bf16 v[108:111], v[140:143], v[172:175], v[108:111]
	v_mfma_f32_16x16x32_bf16 v[124:127], v[140:143], v[164:167], v[124:127]
	v_mfma_f32_16x16x32_bf16 v[128:131], v[136:139], v[168:171], v[128:131]
	v_mfma_f32_16x16x32_bf16 v[112:115], v[136:139], v[176:179], v[112:115]
	v_mfma_f32_16x16x32_bf16 v[96:99], v[136:139], v[184:187], v[96:99]
	v_mfma_f32_16x16x32_bf16 v[80:83], v[136:139], v[192:195], v[80:83]
	v_mfma_f32_16x16x32_bf16 v[68:71], v[144:147], v[192:195], v[68:71]
	v_mfma_f32_16x16x32_bf16 v[92:95], v[144:147], v[184:187], v[92:95]
	v_mfma_f32_16x16x32_bf16 v[108:111], v[144:147], v[176:179], v[108:111]
	v_mfma_f32_16x16x32_bf16 v[124:127], v[144:147], v[168:171], v[124:127]
	s_setprio 0
	s_barrier
	s_add_i32 s58, s78, s48
	v_lshl_add_u64 v[2:3], v[2:3], 0, s[16:17]
	s_mov_b32 m0, s58
	ds_read_b128 v[188:191], v224 offset:49152
	ds_read_b128 v[192:195], v224 offset:50176
	ds_read_b128 v[180:183], v224 offset:51200
	ds_read_b128 v[184:187], v224 offset:52224
	ds_read_b128 v[172:175], v224 offset:53248
	ds_read_b128 v[176:179], v224 offset:54272
	ds_read_b128 v[164:167], v224 offset:55296
	ds_read_b128 v[168:171], v224 offset:56320
	global_load_lds_dwordx4 v[2:3], off
	s_add_i32 m0, s58, 0x2000
	s_add_u32 s56, s56, 0x80080
	v_lshl_add_u64 v[2:3], v[212:213], 0, s[16:17]
	s_addc_u32 s57, s57, 0
	s_add_i32 s58, s79, s48
	global_load_lds_dwordx4 v[2:3], off
	v_lshl_add_u64 v[2:3], s[56:57], 0, v[198:199]
	s_mov_b32 m0, s58
	s_and_b64 vcc, exec, s[10:11]
	global_load_lds_dwordx4 v[2:3], off
	v_lshl_add_u64 v[2:3], s[56:57], 0, v[202:203]
	s_add_i32 m0, s58, 0x2000
	s_nop 0
	global_load_lds_dwordx4 v[2:3], off
	v_lshl_add_u64 v[2:3], v[214:215], 0, s[16:17]
	s_mov_b32 m0, s63
	s_nop 0
	global_load_lds_dwordx4 v[2:3], off
	v_lshl_add_u64 v[2:3], v[216:217], 0, s[16:17]
	s_mov_b32 m0, s64
	s_nop 0
	global_load_lds_dwordx4 v[2:3], off
	s_waitcnt vmcnt(8)
	s_waitcnt lgkmcnt(0)
	s_barrier
	s_cbranch_vccnz .LBB0_434
	s_setprio 1
	v_mfma_f32_16x16x32_bf16 v[56:59], v[148:151], v[188:191], v[56:59]
	v_mfma_f32_16x16x32_bf16 v[52:55], v[156:159], v[188:191], v[52:55]
	v_mfma_f32_16x16x32_bf16 v[40:43], v[148:151], v[180:183], v[40:43]
	v_mfma_f32_16x16x32_bf16 v[36:39], v[156:159], v[180:183], v[36:39]
	v_mfma_f32_16x16x32_bf16 v[24:27], v[148:151], v[172:175], v[24:27]
	v_mfma_f32_16x16x32_bf16 v[20:23], v[156:159], v[172:175], v[20:23]
	v_mfma_f32_16x16x32_bf16 v[8:11], v[148:151], v[164:167], v[8:11]
	v_mfma_f32_16x16x32_bf16 v[2:5], v[156:159], v[164:167], v[4:7]
	v_mfma_f32_16x16x32_bf16 v[56:59], v[152:155], v[192:195], v[56:59]
	v_mfma_f32_16x16x32_bf16 v[52:55], v[160:163], v[192:195], v[52:55]
	v_mfma_f32_16x16x32_bf16 v[40:43], v[152:155], v[184:187], v[40:43]
	v_mfma_f32_16x16x32_bf16 v[36:39], v[160:163], v[184:187], v[36:39]
	v_mfma_f32_16x16x32_bf16 v[24:27], v[152:155], v[176:179], v[24:27]
	v_mfma_f32_16x16x32_bf16 v[20:23], v[160:163], v[176:179], v[20:23]
	v_mfma_f32_16x16x32_bf16 v[8:11], v[152:155], v[168:171], v[8:11]
	v_mfma_f32_16x16x32_bf16 v[4:7], v[160:163], v[168:171], v[2:5]
	v_mfma_f32_16x16x32_bf16 v[64:67], v[132:135], v[188:191], v[64:67]
	v_mfma_f32_16x16x32_bf16 v[48:51], v[132:135], v[180:183], v[48:51]
	v_mfma_f32_16x16x32_bf16 v[32:35], v[132:135], v[172:175], v[32:35]
	v_mfma_f32_16x16x32_bf16 v[16:19], v[132:135], v[164:167], v[16:19]
	v_mfma_f32_16x16x32_bf16 v[12:15], v[140:143], v[164:167], v[12:15]
	v_mfma_f32_16x16x32_bf16 v[28:31], v[140:143], v[172:175], v[28:31]
	v_mfma_f32_16x16x32_bf16 v[44:47], v[140:143], v[180:183], v[44:47]
	v_mfma_f32_16x16x32_bf16 v[60:63], v[140:143], v[188:191], v[60:63]
	v_mfma_f32_16x16x32_bf16 v[64:67], v[136:139], v[192:195], v[64:67]
	v_mfma_f32_16x16x32_bf16 v[48:51], v[136:139], v[184:187], v[48:51]
	v_mfma_f32_16x16x32_bf16 v[32:35], v[136:139], v[176:179], v[32:35]
	v_mfma_f32_16x16x32_bf16 v[16:19], v[136:139], v[168:171], v[16:19]
	v_mfma_f32_16x16x32_bf16 v[12:15], v[144:147], v[168:171], v[12:15]
	v_mfma_f32_16x16x32_bf16 v[28:31], v[144:147], v[176:179], v[28:31]
	v_mfma_f32_16x16x32_bf16 v[44:47], v[144:147], v[184:187], v[44:47]
	v_mfma_f32_16x16x32_bf16 v[60:63], v[144:147], v[192:195], v[60:63]
	s_setprio 0
	s_branch .LBB0_434

.LBB0_523:
	ds_read_b128 v[144:147], v151
	ds_read_b128 v[156:159], v151 offset:1024
	ds_read_b128 v[160:163], v151 offset:2048
	ds_read_b128 v[164:167], v151 offset:3072
	ds_read_b128 v[168:171], v152
	ds_read_b128 v[172:175], v152 offset:1024
	ds_read_b128 v[176:179], v152 offset:2048
	ds_read_b128 v[180:183], v152 offset:3072
	s_add_u32 s36, s34, 0x100
	s_addc_u32 s37, s35, 0
	s_cmpk_eq_i32 s66, 0x54
	s_cselect_b32 s55, s13, s37
	s_cselect_b32 s54, s12, s36
	s_cselect_b32 s53, s31, s47
	s_cselect_b32 s52, s30, s46
	v_lshl_add_u64 v[216:217], s[34:35], 0, v[138:139]
	s_add_i32 m0, s49, 0xc000
	ds_read_b128 v[184:187], v153
	ds_read_b128 v[188:191], v153 offset:1024
	ds_read_b128 v[192:195], v153 offset:2048
	ds_read_b128 v[196:199], v153 offset:3072
	ds_read_b128 v[200:203], v153 offset:4096
	ds_read_b128 v[204:207], v153 offset:5120
	ds_read_b128 v[208:211], v153 offset:6144
	ds_read_b128 v[212:215], v153 offset:7168
	global_load_lds_dwordx4 v[216:217], off
	v_lshl_add_u64 v[216:217], s[34:35], 0, v[136:137]
	s_add_i32 m0, s49, 0xe000
	s_nop 0
	global_load_lds_dwordx4 v[216:217], off
	s_waitcnt vmcnt(8)
	s_waitcnt lgkmcnt(0)
	s_barrier
	s_setprio 1
	v_mfma_f32_16x16x32_bf16 v[124:127], v[144:147], v[184:187], v[124:127]
	v_mfma_f32_16x16x32_bf16 v[108:111], v[144:147], v[192:195], v[108:111]
	v_mfma_f32_16x16x32_bf16 v[92:95], v[144:147], v[200:203], v[92:95]
	v_mfma_f32_16x16x32_bf16 v[76:79], v[144:147], v[208:211], v[76:79]
	v_mfma_f32_16x16x32_bf16 v[72:75], v[160:163], v[208:211], v[72:75]
	v_mfma_f32_16x16x32_bf16 v[88:91], v[160:163], v[200:203], v[88:91]
	v_mfma_f32_16x16x32_bf16 v[104:107], v[160:163], v[192:195], v[104:107]
	v_mfma_f32_16x16x32_bf16 v[120:123], v[160:163], v[184:187], v[120:123]
	v_mfma_f32_16x16x32_bf16 v[124:127], v[156:159], v[188:191], v[124:127]
	v_mfma_f32_16x16x32_bf16 v[108:111], v[156:159], v[196:199], v[108:111]
	v_mfma_f32_16x16x32_bf16 v[92:95], v[156:159], v[204:207], v[92:95]
	v_mfma_f32_16x16x32_bf16 v[76:79], v[156:159], v[212:215], v[76:79]
	v_mfma_f32_16x16x32_bf16 v[72:75], v[164:167], v[212:215], v[72:75]
	v_mfma_f32_16x16x32_bf16 v[88:91], v[164:167], v[204:207], v[88:91]
	v_mfma_f32_16x16x32_bf16 v[104:107], v[164:167], v[196:199], v[104:107]
	v_mfma_f32_16x16x32_bf16 v[120:123], v[164:167], v[188:191], v[120:123]
	v_mfma_f32_16x16x32_bf16 v[116:119], v[168:171], v[184:187], v[116:119]
	v_mfma_f32_16x16x32_bf16 v[100:103], v[168:171], v[192:195], v[100:103]
	v_mfma_f32_16x16x32_bf16 v[84:87], v[168:171], v[200:203], v[84:87]
	v_mfma_f32_16x16x32_bf16 v[68:71], v[168:171], v[208:211], v[68:71]
	v_mfma_f32_16x16x32_bf16 v[64:67], v[176:179], v[208:211], v[64:67]
	v_mfma_f32_16x16x32_bf16 v[80:83], v[176:179], v[200:203], v[80:83]
	v_mfma_f32_16x16x32_bf16 v[96:99], v[176:179], v[192:195], v[96:99]
	v_mfma_f32_16x16x32_bf16 v[112:115], v[176:179], v[184:187], v[112:115]
	v_mfma_f32_16x16x32_bf16 v[116:119], v[172:175], v[188:191], v[116:119]
	v_mfma_f32_16x16x32_bf16 v[100:103], v[172:175], v[196:199], v[100:103]
	v_mfma_f32_16x16x32_bf16 v[84:87], v[172:175], v[204:207], v[84:87]
	v_mfma_f32_16x16x32_bf16 v[68:71], v[172:175], v[212:215], v[68:71]
	v_mfma_f32_16x16x32_bf16 v[64:67], v[180:183], v[212:215], v[64:67]
	v_mfma_f32_16x16x32_bf16 v[80:83], v[180:183], v[204:207], v[80:83]
	v_mfma_f32_16x16x32_bf16 v[96:99], v[180:183], v[196:199], v[96:99]
	v_mfma_f32_16x16x32_bf16 v[112:115], v[180:183], v[188:191], v[112:115]
	s_setprio 0
	s_barrier
	s_add_i32 s34, s62, s48
	v_lshl_add_u64 v[216:217], s[52:53], 0, v[130:131]
	s_mov_b32 m0, s34
	ds_read_b128 v[184:187], v153 offset:16384
	ds_read_b128 v[188:191], v153 offset:17408
	ds_read_b128 v[192:195], v153 offset:18432
	ds_read_b128 v[196:199], v153 offset:19456
	ds_read_b128 v[200:203], v153 offset:20480
	ds_read_b128 v[204:207], v153 offset:21504
	ds_read_b128 v[208:211], v153 offset:22528
	ds_read_b128 v[212:215], v153 offset:23552
	global_load_lds_dwordx4 v[216:217], off
	s_add_i32 m0, s34, 0x2000
	s_add_u32 s34, s52, 0x160000
	v_lshl_add_u64 v[218:219], s[52:53], 0, v[134:135]
	s_addc_u32 s35, s53, 0
	s_add_i32 s67, s63, s48
	global_load_lds_dwordx4 v[218:219], off
	v_lshl_add_u64 v[220:221], s[34:35], 0, v[130:131]
	s_mov_b32 m0, s67
	v_lshl_add_u64 v[222:223], s[54:55], 0, v[132:133]
	global_load_lds_dwordx4 v[220:221], off
	v_lshl_add_u64 v[220:221], s[34:35], 0, v[134:135]
	s_add_i32 m0, s67, 0x2000
	s_nop 0
	global_load_lds_dwordx4 v[220:221], off
	v_lshl_add_u64 v[220:221], s[54:55], 0, v[128:129]
	s_mov_b32 m0, s49
	s_nop 0
	global_load_lds_dwordx4 v[220:221], off
	s_mov_b32 m0, s56
	s_nop 0
	global_load_lds_dwordx4 v[222:223], off
	s_waitcnt vmcnt(8)
	s_waitcnt lgkmcnt(0)
	s_barrier
	s_setprio 1
	v_mfma_f32_16x16x32_bf16 v[60:63], v[144:147], v[184:187], v[60:63]
	v_mfma_f32_16x16x32_bf16 v[44:47], v[144:147], v[192:195], v[44:47]
	v_mfma_f32_16x16x32_bf16 v[28:31], v[144:147], v[200:203], v[28:31]
	v_mfma_f32_16x16x32_bf16 v[12:15], v[144:147], v[208:211], v[12:15]
	v_mfma_f32_16x16x32_bf16 v[8:11], v[160:163], v[208:211], v[8:11]
	v_mfma_f32_16x16x32_bf16 v[24:27], v[160:163], v[200:203], v[24:27]
	v_mfma_f32_16x16x32_bf16 v[40:43], v[160:163], v[192:195], v[40:43]
	v_mfma_f32_16x16x32_bf16 v[56:59], v[160:163], v[184:187], v[56:59]
	v_mfma_f32_16x16x32_bf16 v[60:63], v[156:159], v[188:191], v[60:63]
	v_mfma_f32_16x16x32_bf16 v[44:47], v[156:159], v[196:199], v[44:47]
	v_mfma_f32_16x16x32_bf16 v[28:31], v[156:159], v[204:207], v[28:31]
	v_mfma_f32_16x16x32_bf16 v[12:15], v[156:159], v[212:215], v[12:15]
	v_mfma_f32_16x16x32_bf16 v[8:11], v[164:167], v[212:215], v[8:11]
	v_mfma_f32_16x16x32_bf16 v[24:27], v[164:167], v[204:207], v[24:27]
	v_mfma_f32_16x16x32_bf16 v[40:43], v[164:167], v[196:199], v[40:43]
	v_mfma_f32_16x16x32_bf16 v[56:59], v[164:167], v[188:191], v[56:59]
	v_mfma_f32_16x16x32_bf16 v[52:55], v[168:171], v[184:187], v[52:55]
	v_mfma_f32_16x16x32_bf16 v[36:39], v[168:171], v[192:195], v[36:39]
	v_mfma_f32_16x16x32_bf16 v[20:23], v[168:171], v[200:203], v[20:23]
	v_mfma_f32_16x16x32_bf16 v[4:7], v[168:171], v[208:211], v[4:7]
	v_mfma_f32_16x16x32_bf16 v[0:3], v[176:179], v[208:211], v[0:3]
	v_mfma_f32_16x16x32_bf16 v[16:19], v[176:179], v[200:203], v[16:19]
	v_mfma_f32_16x16x32_bf16 v[32:35], v[176:179], v[192:195], v[32:35]
	v_mfma_f32_16x16x32_bf16 v[48:51], v[176:179], v[184:187], v[48:51]
	v_mfma_f32_16x16x32_bf16 v[52:55], v[172:175], v[188:191], v[52:55]
	v_mfma_f32_16x16x32_bf16 v[36:39], v[172:175], v[196:199], v[36:39]
	v_mfma_f32_16x16x32_bf16 v[20:23], v[172:175], v[204:207], v[20:23]
	v_mfma_f32_16x16x32_bf16 v[4:7], v[172:175], v[212:215], v[4:7]
	v_mfma_f32_16x16x32_bf16 v[0:3], v[180:183], v[212:215], v[0:3]
	v_mfma_f32_16x16x32_bf16 v[16:19], v[180:183], v[204:207], v[16:19]
	v_mfma_f32_16x16x32_bf16 v[32:35], v[180:183], v[196:199], v[32:35]
	v_mfma_f32_16x16x32_bf16 v[48:51], v[180:183], v[188:191], v[48:51]
	s_setprio 0
	s_barrier
	s_add_i32 s67, 0, 0x18000
	v_add_u32_e32 v155, s67, v149
	s_add_i32 s70, 0, 0x1c000
	ds_read_b128 v[144:147], v155
	ds_read_b128 v[156:159], v155 offset:1024
	ds_read_b128 v[160:163], v155 offset:2048
	ds_read_b128 v[164:167], v155 offset:3072
	v_add_u32_e32 v155, s70, v149
	ds_read_b128 v[168:171], v155
	ds_read_b128 v[172:175], v155 offset:1024
	ds_read_b128 v[176:179], v155 offset:2048
	ds_read_b128 v[180:183], v155 offset:3072
	s_add_u32 s34, s54, 0x160000
	s_addc_u32 s35, s55, 0
	s_mov_b32 m0, s57
	v_lshl_add_u64 v[224:225], s[34:35], 0, v[128:129]
	ds_read_b128 v[184:187], v153 offset:32768
	ds_read_b128 v[188:191], v153 offset:33792
	ds_read_b128 v[192:195], v153 offset:34816
	ds_read_b128 v[196:199], v153 offset:35840
	ds_read_b128 v[200:203], v153 offset:36864
	ds_read_b128 v[204:207], v153 offset:37888
	ds_read_b128 v[208:211], v153 offset:38912
	ds_read_b128 v[212:215], v153 offset:39936
	global_load_lds_dwordx4 v[224:225], off
	v_lshl_add_u64 v[224:225], s[34:35], 0, v[132:133]
	s_mov_b32 m0, s58
	s_nop 0
	global_load_lds_dwordx4 v[224:225], off
	s_waitcnt vmcnt(8)
	s_waitcnt lgkmcnt(0)
	s_barrier
	s_setprio 1
	v_mfma_f32_16x16x32_bf16 v[124:127], v[144:147], v[184:187], v[124:127]
	v_mfma_f32_16x16x32_bf16 v[108:111], v[144:147], v[192:195], v[108:111]
	v_mfma_f32_16x16x32_bf16 v[92:95], v[144:147], v[200:203], v[92:95]
	v_mfma_f32_16x16x32_bf16 v[76:79], v[144:147], v[208:211], v[76:79]
	v_mfma_f32_16x16x32_bf16 v[72:75], v[160:163], v[208:211], v[72:75]
	v_mfma_f32_16x16x32_bf16 v[88:91], v[160:163], v[200:203], v[88:91]
	v_mfma_f32_16x16x32_bf16 v[104:107], v[160:163], v[192:195], v[104:107]
	v_mfma_f32_16x16x32_bf16 v[120:123], v[160:163], v[184:187], v[120:123]
	v_mfma_f32_16x16x32_bf16 v[124:127], v[156:159], v[188:191], v[124:127]
	v_mfma_f32_16x16x32_bf16 v[108:111], v[156:159], v[196:199], v[108:111]
	v_mfma_f32_16x16x32_bf16 v[92:95], v[156:159], v[204:207], v[92:95]
	v_mfma_f32_16x16x32_bf16 v[76:79], v[156:159], v[212:215], v[76:79]
	v_mfma_f32_16x16x32_bf16 v[72:75], v[164:167], v[212:215], v[72:75]
	v_mfma_f32_16x16x32_bf16 v[88:91], v[164:167], v[204:207], v[88:91]
	v_mfma_f32_16x16x32_bf16 v[104:107], v[164:167], v[196:199], v[104:107]
	v_mfma_f32_16x16x32_bf16 v[120:123], v[164:167], v[188:191], v[120:123]
	v_mfma_f32_16x16x32_bf16 v[116:119], v[168:171], v[184:187], v[116:119]
	v_mfma_f32_16x16x32_bf16 v[100:103], v[168:171], v[192:195], v[100:103]
	v_mfma_f32_16x16x32_bf16 v[84:87], v[168:171], v[200:203], v[84:87]
	v_mfma_f32_16x16x32_bf16 v[68:71], v[168:171], v[208:211], v[68:71]
	v_mfma_f32_16x16x32_bf16 v[64:67], v[176:179], v[208:211], v[64:67]
	v_mfma_f32_16x16x32_bf16 v[80:83], v[176:179], v[200:203], v[80:83]
	v_mfma_f32_16x16x32_bf16 v[96:99], v[176:179], v[192:195], v[96:99]
	v_mfma_f32_16x16x32_bf16 v[112:115], v[176:179], v[184:187], v[112:115]
	v_mfma_f32_16x16x32_bf16 v[116:119], v[172:175], v[188:191], v[116:119]
	v_mfma_f32_16x16x32_bf16 v[100:103], v[172:175], v[196:199], v[100:103]
	v_mfma_f32_16x16x32_bf16 v[84:87], v[172:175], v[204:207], v[84:87]
	v_mfma_f32_16x16x32_bf16 v[68:71], v[172:175], v[212:215], v[68:71]
	v_mfma_f32_16x16x32_bf16 v[64:67], v[180:183], v[212:215], v[64:67]
	v_mfma_f32_16x16x32_bf16 v[80:83], v[180:183], v[204:207], v[80:83]
	v_mfma_f32_16x16x32_bf16 v[96:99], v[180:183], v[196:199], v[96:99]
	v_mfma_f32_16x16x32_bf16 v[112:115], v[180:183], v[188:191], v[112:115]
	s_setprio 0
	s_barrier
	s_add_i32 s34, s67, s48
	v_lshl_add_u64 v[216:217], v[216:217], 0, s[24:25]
	s_mov_b32 m0, s34
	ds_read_b128 v[184:187], v153 offset:49152
	ds_read_b128 v[188:191], v153 offset:50176
	ds_read_b128 v[192:195], v153 offset:51200
	ds_read_b128 v[196:199], v153 offset:52224
	ds_read_b128 v[200:203], v153 offset:53248
	ds_read_b128 v[204:207], v153 offset:54272
	ds_read_b128 v[208:211], v153 offset:55296
	ds_read_b128 v[212:215], v153 offset:56320
	global_load_lds_dwordx4 v[216:217], off
	s_add_i32 m0, s34, 0x2000
	s_add_u32 s34, s52, 0x160080
	v_lshl_add_u64 v[216:217], v[218:219], 0, s[24:25]
	s_addc_u32 s35, s53, 0
	s_add_i32 s52, s70, s48
	global_load_lds_dwordx4 v[216:217], off
	v_lshl_add_u64 v[216:217], s[34:35], 0, v[130:131]
	s_mov_b32 m0, s52
	s_nop 0
	global_load_lds_dwordx4 v[216:217], off
	v_lshl_add_u64 v[216:217], s[34:35], 0, v[134:135]
	s_add_i32 m0, s52, 0x2000
	s_nop 0
	global_load_lds_dwordx4 v[216:217], off
	v_lshl_add_u64 v[216:217], v[220:221], 0, s[24:25]
	s_mov_b32 m0, s60
	s_nop 0
	global_load_lds_dwordx4 v[216:217], off
	v_lshl_add_u64 v[216:217], v[222:223], 0, s[24:25]
	s_mov_b32 m0, s61
	s_nop 0
	global_load_lds_dwordx4 v[216:217], off
	s_waitcnt vmcnt(8)
	s_waitcnt lgkmcnt(0)
	s_barrier
	s_setprio 1
	v_mfma_f32_16x16x32_bf16 v[60:63], v[144:147], v[184:187], v[60:63]
	v_mfma_f32_16x16x32_bf16 v[44:47], v[144:147], v[192:195], v[44:47]
	v_mfma_f32_16x16x32_bf16 v[28:31], v[144:147], v[200:203], v[28:31]
	v_mfma_f32_16x16x32_bf16 v[12:15], v[144:147], v[208:211], v[12:15]
	v_mfma_f32_16x16x32_bf16 v[8:11], v[160:163], v[208:211], v[8:11]
	v_mfma_f32_16x16x32_bf16 v[24:27], v[160:163], v[200:203], v[24:27]
	v_mfma_f32_16x16x32_bf16 v[40:43], v[160:163], v[192:195], v[40:43]
	v_mfma_f32_16x16x32_bf16 v[56:59], v[160:163], v[184:187], v[56:59]
	v_mfma_f32_16x16x32_bf16 v[60:63], v[156:159], v[188:191], v[60:63]
	v_mfma_f32_16x16x32_bf16 v[44:47], v[156:159], v[196:199], v[44:47]
	v_mfma_f32_16x16x32_bf16 v[28:31], v[156:159], v[204:207], v[28:31]
	v_mfma_f32_16x16x32_bf16 v[12:15], v[156:159], v[212:215], v[12:15]
	v_mfma_f32_16x16x32_bf16 v[8:11], v[164:167], v[212:215], v[8:11]
	v_mfma_f32_16x16x32_bf16 v[24:27], v[164:167], v[204:207], v[24:27]
	v_mfma_f32_16x16x32_bf16 v[40:43], v[164:167], v[196:199], v[40:43]
	v_mfma_f32_16x16x32_bf16 v[56:59], v[164:167], v[188:191], v[56:59]
	v_mfma_f32_16x16x32_bf16 v[52:55], v[168:171], v[184:187], v[52:55]
	v_mfma_f32_16x16x32_bf16 v[36:39], v[168:171], v[192:195], v[36:39]
	v_mfma_f32_16x16x32_bf16 v[20:23], v[168:171], v[200:203], v[20:23]
	v_mfma_f32_16x16x32_bf16 v[4:7], v[168:171], v[208:211], v[4:7]
	v_mfma_f32_16x16x32_bf16 v[0:3], v[176:179], v[208:211], v[0:3]
	v_mfma_f32_16x16x32_bf16 v[16:19], v[176:179], v[200:203], v[16:19]
	v_mfma_f32_16x16x32_bf16 v[32:35], v[176:179], v[192:195], v[32:35]
	v_mfma_f32_16x16x32_bf16 v[48:51], v[176:179], v[184:187], v[48:51]
	v_mfma_f32_16x16x32_bf16 v[52:55], v[172:175], v[188:191], v[52:55]
	v_mfma_f32_16x16x32_bf16 v[36:39], v[172:175], v[196:199], v[36:39]
	v_mfma_f32_16x16x32_bf16 v[20:23], v[172:175], v[204:207], v[20:23]
	v_mfma_f32_16x16x32_bf16 v[4:7], v[172:175], v[212:215], v[4:7]
	v_mfma_f32_16x16x32_bf16 v[0:3], v[180:183], v[212:215], v[0:3]
	v_mfma_f32_16x16x32_bf16 v[16:19], v[180:183], v[204:207], v[16:19]
	v_mfma_f32_16x16x32_bf16 v[32:35], v[180:183], v[196:199], v[32:35]
	v_mfma_f32_16x16x32_bf16 v[48:51], v[180:183], v[188:191], v[48:51]
	s_setprio 0
	s_barrier
	s_add_i32 s66, s66, 2
	s_add_u32 s46, s46, 0x100
	s_addc_u32 s47, s47, 0
	s_cmpk_gt_u32 s66, 0x55
	s_mov_b64 s[34:35], s[36:37]
	s_cbranch_scc0 .LBB0_523
	s_and_b64 vcc, exec, s[26:27]
	s_cbranch_vccz .LBB0_526
	s_barrier

.LBB0_617:
	ds_read_b128 v[146:149], v159
	ds_read_b128 v[150:153], v159 offset:1024
	ds_read_b128 v[164:167], v159 offset:2048
	ds_read_b128 v[168:171], v159 offset:3072
	ds_read_b128 v[172:175], v160
	ds_read_b128 v[176:179], v160 offset:1024
	ds_read_b128 v[180:183], v160 offset:2048
	ds_read_b128 v[184:187], v160 offset:3072
	s_add_u32 s58, s56, 0xfff80080
	s_addc_u32 s59, s57, -1
	s_cmp_eq_u32 s55, 28
	s_cselect_b32 s61, s35, s59
	s_cselect_b32 s60, s46, s58
	s_cselect_b32 s59, s31, s51
	s_cselect_b32 s58, s47, s50
	v_lshl_add_u64 v[154:155], s[56:57], 0, v[140:141]
	s_add_i32 m0, s45, 0xc000
	ds_read_b128 v[188:191], v161
	ds_read_b128 v[192:195], v161 offset:1024
	ds_read_b128 v[196:199], v161 offset:2048
	ds_read_b128 v[200:203], v161 offset:3072
	ds_read_b128 v[204:207], v161 offset:4096
	ds_read_b128 v[208:211], v161 offset:5120
	ds_read_b128 v[212:215], v161 offset:6144
	ds_read_b128 v[216:219], v161 offset:7168
	global_load_lds_dwordx4 v[154:155], off
	v_lshl_add_u64 v[154:155], s[56:57], 0, v[138:139]
	s_add_i32 m0, s45, 0xe000
	s_nop 0
	global_load_lds_dwordx4 v[154:155], off
	s_waitcnt vmcnt(8)
	s_waitcnt lgkmcnt(0)
	s_barrier
	s_setprio 1
	v_mfma_f32_16x16x32_bf16 v[124:127], v[146:149], v[188:191], v[124:127]
	v_mfma_f32_16x16x32_bf16 v[108:111], v[146:149], v[196:199], v[108:111]
	v_mfma_f32_16x16x32_bf16 v[92:95], v[146:149], v[204:207], v[92:95]
	v_mfma_f32_16x16x32_bf16 v[76:79], v[146:149], v[212:215], v[76:79]
	v_mfma_f32_16x16x32_bf16 v[72:75], v[164:167], v[212:215], v[72:75]
	v_mfma_f32_16x16x32_bf16 v[88:91], v[164:167], v[204:207], v[88:91]
	v_mfma_f32_16x16x32_bf16 v[104:107], v[164:167], v[196:199], v[104:107]
	v_mfma_f32_16x16x32_bf16 v[120:123], v[164:167], v[188:191], v[120:123]
	v_mfma_f32_16x16x32_bf16 v[124:127], v[150:153], v[192:195], v[124:127]
	v_mfma_f32_16x16x32_bf16 v[108:111], v[150:153], v[200:203], v[108:111]
	v_mfma_f32_16x16x32_bf16 v[92:95], v[150:153], v[208:211], v[92:95]
	v_mfma_f32_16x16x32_bf16 v[76:79], v[150:153], v[216:219], v[76:79]
	v_mfma_f32_16x16x32_bf16 v[72:75], v[168:171], v[216:219], v[72:75]
	v_mfma_f32_16x16x32_bf16 v[88:91], v[168:171], v[208:211], v[88:91]
	v_mfma_f32_16x16x32_bf16 v[104:107], v[168:171], v[200:203], v[104:107]
	v_mfma_f32_16x16x32_bf16 v[120:123], v[168:171], v[192:195], v[120:123]
	v_mfma_f32_16x16x32_bf16 v[116:119], v[172:175], v[188:191], v[116:119]
	v_mfma_f32_16x16x32_bf16 v[100:103], v[172:175], v[196:199], v[100:103]
	v_mfma_f32_16x16x32_bf16 v[84:87], v[172:175], v[204:207], v[84:87]
	v_mfma_f32_16x16x32_bf16 v[68:71], v[172:175], v[212:215], v[68:71]
	v_mfma_f32_16x16x32_bf16 v[64:67], v[180:183], v[212:215], v[64:67]
	v_mfma_f32_16x16x32_bf16 v[80:83], v[180:183], v[204:207], v[80:83]
	v_mfma_f32_16x16x32_bf16 v[96:99], v[180:183], v[196:199], v[96:99]
	v_mfma_f32_16x16x32_bf16 v[112:115], v[180:183], v[188:191], v[112:115]
	v_mfma_f32_16x16x32_bf16 v[116:119], v[176:179], v[192:195], v[116:119]
	v_mfma_f32_16x16x32_bf16 v[100:103], v[176:179], v[200:203], v[100:103]
	v_mfma_f32_16x16x32_bf16 v[84:87], v[176:179], v[208:211], v[84:87]
	v_mfma_f32_16x16x32_bf16 v[68:71], v[176:179], v[216:219], v[68:71]
	v_mfma_f32_16x16x32_bf16 v[64:67], v[184:187], v[216:219], v[64:67]
	v_mfma_f32_16x16x32_bf16 v[80:83], v[184:187], v[208:211], v[80:83]
	v_mfma_f32_16x16x32_bf16 v[96:99], v[184:187], v[200:203], v[96:99]
	v_mfma_f32_16x16x32_bf16 v[112:115], v[184:187], v[192:195], v[112:115]
	s_setprio 0
	s_barrier
	s_add_i32 s72, s66, s44
	v_lshl_add_u64 v[154:155], s[58:59], 0, v[130:131]
	s_mov_b32 m0, s72
	ds_read_b128 v[188:191], v161 offset:16384
	ds_read_b128 v[192:195], v161 offset:17408
	ds_read_b128 v[196:199], v161 offset:18432
	ds_read_b128 v[200:203], v161 offset:19456
	ds_read_b128 v[204:207], v161 offset:20480
	ds_read_b128 v[208:211], v161 offset:21504
	ds_read_b128 v[212:215], v161 offset:22528
	ds_read_b128 v[216:219], v161 offset:23552
	global_load_lds_dwordx4 v[154:155], off
	s_add_i32 m0, s72, 0x2000
	s_add_u32 s80, s58, 0x80000
	v_lshl_add_u64 v[220:221], s[58:59], 0, v[134:135]
	s_addc_u32 s81, s59, 0
	s_add_i32 s72, s67, s44
	global_load_lds_dwordx4 v[220:221], off
	v_lshl_add_u64 v[222:223], s[80:81], 0, v[130:131]
	s_mov_b32 m0, s72
	v_lshl_add_u64 v[224:225], s[60:61], 0, v[132:133]
	global_load_lds_dwordx4 v[222:223], off
	v_lshl_add_u64 v[222:223], s[80:81], 0, v[134:135]
	s_add_i32 m0, s72, 0x2000
	s_nop 0
	global_load_lds_dwordx4 v[222:223], off
	v_lshl_add_u64 v[222:223], s[60:61], 0, v[128:129]
	s_mov_b32 m0, s45
	s_nop 0
	global_load_lds_dwordx4 v[222:223], off
	s_mov_b32 m0, s48
	s_nop 0
	global_load_lds_dwordx4 v[224:225], off
	s_waitcnt vmcnt(8)
	s_waitcnt lgkmcnt(0)
	s_barrier
	s_setprio 1
	v_mfma_f32_16x16x32_bf16 v[60:63], v[146:149], v[188:191], v[60:63]
	v_mfma_f32_16x16x32_bf16 v[44:47], v[146:149], v[196:199], v[44:47]
	v_mfma_f32_16x16x32_bf16 v[28:31], v[146:149], v[204:207], v[28:31]
	v_mfma_f32_16x16x32_bf16 v[12:15], v[146:149], v[212:215], v[12:15]
	v_mfma_f32_16x16x32_bf16 v[8:11], v[164:167], v[212:215], v[8:11]
	v_mfma_f32_16x16x32_bf16 v[24:27], v[164:167], v[204:207], v[24:27]
	v_mfma_f32_16x16x32_bf16 v[40:43], v[164:167], v[196:199], v[40:43]
	v_mfma_f32_16x16x32_bf16 v[56:59], v[164:167], v[188:191], v[56:59]
	v_mfma_f32_16x16x32_bf16 v[60:63], v[150:153], v[192:195], v[60:63]
	v_mfma_f32_16x16x32_bf16 v[44:47], v[150:153], v[200:203], v[44:47]
	v_mfma_f32_16x16x32_bf16 v[28:31], v[150:153], v[208:211], v[28:31]
	v_mfma_f32_16x16x32_bf16 v[12:15], v[150:153], v[216:219], v[12:15]
	v_mfma_f32_16x16x32_bf16 v[8:11], v[168:171], v[216:219], v[8:11]
	v_mfma_f32_16x16x32_bf16 v[24:27], v[168:171], v[208:211], v[24:27]
	v_mfma_f32_16x16x32_bf16 v[40:43], v[168:171], v[200:203], v[40:43]
	v_mfma_f32_16x16x32_bf16 v[56:59], v[168:171], v[192:195], v[56:59]
	v_mfma_f32_16x16x32_bf16 v[52:55], v[172:175], v[188:191], v[52:55]
	v_mfma_f32_16x16x32_bf16 v[36:39], v[172:175], v[196:199], v[36:39]
	v_mfma_f32_16x16x32_bf16 v[20:23], v[172:175], v[204:207], v[20:23]
	v_mfma_f32_16x16x32_bf16 v[4:7], v[172:175], v[212:215], v[4:7]
	v_mfma_f32_16x16x32_bf16 v[0:3], v[180:183], v[212:215], v[0:3]
	v_mfma_f32_16x16x32_bf16 v[16:19], v[180:183], v[204:207], v[16:19]
	v_mfma_f32_16x16x32_bf16 v[32:35], v[180:183], v[196:199], v[32:35]
	v_mfma_f32_16x16x32_bf16 v[48:51], v[180:183], v[188:191], v[48:51]
	v_mfma_f32_16x16x32_bf16 v[52:55], v[176:179], v[192:195], v[52:55]
	v_mfma_f32_16x16x32_bf16 v[36:39], v[176:179], v[200:203], v[36:39]
	v_mfma_f32_16x16x32_bf16 v[20:23], v[176:179], v[208:211], v[20:23]
	v_mfma_f32_16x16x32_bf16 v[4:7], v[176:179], v[216:219], v[4:7]
	v_mfma_f32_16x16x32_bf16 v[0:3], v[184:187], v[216:219], v[0:3]
	v_mfma_f32_16x16x32_bf16 v[16:19], v[184:187], v[208:211], v[16:19]
	v_mfma_f32_16x16x32_bf16 v[32:35], v[184:187], v[200:203], v[32:35]
	v_mfma_f32_16x16x32_bf16 v[48:51], v[184:187], v[192:195], v[48:51]
	s_setprio 0
	s_barrier
	s_add_i32 s72, 0, 0x18000
	s_add_i32 s78, 0, 0x1c000
	v_add_u32_e32 v168, s72, v157
	v_add_u32_e32 v184, s78, v157
	ds_read_b128 v[146:149], v168
	ds_read_b128 v[150:153], v168 offset:1024
	ds_read_b128 v[164:167], v168 offset:2048
	ds_read_b128 v[168:171], v168 offset:3072
	ds_read_b128 v[172:175], v184
	ds_read_b128 v[176:179], v184 offset:1024
	ds_read_b128 v[180:183], v184 offset:2048
	ds_read_b128 v[184:187], v184 offset:3072
	s_add_u32 s60, s60, 0x80000
	s_addc_u32 s61, s61, 0
	s_mov_b32 m0, s49
	v_lshl_add_u64 v[226:227], s[60:61], 0, v[128:129]
	ds_read_b128 v[188:191], v161 offset:32768
	ds_read_b128 v[192:195], v161 offset:33792
	ds_read_b128 v[196:199], v161 offset:34816
	ds_read_b128 v[200:203], v161 offset:35840
	ds_read_b128 v[204:207], v161 offset:36864
	ds_read_b128 v[208:211], v161 offset:37888
	ds_read_b128 v[212:215], v161 offset:38912
	ds_read_b128 v[216:219], v161 offset:39936
	global_load_lds_dwordx4 v[226:227], off
	v_lshl_add_u64 v[226:227], s[60:61], 0, v[132:133]
	s_mov_b32 m0, s62
	s_nop 0
	global_load_lds_dwordx4 v[226:227], off
	s_waitcnt vmcnt(8)
	s_waitcnt lgkmcnt(0)
	s_barrier
	s_setprio 1
	v_mfma_f32_16x16x32_bf16 v[124:127], v[146:149], v[188:191], v[124:127]
	v_mfma_f32_16x16x32_bf16 v[108:111], v[146:149], v[196:199], v[108:111]
	v_mfma_f32_16x16x32_bf16 v[92:95], v[146:149], v[204:207], v[92:95]
	v_mfma_f32_16x16x32_bf16 v[76:79], v[146:149], v[212:215], v[76:79]
	v_mfma_f32_16x16x32_bf16 v[72:75], v[164:167], v[212:215], v[72:75]
	v_mfma_f32_16x16x32_bf16 v[88:91], v[164:167], v[204:207], v[88:91]
	v_mfma_f32_16x16x32_bf16 v[104:107], v[164:167], v[196:199], v[104:107]
	v_mfma_f32_16x16x32_bf16 v[120:123], v[164:167], v[188:191], v[120:123]
	v_mfma_f32_16x16x32_bf16 v[124:127], v[150:153], v[192:195], v[124:127]
	v_mfma_f32_16x16x32_bf16 v[108:111], v[150:153], v[200:203], v[108:111]
	v_mfma_f32_16x16x32_bf16 v[92:95], v[150:153], v[208:211], v[92:95]
	v_mfma_f32_16x16x32_bf16 v[76:79], v[150:153], v[216:219], v[76:79]
	v_mfma_f32_16x16x32_bf16 v[72:75], v[168:171], v[216:219], v[72:75]
	v_mfma_f32_16x16x32_bf16 v[88:91], v[168:171], v[208:211], v[88:91]
	v_mfma_f32_16x16x32_bf16 v[104:107], v[168:171], v[200:203], v[104:107]
	v_mfma_f32_16x16x32_bf16 v[120:123], v[168:171], v[192:195], v[120:123]
	v_mfma_f32_16x16x32_bf16 v[116:119], v[172:175], v[188:191], v[116:119]
	v_mfma_f32_16x16x32_bf16 v[100:103], v[172:175], v[196:199], v[100:103]
	v_mfma_f32_16x16x32_bf16 v[84:87], v[172:175], v[204:207], v[84:87]
	v_mfma_f32_16x16x32_bf16 v[68:71], v[172:175], v[212:215], v[68:71]
	v_mfma_f32_16x16x32_bf16 v[64:67], v[180:183], v[212:215], v[64:67]
	v_mfma_f32_16x16x32_bf16 v[80:83], v[180:183], v[204:207], v[80:83]
	v_mfma_f32_16x16x32_bf16 v[96:99], v[180:183], v[196:199], v[96:99]
	v_mfma_f32_16x16x32_bf16 v[112:115], v[180:183], v[188:191], v[112:115]
	v_mfma_f32_16x16x32_bf16 v[116:119], v[176:179], v[192:195], v[116:119]
	v_mfma_f32_16x16x32_bf16 v[100:103], v[176:179], v[200:203], v[100:103]
	v_mfma_f32_16x16x32_bf16 v[84:87], v[176:179], v[208:211], v[84:87]
	v_mfma_f32_16x16x32_bf16 v[68:71], v[176:179], v[216:219], v[68:71]
	v_mfma_f32_16x16x32_bf16 v[64:67], v[184:187], v[216:219], v[64:67]
	v_mfma_f32_16x16x32_bf16 v[80:83], v[184:187], v[208:211], v[80:83]
	v_mfma_f32_16x16x32_bf16 v[96:99], v[184:187], v[200:203], v[96:99]
	v_mfma_f32_16x16x32_bf16 v[112:115], v[184:187], v[192:195], v[112:115]
	s_setprio 0
	s_barrier
	s_add_i32 s60, s72, s44
	v_lshl_add_u64 v[154:155], v[154:155], 0, s[24:25]
	s_mov_b32 m0, s60
	ds_read_b128 v[188:191], v161 offset:49152
	ds_read_b128 v[192:195], v161 offset:50176
	ds_read_b128 v[196:199], v161 offset:51200
	ds_read_b128 v[200:203], v161 offset:52224
	ds_read_b128 v[204:207], v161 offset:53248
	ds_read_b128 v[208:211], v161 offset:54272
	ds_read_b128 v[212:215], v161 offset:55296
	ds_read_b128 v[216:219], v161 offset:56320
	global_load_lds_dwordx4 v[154:155], off
	s_add_i32 m0, s60, 0x2000
	s_add_u32 s58, s58, 0x80080
	v_lshl_add_u64 v[154:155], v[220:221], 0, s[24:25]
	s_addc_u32 s59, s59, 0
	s_add_i32 s60, s78, s44
	global_load_lds_dwordx4 v[154:155], off
	v_lshl_add_u64 v[154:155], s[58:59], 0, v[130:131]
	s_mov_b32 m0, s60
	s_nop 0
	global_load_lds_dwordx4 v[154:155], off
	v_lshl_add_u64 v[154:155], s[58:59], 0, v[134:135]
	s_add_i32 m0, s60, 0x2000
	s_nop 0
	global_load_lds_dwordx4 v[154:155], off
	v_lshl_add_u64 v[154:155], v[222:223], 0, s[24:25]
	s_mov_b32 m0, s64
	s_nop 0
	global_load_lds_dwordx4 v[154:155], off
	v_lshl_add_u64 v[154:155], v[224:225], 0, s[24:25]
	s_mov_b32 m0, s65
	s_nop 0
	global_load_lds_dwordx4 v[154:155], off
	s_waitcnt vmcnt(8)
	s_waitcnt lgkmcnt(0)
	s_barrier
	s_setprio 1
	v_mfma_f32_16x16x32_bf16 v[60:63], v[146:149], v[188:191], v[60:63]
	v_mfma_f32_16x16x32_bf16 v[44:47], v[146:149], v[196:199], v[44:47]
	v_mfma_f32_16x16x32_bf16 v[28:31], v[146:149], v[204:207], v[28:31]
	v_mfma_f32_16x16x32_bf16 v[12:15], v[146:149], v[212:215], v[12:15]
	v_mfma_f32_16x16x32_bf16 v[8:11], v[164:167], v[212:215], v[8:11]
	v_mfma_f32_16x16x32_bf16 v[24:27], v[164:167], v[204:207], v[24:27]
	v_mfma_f32_16x16x32_bf16 v[40:43], v[164:167], v[196:199], v[40:43]
	v_mfma_f32_16x16x32_bf16 v[56:59], v[164:167], v[188:191], v[56:59]
	v_mfma_f32_16x16x32_bf16 v[60:63], v[150:153], v[192:195], v[60:63]
	v_mfma_f32_16x16x32_bf16 v[44:47], v[150:153], v[200:203], v[44:47]
	v_mfma_f32_16x16x32_bf16 v[28:31], v[150:153], v[208:211], v[28:31]
	v_mfma_f32_16x16x32_bf16 v[12:15], v[150:153], v[216:219], v[12:15]
	v_mfma_f32_16x16x32_bf16 v[8:11], v[168:171], v[216:219], v[8:11]
	v_mfma_f32_16x16x32_bf16 v[24:27], v[168:171], v[208:211], v[24:27]
	v_mfma_f32_16x16x32_bf16 v[40:43], v[168:171], v[200:203], v[40:43]
	v_mfma_f32_16x16x32_bf16 v[56:59], v[168:171], v[192:195], v[56:59]
	v_mfma_f32_16x16x32_bf16 v[52:55], v[172:175], v[188:191], v[52:55]
	v_mfma_f32_16x16x32_bf16 v[36:39], v[172:175], v[196:199], v[36:39]
	v_mfma_f32_16x16x32_bf16 v[20:23], v[172:175], v[204:207], v[20:23]
	v_mfma_f32_16x16x32_bf16 v[4:7], v[172:175], v[212:215], v[4:7]
	v_mfma_f32_16x16x32_bf16 v[0:3], v[180:183], v[212:215], v[0:3]
	v_mfma_f32_16x16x32_bf16 v[16:19], v[180:183], v[204:207], v[16:19]
	v_mfma_f32_16x16x32_bf16 v[32:35], v[180:183], v[196:199], v[32:35]
	v_mfma_f32_16x16x32_bf16 v[48:51], v[180:183], v[188:191], v[48:51]
	v_mfma_f32_16x16x32_bf16 v[52:55], v[176:179], v[192:195], v[52:55]
	v_mfma_f32_16x16x32_bf16 v[36:39], v[176:179], v[200:203], v[36:39]
	v_mfma_f32_16x16x32_bf16 v[20:23], v[176:179], v[208:211], v[20:23]
	v_mfma_f32_16x16x32_bf16 v[4:7], v[176:179], v[216:219], v[4:7]
	v_mfma_f32_16x16x32_bf16 v[0:3], v[184:187], v[216:219], v[0:3]
	v_mfma_f32_16x16x32_bf16 v[16:19], v[184:187], v[208:211], v[16:19]
	v_mfma_f32_16x16x32_bf16 v[32:35], v[184:187], v[200:203], v[32:35]
	v_mfma_f32_16x16x32_bf16 v[48:51], v[184:187], v[192:195], v[48:51]
	s_setprio 0
	s_barrier
	s_add_i32 s55, s55, 2
	s_add_u32 s50, s50, 0x100
	s_addc_u32 s51, s51, 0
	s_add_u32 s56, s56, 0x100
	s_addc_u32 s57, s57, 0
	s_cmp_gt_u32 s55, 29
	s_cbranch_scc0 .LBB0_617
	s_and_b64 vcc, exec, s[26:27]
	s_cbranch_vccz .LBB0_620
	s_barrier

.LBB0_708:
	ds_read_b128 v[0:3], v145
	ds_read_b128 v[4:7], v145 offset:1024
	ds_read_b128 v[8:11], v145 offset:2048
	ds_read_b128 v[12:15], v145 offset:3072
	ds_read_b128 v[16:19], v146
	ds_read_b128 v[20:23], v146 offset:1024
	ds_read_b128 v[24:27], v146 offset:2048
	ds_read_b128 v[28:31], v146 offset:3072
	s_ashr_i32 s37, s36, 31
	s_lshl_b64 s[52:53], s[36:37], 17
	s_add_u32 s52, s6, s52
	s_addc_u32 s53, s7, s53
	s_and_b64 s[54:55], s[8:9], exec
	s_cselect_b32 s65, s53, s59
	s_cselect_b32 s64, s52, s58
	s_ashr_i32 s35, s34, 31
	s_lshl_b64 s[54:55], s[34:35], 17
	s_add_u32 s54, s44, s54
	s_addc_u32 s55, s45, s55
	s_and_b64 s[62:63], s[8:9], exec
	s_cselect_b32 s63, s55, s61
	s_cselect_b32 s62, s54, s60
	s_add_u32 s86, s58, 0x10080
	s_addc_u32 s87, s59, 0
	s_mov_b32 m0, s72
	v_lshl_add_u64 v[64:65], s[86:87], 0, v[128:129]
	ds_read_b128 v[32:35], v147
	ds_read_b128 v[36:39], v147 offset:1024
	ds_read_b128 v[40:43], v147 offset:2048
	ds_read_b128 v[44:47], v147 offset:3072
	ds_read_b128 v[48:51], v147 offset:4096
	ds_read_b128 v[52:55], v147 offset:5120
	ds_read_b128 v[56:59], v147 offset:6144
	ds_read_b128 v[60:63], v147 offset:7168
	global_load_lds_dwordx4 v[64:65], off
	v_lshl_add_u64 v[64:65], s[86:87], 0, v[132:133]
	s_mov_b32 m0, s80
	s_nop 0
	global_load_lds_dwordx4 v[64:65], off
	s_waitcnt vmcnt(8)
	s_waitcnt lgkmcnt(0)
	s_barrier
	s_setprio 1
	v_mfma_f32_16x16x32_bf16 v[64:67], v[0:3], v[32:35], 0
	v_mfma_f32_16x16x32_bf16 v[68:71], v[8:11], v[32:35], 0
	v_mfma_f32_16x16x32_bf16 v[72:75], v[0:3], v[40:43], 0
	v_mfma_f32_16x16x32_bf16 v[76:79], v[8:11], v[40:43], 0
	v_mfma_f32_16x16x32_bf16 v[80:83], v[0:3], v[48:51], 0
	v_mfma_f32_16x16x32_bf16 v[84:87], v[8:11], v[48:51], 0
	v_mfma_f32_16x16x32_bf16 v[88:91], v[0:3], v[56:59], 0
	v_mfma_f32_16x16x32_bf16 v[92:95], v[8:11], v[56:59], 0
	v_mfma_f32_16x16x32_bf16 v[64:67], v[4:7], v[36:39], v[64:67]
	v_mfma_f32_16x16x32_bf16 v[68:71], v[12:15], v[36:39], v[68:71]
	v_mfma_f32_16x16x32_bf16 v[72:75], v[4:7], v[44:47], v[72:75]
	v_mfma_f32_16x16x32_bf16 v[76:79], v[12:15], v[44:47], v[76:79]
	v_mfma_f32_16x16x32_bf16 v[80:83], v[4:7], v[52:55], v[80:83]
	v_mfma_f32_16x16x32_bf16 v[84:87], v[12:15], v[52:55], v[84:87]
	v_mfma_f32_16x16x32_bf16 v[88:91], v[4:7], v[60:63], v[88:91]
	v_mfma_f32_16x16x32_bf16 v[92:95], v[12:15], v[60:63], v[92:95]
	v_mfma_f32_16x16x32_bf16 v[96:99], v[16:19], v[32:35], 0
	v_mfma_f32_16x16x32_bf16 v[32:35], v[24:27], v[32:35], 0
	v_mfma_f32_16x16x32_bf16 v[96:99], v[20:23], v[36:39], v[96:99]
	v_mfma_f32_16x16x32_bf16 v[32:35], v[28:31], v[36:39], v[32:35]
	v_mfma_f32_16x16x32_bf16 v[36:39], v[16:19], v[40:43], 0
	v_mfma_f32_16x16x32_bf16 v[40:43], v[24:27], v[40:43], 0
	v_mfma_f32_16x16x32_bf16 v[36:39], v[20:23], v[44:47], v[36:39]
	v_mfma_f32_16x16x32_bf16 v[40:43], v[28:31], v[44:47], v[40:43]
	v_mfma_f32_16x16x32_bf16 v[44:47], v[16:19], v[48:51], 0
	v_mfma_f32_16x16x32_bf16 v[48:51], v[24:27], v[48:51], 0
	v_mfma_f32_16x16x32_bf16 v[44:47], v[20:23], v[52:55], v[44:47]
	v_mfma_f32_16x16x32_bf16 v[48:51], v[28:31], v[52:55], v[48:51]
	v_mfma_f32_16x16x32_bf16 v[52:55], v[16:19], v[56:59], 0
	v_mfma_f32_16x16x32_bf16 v[56:59], v[24:27], v[56:59], 0
	v_mfma_f32_16x16x32_bf16 v[52:55], v[20:23], v[60:63], v[52:55]
	v_mfma_f32_16x16x32_bf16 v[56:59], v[28:31], v[60:63], v[56:59]
	s_setprio 0
	s_barrier
	s_add_i32 s85, s70, s48
	v_lshl_add_u64 v[140:141], s[60:61], 0, v[130:131]
	s_add_i32 s35, s85, 0x2000
	v_lshl_add_u64 v[148:149], v[140:141], 0, s[20:21]
	s_mov_b32 m0, s85
	v_lshl_add_u64 v[212:213], s[60:61], 0, v[134:135]
	s_add_u32 s86, s60, 0x10100
	ds_read_b128 v[60:63], v147 offset:16384
	ds_read_b128 v[100:103], v147 offset:17408
	ds_read_b128 v[104:107], v147 offset:18432
	ds_read_b128 v[108:111], v147 offset:19456
	ds_read_b128 v[112:115], v147 offset:20480
	ds_read_b128 v[116:119], v147 offset:21504
	ds_read_b128 v[120:123], v147 offset:22528
	ds_read_b128 v[124:127], v147 offset:23552
	global_load_lds_dwordx4 v[148:149], off
	v_lshl_add_u64 v[148:149], v[212:213], 0, s[20:21]
	s_mov_b32 m0, s35
	s_addc_u32 s87, s61, 0
	s_add_i32 s37, s71, s48
	global_load_lds_dwordx4 v[148:149], off
	v_lshl_add_u64 v[148:149], s[86:87], 0, v[130:131]
	s_mov_b32 m0, s37
	s_add_i32 s47, s37, 0x2000
	global_load_lds_dwordx4 v[148:149], off
	v_lshl_add_u64 v[148:149], s[86:87], 0, v[134:135]
	s_mov_b32 m0, s47
	v_lshl_add_u64 v[214:215], s[58:59], 0, v[128:129]
	global_load_lds_dwordx4 v[148:149], off
	v_lshl_add_u64 v[148:149], v[214:215], 0, s[20:21]
	s_mov_b32 m0, s49
	v_lshl_add_u64 v[216:217], s[58:59], 0, v[132:133]
	global_load_lds_dwordx4 v[148:149], off
	v_lshl_add_u64 v[148:149], v[216:217], 0, s[20:21]
	s_mov_b32 m0, s50
	s_nop 0
	global_load_lds_dwordx4 v[148:149], off
	s_waitcnt vmcnt(8)
	s_waitcnt lgkmcnt(0)
	s_barrier
	s_setprio 1
	v_mfma_f32_16x16x32_bf16 v[148:151], v[0:3], v[60:63], 0
	v_mfma_f32_16x16x32_bf16 v[156:159], v[0:3], v[104:107], 0
	v_mfma_f32_16x16x32_bf16 v[164:167], v[0:3], v[112:115], 0
	v_mfma_f32_16x16x32_bf16 v[0:3], v[0:3], v[120:123], 0
	v_mfma_f32_16x16x32_bf16 v[148:151], v[4:7], v[100:103], v[148:151]
	v_mfma_f32_16x16x32_bf16 v[156:159], v[4:7], v[108:111], v[156:159]
	v_mfma_f32_16x16x32_bf16 v[164:167], v[4:7], v[116:119], v[164:167]
	v_mfma_f32_16x16x32_bf16 v[0:3], v[4:7], v[124:127], v[0:3]
	v_mfma_f32_16x16x32_bf16 v[4:7], v[8:11], v[120:123], 0
	v_mfma_f32_16x16x32_bf16 v[152:155], v[8:11], v[60:63], 0
	v_mfma_f32_16x16x32_bf16 v[160:163], v[8:11], v[104:107], 0
	v_mfma_f32_16x16x32_bf16 v[168:171], v[8:11], v[112:115], 0
	v_mfma_f32_16x16x32_bf16 v[4:7], v[12:15], v[124:127], v[4:7]
	v_mfma_f32_16x16x32_bf16 v[152:155], v[12:15], v[100:103], v[152:155]
	v_mfma_f32_16x16x32_bf16 v[160:163], v[12:15], v[108:111], v[160:163]
	v_mfma_f32_16x16x32_bf16 v[168:171], v[12:15], v[116:119], v[168:171]
	v_mfma_f32_16x16x32_bf16 v[8:11], v[16:19], v[60:63], 0
	v_mfma_f32_16x16x32_bf16 v[12:15], v[24:27], v[60:63], 0
	v_mfma_f32_16x16x32_bf16 v[8:11], v[20:23], v[100:103], v[8:11]
	v_mfma_f32_16x16x32_bf16 v[12:15], v[28:31], v[100:103], v[12:15]
	v_mfma_f32_16x16x32_bf16 v[60:63], v[16:19], v[104:107], 0
	v_mfma_f32_16x16x32_bf16 v[100:103], v[24:27], v[104:107], 0
	v_mfma_f32_16x16x32_bf16 v[104:107], v[16:19], v[112:115], 0
	v_mfma_f32_16x16x32_bf16 v[16:19], v[16:19], v[120:123], 0
	v_mfma_f32_16x16x32_bf16 v[60:63], v[20:23], v[108:111], v[60:63]
	v_mfma_f32_16x16x32_bf16 v[100:103], v[28:31], v[108:111], v[100:103]
	v_mfma_f32_16x16x32_bf16 v[104:107], v[20:23], v[116:119], v[104:107]
	v_mfma_f32_16x16x32_bf16 v[108:111], v[24:27], v[112:115], 0
	v_mfma_f32_16x16x32_bf16 v[16:19], v[20:23], v[124:127], v[16:19]
	v_mfma_f32_16x16x32_bf16 v[20:23], v[24:27], v[120:123], 0
	v_mfma_f32_16x16x32_bf16 v[108:111], v[28:31], v[116:119], v[108:111]
	v_mfma_f32_16x16x32_bf16 v[20:23], v[28:31], v[124:127], v[20:23]
	s_setprio 0
	s_barrier
	s_add_i32 s78, 0, 0x18000
	s_add_i32 s79, 0, 0x1c000
	v_add_u32_e32 v224, s78, v143
	v_add_u32_e32 v232, s79, v143
	ds_read_b128 v[24:27], v224
	ds_read_b128 v[28:31], v224 offset:1024
	ds_read_b128 v[112:115], v224 offset:2048
	ds_read_b128 v[116:119], v224 offset:3072
	ds_read_b128 v[120:123], v232
	ds_read_b128 v[124:127], v232 offset:1024
	ds_read_b128 v[172:175], v232 offset:2048
	ds_read_b128 v[176:179], v232 offset:3072
	s_add_u32 s86, s58, 0x10100
	s_addc_u32 s87, s59, 0
	s_mov_b32 m0, s51
	v_lshl_add_u64 v[218:219], s[86:87], 0, v[128:129]
	ds_read_b128 v[180:183], v147 offset:32768
	ds_read_b128 v[184:187], v147 offset:33792
	ds_read_b128 v[188:191], v147 offset:34816
	ds_read_b128 v[192:195], v147 offset:35840
	ds_read_b128 v[196:199], v147 offset:36864
	ds_read_b128 v[200:203], v147 offset:37888
	ds_read_b128 v[204:207], v147 offset:38912
	ds_read_b128 v[208:211], v147 offset:39936
	global_load_lds_dwordx4 v[218:219], off
	v_lshl_add_u64 v[218:219], s[86:87], 0, v[132:133]
	s_mov_b32 m0, s57
	s_nop 0
	global_load_lds_dwordx4 v[218:219], off
	s_waitcnt vmcnt(8)
	s_waitcnt lgkmcnt(0)
	s_barrier
	s_setprio 1
	v_mfma_f32_16x16x32_bf16 v[64:67], v[24:27], v[180:183], v[64:67]
	v_mfma_f32_16x16x32_bf16 v[72:75], v[24:27], v[188:191], v[72:75]
	v_mfma_f32_16x16x32_bf16 v[80:83], v[24:27], v[196:199], v[80:83]
	v_mfma_f32_16x16x32_bf16 v[88:91], v[24:27], v[204:207], v[88:91]
	v_mfma_f32_16x16x32_bf16 v[92:95], v[112:115], v[204:207], v[92:95]
	v_mfma_f32_16x16x32_bf16 v[84:87], v[112:115], v[196:199], v[84:87]
	v_mfma_f32_16x16x32_bf16 v[76:79], v[112:115], v[188:191], v[76:79]
	v_mfma_f32_16x16x32_bf16 v[68:71], v[112:115], v[180:183], v[68:71]
	v_mfma_f32_16x16x32_bf16 v[64:67], v[28:31], v[184:187], v[64:67]
	v_mfma_f32_16x16x32_bf16 v[72:75], v[28:31], v[192:195], v[72:75]
	v_mfma_f32_16x16x32_bf16 v[80:83], v[28:31], v[200:203], v[80:83]
	v_mfma_f32_16x16x32_bf16 v[88:91], v[28:31], v[208:211], v[88:91]
	v_mfma_f32_16x16x32_bf16 v[92:95], v[116:119], v[208:211], v[92:95]
	v_mfma_f32_16x16x32_bf16 v[84:87], v[116:119], v[200:203], v[84:87]
	v_mfma_f32_16x16x32_bf16 v[76:79], v[116:119], v[192:195], v[76:79]
	v_mfma_f32_16x16x32_bf16 v[68:71], v[116:119], v[184:187], v[68:71]
	v_mfma_f32_16x16x32_bf16 v[96:99], v[120:123], v[180:183], v[96:99]
	v_mfma_f32_16x16x32_bf16 v[36:39], v[120:123], v[188:191], v[36:39]
	v_mfma_f32_16x16x32_bf16 v[44:47], v[120:123], v[196:199], v[44:47]
	v_mfma_f32_16x16x32_bf16 v[52:55], v[120:123], v[204:207], v[52:55]
	v_mfma_f32_16x16x32_bf16 v[56:59], v[172:175], v[204:207], v[56:59]
	v_mfma_f32_16x16x32_bf16 v[48:51], v[172:175], v[196:199], v[48:51]
	v_mfma_f32_16x16x32_bf16 v[40:43], v[172:175], v[188:191], v[40:43]
	v_mfma_f32_16x16x32_bf16 v[32:35], v[172:175], v[180:183], v[32:35]
	v_mfma_f32_16x16x32_bf16 v[96:99], v[124:127], v[184:187], v[96:99]
	v_mfma_f32_16x16x32_bf16 v[36:39], v[124:127], v[192:195], v[36:39]
	v_mfma_f32_16x16x32_bf16 v[44:47], v[124:127], v[200:203], v[44:47]
	v_mfma_f32_16x16x32_bf16 v[52:55], v[124:127], v[208:211], v[52:55]
	v_mfma_f32_16x16x32_bf16 v[56:59], v[176:179], v[208:211], v[56:59]
	v_mfma_f32_16x16x32_bf16 v[48:51], v[176:179], v[200:203], v[48:51]
	v_mfma_f32_16x16x32_bf16 v[40:43], v[176:179], v[192:195], v[40:43]
	v_mfma_f32_16x16x32_bf16 v[32:35], v[176:179], v[184:187], v[32:35]
	s_setprio 0
	s_barrier
	s_add_i32 s87, s78, s48
	s_add_i32 s86, s87, 0x2000
	v_lshl_add_u64 v[140:141], v[140:141], 0, s[22:23]
	s_mov_b32 m0, s87
	s_add_u32 s88, s60, 0x10180
	ds_read_b128 v[180:183], v147 offset:49152
	ds_read_b128 v[184:187], v147 offset:50176
	ds_read_b128 v[188:191], v147 offset:51200
	ds_read_b128 v[192:195], v147 offset:52224
	ds_read_b128 v[196:199], v147 offset:53248
	ds_read_b128 v[200:203], v147 offset:54272
	ds_read_b128 v[204:207], v147 offset:55296
	ds_read_b128 v[208:211], v147 offset:56320
	global_load_lds_dwordx4 v[140:141], off
	v_lshl_add_u64 v[140:141], v[212:213], 0, s[22:23]
	s_mov_b32 m0, s86
	s_addc_u32 s89, s61, 0
	s_add_i32 s60, s79, s48
	global_load_lds_dwordx4 v[140:141], off
	v_lshl_add_u64 v[140:141], s[88:89], 0, v[130:131]
	s_mov_b32 m0, s60
	s_add_i32 s61, s60, 0x2000
	global_load_lds_dwordx4 v[140:141], off
	v_lshl_add_u64 v[140:141], s[88:89], 0, v[134:135]
	s_mov_b32 m0, s61
	s_nop 0
	global_load_lds_dwordx4 v[140:141], off
	v_lshl_add_u64 v[140:141], v[214:215], 0, s[22:23]
	s_mov_b32 m0, s66
	s_nop 0
	global_load_lds_dwordx4 v[140:141], off
	v_lshl_add_u64 v[140:141], v[216:217], 0, s[22:23]
	s_mov_b32 m0, s67
	s_nop 0
	global_load_lds_dwordx4 v[140:141], off
	s_waitcnt vmcnt(8)
	s_waitcnt lgkmcnt(0)
	s_barrier
	s_setprio 1
	v_mfma_f32_16x16x32_bf16 v[0:3], v[24:27], v[204:207], v[0:3]
	v_mfma_f32_16x16x32_bf16 v[148:151], v[24:27], v[180:183], v[148:151]
	v_mfma_f32_16x16x32_bf16 v[156:159], v[24:27], v[188:191], v[156:159]
	v_mfma_f32_16x16x32_bf16 v[164:167], v[24:27], v[196:199], v[164:167]
	v_mfma_f32_16x16x32_bf16 v[168:171], v[112:115], v[196:199], v[168:171]
	v_mfma_f32_16x16x32_bf16 v[160:163], v[112:115], v[188:191], v[160:163]
	v_mfma_f32_16x16x32_bf16 v[152:155], v[112:115], v[180:183], v[152:155]
	v_mfma_f32_16x16x32_bf16 v[4:7], v[112:115], v[204:207], v[4:7]
	v_mfma_f32_16x16x32_bf16 v[0:3], v[28:31], v[208:211], v[0:3]
	v_mfma_f32_16x16x32_bf16 v[148:151], v[28:31], v[184:187], v[148:151]
	v_mfma_f32_16x16x32_bf16 v[156:159], v[28:31], v[192:195], v[156:159]
	v_mfma_f32_16x16x32_bf16 v[164:167], v[28:31], v[200:203], v[164:167]
	v_mfma_f32_16x16x32_bf16 v[168:171], v[116:119], v[200:203], v[168:171]
	v_mfma_f32_16x16x32_bf16 v[160:163], v[116:119], v[192:195], v[160:163]
	v_mfma_f32_16x16x32_bf16 v[152:155], v[116:119], v[184:187], v[152:155]
	v_mfma_f32_16x16x32_bf16 v[4:7], v[116:119], v[208:211], v[4:7]
	v_mfma_f32_16x16x32_bf16 v[8:11], v[120:123], v[180:183], v[8:11]
	v_mfma_f32_16x16x32_bf16 v[12:15], v[172:175], v[180:183], v[12:15]
	v_mfma_f32_16x16x32_bf16 v[24:27], v[120:123], v[188:191], v[60:63]
	v_mfma_f32_16x16x32_bf16 v[28:31], v[172:175], v[188:191], v[100:103]
	v_mfma_f32_16x16x32_bf16 v[60:63], v[120:123], v[196:199], v[104:107]
	v_mfma_f32_16x16x32_bf16 v[100:103], v[172:175], v[196:199], v[108:111]
	v_mfma_f32_16x16x32_bf16 v[16:19], v[120:123], v[204:207], v[16:19]
	v_mfma_f32_16x16x32_bf16 v[20:23], v[172:175], v[204:207], v[20:23]
	v_mfma_f32_16x16x32_bf16 v[8:11], v[124:127], v[184:187], v[8:11]
	v_mfma_f32_16x16x32_bf16 v[12:15], v[176:179], v[184:187], v[12:15]
	v_mfma_f32_16x16x32_bf16 v[24:27], v[124:127], v[192:195], v[24:27]
	v_mfma_f32_16x16x32_bf16 v[28:31], v[176:179], v[192:195], v[28:31]
	v_mfma_f32_16x16x32_bf16 v[60:63], v[124:127], v[200:203], v[60:63]
	v_mfma_f32_16x16x32_bf16 v[100:103], v[176:179], v[200:203], v[100:103]
	v_mfma_f32_16x16x32_bf16 v[16:19], v[124:127], v[208:211], v[16:19]
	v_mfma_f32_16x16x32_bf16 v[20:23], v[176:179], v[208:211], v[20:23]
	s_setprio 0
	s_barrier
	ds_read_b128 v[104:107], v145
	ds_read_b128 v[108:111], v145 offset:1024
	ds_read_b128 v[112:115], v145 offset:2048
	ds_read_b128 v[116:119], v145 offset:3072
	ds_read_b128 v[120:123], v146
	ds_read_b128 v[124:127], v146 offset:1024
	ds_read_b128 v[172:175], v146 offset:2048
	ds_read_b128 v[176:179], v146 offset:3072
	s_add_u32 s58, s58, 0x10180
	s_addc_u32 s59, s59, 0
	s_mov_b32 m0, s72
	v_lshl_add_u64 v[140:141], s[58:59], 0, v[128:129]
	ds_read_b128 v[180:183], v147
	ds_read_b128 v[184:187], v147 offset:1024
	ds_read_b128 v[188:191], v147 offset:2048
	ds_read_b128 v[192:195], v147 offset:3072
	ds_read_b128 v[196:199], v147 offset:4096
	ds_read_b128 v[200:203], v147 offset:5120
	ds_read_b128 v[204:207], v147 offset:6144
	ds_read_b128 v[208:211], v147 offset:7168
	global_load_lds_dwordx4 v[140:141], off
	v_lshl_add_u64 v[140:141], s[58:59], 0, v[132:133]
	s_mov_b32 m0, s80
	s_nop 0
	global_load_lds_dwordx4 v[140:141], off
	s_waitcnt vmcnt(8)
	s_waitcnt lgkmcnt(0)
	s_barrier
	s_setprio 1
	v_mfma_f32_16x16x32_bf16 v[88:91], v[104:107], v[204:207], v[88:91]
	v_mfma_f32_16x16x32_bf16 v[64:67], v[104:107], v[180:183], v[64:67]
	v_mfma_f32_16x16x32_bf16 v[68:71], v[112:115], v[180:183], v[68:71]
	v_mfma_f32_16x16x32_bf16 v[72:75], v[104:107], v[188:191], v[72:75]
	v_mfma_f32_16x16x32_bf16 v[76:79], v[112:115], v[188:191], v[76:79]
	v_mfma_f32_16x16x32_bf16 v[80:83], v[104:107], v[196:199], v[80:83]
	v_mfma_f32_16x16x32_bf16 v[84:87], v[112:115], v[196:199], v[84:87]
	v_mfma_f32_16x16x32_bf16 v[212:215], v[108:111], v[208:211], v[88:91]
	v_mfma_f32_16x16x32_bf16 v[88:91], v[112:115], v[204:207], v[92:95]
	v_mfma_f32_16x16x32_bf16 v[64:67], v[108:111], v[184:187], v[64:67]
	v_mfma_f32_16x16x32_bf16 v[68:71], v[116:119], v[184:187], v[68:71]
	v_mfma_f32_16x16x32_bf16 v[72:75], v[108:111], v[192:195], v[72:75]
	v_mfma_f32_16x16x32_bf16 v[76:79], v[116:119], v[192:195], v[76:79]
	v_mfma_f32_16x16x32_bf16 v[80:83], v[108:111], v[200:203], v[80:83]
	v_mfma_f32_16x16x32_bf16 v[84:87], v[116:119], v[200:203], v[84:87]
	v_mfma_f32_16x16x32_bf16 v[92:95], v[116:119], v[208:211], v[88:91]
	v_mfma_f32_16x16x32_bf16 v[48:51], v[172:175], v[196:199], v[48:51]
	v_mfma_f32_16x16x32_bf16 v[88:91], v[120:123], v[180:183], v[96:99]
	v_mfma_f32_16x16x32_bf16 v[32:35], v[172:175], v[180:183], v[32:35]
	v_mfma_f32_16x16x32_bf16 v[36:39], v[120:123], v[188:191], v[36:39]
	v_mfma_f32_16x16x32_bf16 v[40:43], v[172:175], v[188:191], v[40:43]
	v_mfma_f32_16x16x32_bf16 v[44:47], v[120:123], v[196:199], v[44:47]
	v_mfma_f32_16x16x32_bf16 v[180:183], v[176:179], v[200:203], v[48:51]
	v_mfma_f32_16x16x32_bf16 v[48:51], v[120:123], v[204:207], v[52:55]
	v_mfma_f32_16x16x32_bf16 v[32:35], v[176:179], v[184:187], v[32:35]
	v_mfma_f32_16x16x32_bf16 v[36:39], v[124:127], v[192:195], v[36:39]
	v_mfma_f32_16x16x32_bf16 v[40:43], v[176:179], v[192:195], v[40:43]
	v_mfma_f32_16x16x32_bf16 v[44:47], v[124:127], v[200:203], v[44:47]
	v_mfma_f32_16x16x32_bf16 v[52:55], v[124:127], v[208:211], v[48:51]
	v_mfma_f32_16x16x32_bf16 v[48:51], v[172:175], v[204:207], v[56:59]
	v_mfma_f32_16x16x32_bf16 v[216:219], v[124:127], v[184:187], v[88:91]
	v_mfma_f32_16x16x32_bf16 v[184:187], v[176:179], v[208:211], v[48:51]
	s_setprio 0
	s_barrier
	s_mov_b32 m0, s85
	v_lshl_add_u64 v[140:141], s[62:63], 0, v[130:131]
	s_add_u32 s58, s62, 0x10000
	s_nop 0
	ds_read_b128 v[48:51], v147 offset:16384
	ds_read_b128 v[56:59], v147 offset:17408
	ds_read_b128 v[88:91], v147 offset:18432
	ds_read_b128 v[96:99], v147 offset:19456
	ds_read_b128 v[188:191], v147 offset:20480
	ds_read_b128 v[192:195], v147 offset:21504
	ds_read_b128 v[196:199], v147 offset:22528
	ds_read_b128 v[200:203], v147 offset:23552
	global_load_lds_dwordx4 v[140:141], off
	v_lshl_add_u64 v[252:253], s[62:63], 0, v[134:135]
	s_mov_b32 m0, s35
	s_addc_u32 s59, s63, 0
	global_load_lds_dwordx4 v[252:253], off
	v_lshl_add_u64 v[204:205], s[58:59], 0, v[130:131]
	s_mov_b32 m0, s37
	v_lshl_add_u64 v[136:137], s[64:65], 0, v[128:129]
	global_load_lds_dwordx4 v[204:205], off
	v_lshl_add_u64 v[204:205], s[58:59], 0, v[134:135]
	s_mov_b32 m0, s47
	v_lshl_add_u64 v[138:139], s[64:65], 0, v[132:133]
	global_load_lds_dwordx4 v[204:205], off
	s_mov_b32 m0, s49
	s_nop 0
	global_load_lds_dwordx4 v[136:137], off
	s_mov_b32 m0, s50
	s_nop 0
	global_load_lds_dwordx4 v[138:139], off
	s_waitcnt vmcnt(8)
	s_waitcnt lgkmcnt(0)
	s_barrier
	s_setprio 1
	v_mfma_f32_16x16x32_bf16 v[0:3], v[104:107], v[196:199], v[0:3]
	v_mfma_f32_16x16x32_bf16 v[148:151], v[104:107], v[48:51], v[148:151]
	v_mfma_f32_16x16x32_bf16 v[156:159], v[104:107], v[88:91], v[156:159]
	v_mfma_f32_16x16x32_bf16 v[164:167], v[104:107], v[188:191], v[164:167]
	v_mfma_f32_16x16x32_bf16 v[168:171], v[112:115], v[188:191], v[168:171]
	v_mfma_f32_16x16x32_bf16 v[160:163], v[112:115], v[88:91], v[160:163]
	v_mfma_f32_16x16x32_bf16 v[152:155], v[112:115], v[48:51], v[152:155]
	v_mfma_f32_16x16x32_bf16 v[4:7], v[112:115], v[196:199], v[4:7]
	v_mfma_f32_16x16x32_bf16 v[0:3], v[108:111], v[200:203], v[0:3]
	v_mfma_f32_16x16x32_bf16 v[148:151], v[108:111], v[56:59], v[148:151]
	v_mfma_f32_16x16x32_bf16 v[156:159], v[108:111], v[96:99], v[156:159]
	v_mfma_f32_16x16x32_bf16 v[164:167], v[108:111], v[192:195], v[164:167]
	v_mfma_f32_16x16x32_bf16 v[168:171], v[116:119], v[192:195], v[168:171]
	v_mfma_f32_16x16x32_bf16 v[160:163], v[116:119], v[96:99], v[160:163]
	v_mfma_f32_16x16x32_bf16 v[152:155], v[116:119], v[56:59], v[152:155]
	v_mfma_f32_16x16x32_bf16 v[4:7], v[116:119], v[200:203], v[4:7]
	v_mfma_f32_16x16x32_bf16 v[12:15], v[172:175], v[48:51], v[12:15]
	v_mfma_f32_16x16x32_bf16 v[204:207], v[176:179], v[56:59], v[12:15]
	v_mfma_f32_16x16x32_bf16 v[12:15], v[120:123], v[88:91], v[24:27]
	v_mfma_f32_16x16x32_bf16 v[24:27], v[124:127], v[96:99], v[12:15]
	v_mfma_f32_16x16x32_bf16 v[12:15], v[172:175], v[88:91], v[28:31]
	v_mfma_f32_16x16x32_bf16 v[208:211], v[176:179], v[96:99], v[12:15]
	v_mfma_f32_16x16x32_bf16 v[12:15], v[120:123], v[188:191], v[60:63]
	v_mfma_f32_16x16x32_bf16 v[220:223], v[124:127], v[192:195], v[12:15]
	v_mfma_f32_16x16x32_bf16 v[12:15], v[172:175], v[188:191], v[100:103]
	v_mfma_f32_16x16x32_bf16 v[8:11], v[120:123], v[48:51], v[8:11]
	v_mfma_f32_16x16x32_bf16 v[188:191], v[176:179], v[192:195], v[12:15]
	v_mfma_f32_16x16x32_bf16 v[12:15], v[120:123], v[196:199], v[16:19]
	v_mfma_f32_16x16x32_bf16 v[8:11], v[124:127], v[56:59], v[8:11]
	v_mfma_f32_16x16x32_bf16 v[192:195], v[124:127], v[200:203], v[12:15]
	v_mfma_f32_16x16x32_bf16 v[12:15], v[172:175], v[196:199], v[20:23]
	v_mfma_f32_16x16x32_bf16 v[172:175], v[176:179], v[200:203], v[12:15]
	s_setprio 0
	s_barrier
	s_nop 4
	ds_read_b128 v[12:15], v224
	ds_read_b128 v[16:19], v224 offset:1024
	ds_read_b128 v[176:179], v224 offset:2048
	ds_read_b128 v[196:199], v224 offset:3072
	ds_read_b128 v[200:203], v232
	ds_read_b128 v[224:227], v232 offset:1024
	ds_read_b128 v[228:231], v232 offset:2048
	ds_read_b128 v[232:235], v232 offset:3072
	s_add_u32 s58, s64, 0x10000
	s_addc_u32 s59, s65, 0
	s_mov_b32 m0, s51
	v_lshl_add_u64 v[48:49], s[58:59], 0, v[128:129]
	ds_read_b128 v[20:23], v147 offset:32768
	ds_read_b128 v[28:31], v147 offset:33792
	ds_read_b128 v[60:63], v147 offset:34816
	ds_read_b128 v[100:103], v147 offset:35840
	ds_read_b128 v[236:239], v147 offset:36864
	ds_read_b128 v[240:243], v147 offset:37888
	ds_read_b128 v[244:247], v147 offset:38912
	ds_read_b128 v[248:251], v147 offset:39936
	global_load_lds_dwordx4 v[48:49], off
	v_lshl_add_u64 v[48:49], s[58:59], 0, v[132:133]
	s_mov_b32 m0, s57
	s_nop 0
	global_load_lds_dwordx4 v[48:49], off
	s_waitcnt vmcnt(8)
	s_waitcnt lgkmcnt(0)
	s_barrier
	s_setprio 1
	v_mfma_f32_16x16x32_bf16 v[48:51], v[12:15], v[20:23], v[64:67]
	v_mfma_f32_16x16x32_bf16 v[120:123], v[16:19], v[28:31], v[48:51]
	v_mfma_f32_16x16x32_bf16 v[48:51], v[176:179], v[20:23], v[68:71]
	v_mfma_f32_16x16x32_bf16 v[112:115], v[196:199], v[28:31], v[48:51]
	v_mfma_f32_16x16x32_bf16 v[48:51], v[12:15], v[60:63], v[72:75]
	v_mfma_f32_16x16x32_bf16 v[104:107], v[16:19], v[100:103], v[48:51]
	v_mfma_f32_16x16x32_bf16 v[48:51], v[176:179], v[60:63], v[76:79]
	v_mfma_f32_16x16x32_bf16 v[96:99], v[196:199], v[100:103], v[48:51]
	v_mfma_f32_16x16x32_bf16 v[48:51], v[12:15], v[236:239], v[80:83]
	v_mfma_f32_16x16x32_bf16 v[88:91], v[16:19], v[240:243], v[48:51]
	v_mfma_f32_16x16x32_bf16 v[48:51], v[176:179], v[236:239], v[84:87]
	v_mfma_f32_16x16x32_bf16 v[80:83], v[196:199], v[240:243], v[48:51]
	v_mfma_f32_16x16x32_bf16 v[48:51], v[12:15], v[244:247], v[212:215]
	v_mfma_f32_16x16x32_bf16 v[56:59], v[16:19], v[248:251], v[48:51]
	v_mfma_f32_16x16x32_bf16 v[48:51], v[176:179], v[244:247], v[92:95]
	v_mfma_f32_16x16x32_bf16 v[48:51], v[196:199], v[248:251], v[48:51]
	v_mfma_f32_16x16x32_bf16 v[64:67], v[200:203], v[20:23], v[216:219]
	v_mfma_f32_16x16x32_bf16 v[20:23], v[228:231], v[20:23], v[32:35]
	v_mfma_f32_16x16x32_bf16 v[116:119], v[232:235], v[28:31], v[20:23]
	v_mfma_f32_16x16x32_bf16 v[20:23], v[200:203], v[60:63], v[36:39]
	v_mfma_f32_16x16x32_bf16 v[108:111], v[224:227], v[100:103], v[20:23]
	v_mfma_f32_16x16x32_bf16 v[20:23], v[228:231], v[60:63], v[40:43]
	v_mfma_f32_16x16x32_bf16 v[100:103], v[232:235], v[100:103], v[20:23]
	v_mfma_f32_16x16x32_bf16 v[20:23], v[200:203], v[236:239], v[44:47]
	v_mfma_f32_16x16x32_bf16 v[92:95], v[224:227], v[240:243], v[20:23]
	v_mfma_f32_16x16x32_bf16 v[20:23], v[228:231], v[236:239], v[180:183]
	v_mfma_f32_16x16x32_bf16 v[84:87], v[232:235], v[240:243], v[20:23]
	v_mfma_f32_16x16x32_bf16 v[20:23], v[200:203], v[244:247], v[52:55]
	v_mfma_f32_16x16x32_bf16 v[60:63], v[224:227], v[248:251], v[20:23]
	v_mfma_f32_16x16x32_bf16 v[20:23], v[228:231], v[244:247], v[184:187]
	v_mfma_f32_16x16x32_bf16 v[124:127], v[224:227], v[28:31], v[64:67]
	v_mfma_f32_16x16x32_bf16 v[52:55], v[232:235], v[248:251], v[20:23]
	s_setprio 0
	s_barrier
	s_mov_b32 m0, s87
	s_nop 2
	v_lshl_add_u64 v[20:21], v[140:141], 0, s[14:15]
	s_add_u32 s58, s62, 0x10080
	ds_read_b128 v[32:35], v147 offset:49152
	ds_read_b128 v[40:43], v147 offset:50176
	ds_read_b128 v[180:183], v147 offset:51200
	ds_read_b128 v[184:187], v147 offset:52224
	ds_read_b128 v[212:215], v147 offset:53248
	ds_read_b128 v[216:219], v147 offset:54272
	ds_read_b128 v[236:239], v147 offset:55296
	ds_read_b128 v[240:243], v147 offset:56320
	global_load_lds_dwordx4 v[20:21], off
	v_lshl_add_u64 v[20:21], v[252:253], 0, s[14:15]
	s_mov_b32 m0, s86
	s_addc_u32 s59, s63, 0
	global_load_lds_dwordx4 v[20:21], off
	v_lshl_add_u64 v[20:21], s[58:59], 0, v[130:131]
	s_mov_b32 m0, s60
	s_nop 0
	global_load_lds_dwordx4 v[20:21], off
	v_lshl_add_u64 v[20:21], s[58:59], 0, v[134:135]
	s_mov_b32 m0, s61
	s_nop 0
	global_load_lds_dwordx4 v[20:21], off
	v_lshl_add_u64 v[20:21], v[136:137], 0, s[14:15]
	s_mov_b32 m0, s66
	s_nop 0
	global_load_lds_dwordx4 v[20:21], off
	v_lshl_add_u64 v[20:21], v[138:139], 0, s[14:15]
	s_mov_b32 m0, s67
	s_nop 0
	global_load_lds_dwordx4 v[20:21], off
	s_waitcnt vmcnt(8)
	s_waitcnt lgkmcnt(0)
	s_barrier
	s_setprio 1
	v_mfma_f32_16x16x32_bf16 v[20:23], v[12:15], v[32:35], v[148:151]
	v_mfma_f32_16x16x32_bf16 v[76:79], v[16:19], v[40:43], v[20:23]
	v_mfma_f32_16x16x32_bf16 v[20:23], v[176:179], v[32:35], v[152:155]
	v_mfma_f32_16x16x32_bf16 v[68:71], v[196:199], v[40:43], v[20:23]
	v_mfma_f32_16x16x32_bf16 v[20:23], v[12:15], v[180:183], v[156:159]
	v_mfma_f32_16x16x32_bf16 v[44:47], v[16:19], v[184:187], v[20:23]
	v_mfma_f32_16x16x32_bf16 v[20:23], v[176:179], v[180:183], v[160:163]
	v_mfma_f32_16x16x32_bf16 v[36:39], v[196:199], v[184:187], v[20:23]
	v_mfma_f32_16x16x32_bf16 v[20:23], v[12:15], v[212:215], v[164:167]
	v_mfma_f32_16x16x32_bf16 v[0:3], v[12:15], v[236:239], v[0:3]
	v_mfma_f32_16x16x32_bf16 v[28:31], v[16:19], v[216:219], v[20:23]
	v_mfma_f32_16x16x32_bf16 v[20:23], v[176:179], v[212:215], v[168:171]
	v_mfma_f32_16x16x32_bf16 v[12:15], v[16:19], v[240:243], v[0:3]
	v_mfma_f32_16x16x32_bf16 v[0:3], v[176:179], v[236:239], v[4:7]
	v_mfma_f32_16x16x32_bf16 v[20:23], v[196:199], v[216:219], v[20:23]
	v_mfma_f32_16x16x32_bf16 v[4:7], v[196:199], v[240:243], v[0:3]
	v_mfma_f32_16x16x32_bf16 v[0:3], v[200:203], v[32:35], v[8:11]
	v_mfma_f32_16x16x32_bf16 v[72:75], v[224:227], v[40:43], v[0:3]
	v_mfma_f32_16x16x32_bf16 v[0:3], v[228:231], v[32:35], v[204:207]
	v_mfma_f32_16x16x32_bf16 v[64:67], v[232:235], v[40:43], v[0:3]
	v_mfma_f32_16x16x32_bf16 v[0:3], v[200:203], v[180:183], v[24:27]
	v_mfma_f32_16x16x32_bf16 v[40:43], v[224:227], v[184:187], v[0:3]
	v_mfma_f32_16x16x32_bf16 v[0:3], v[228:231], v[180:183], v[208:211]
	v_mfma_f32_16x16x32_bf16 v[32:35], v[232:235], v[184:187], v[0:3]
	v_mfma_f32_16x16x32_bf16 v[0:3], v[200:203], v[212:215], v[220:223]
	v_mfma_f32_16x16x32_bf16 v[24:27], v[224:227], v[216:219], v[0:3]
	v_mfma_f32_16x16x32_bf16 v[0:3], v[228:231], v[212:215], v[188:191]
	v_mfma_f32_16x16x32_bf16 v[16:19], v[232:235], v[216:219], v[0:3]
	v_mfma_f32_16x16x32_bf16 v[0:3], v[200:203], v[236:239], v[192:195]
	v_mfma_f32_16x16x32_bf16 v[8:11], v[224:227], v[240:243], v[0:3]
	v_mfma_f32_16x16x32_bf16 v[0:3], v[228:231], v[236:239], v[172:175]
	v_mfma_f32_16x16x32_bf16 v[0:3], v[232:235], v[240:243], v[0:3]
	s_setprio 0
	s_barrier
	s_andn2_b64 vcc, exec, s[16:17]
	s_cbranch_vccnz .LBB0_710
	s_barrier

.LBB0_731:
	ds_read_b128 v[146:149], v153
	ds_read_b128 v[158:161], v153 offset:1024
	ds_read_b128 v[162:165], v153 offset:2048
	ds_read_b128 v[166:169], v153 offset:3072
	ds_read_b128 v[170:173], v154
	ds_read_b128 v[174:177], v154 offset:1024
	ds_read_b128 v[178:181], v154 offset:2048
	ds_read_b128 v[182:185], v154 offset:3072
	s_add_u32 s34, s30, 0xfff80080
	s_addc_u32 s35, s31, -1
	s_cmp_eq_u32 s61, 28
	s_cselect_b32 s37, s21, s35
	s_cselect_b32 s36, s46, s34
	s_cselect_b32 s35, s19, s60
	s_cselect_b32 s34, s47, s59
	v_lshl_add_u64 v[218:219], s[30:31], 0, v[140:141]
	s_add_i32 m0, s27, 0xc000
	ds_read_b128 v[186:189], v155
	ds_read_b128 v[190:193], v155 offset:1024
	ds_read_b128 v[194:197], v155 offset:2048
	ds_read_b128 v[198:201], v155 offset:3072
	ds_read_b128 v[202:205], v155 offset:4096
	ds_read_b128 v[206:209], v155 offset:5120
	ds_read_b128 v[210:213], v155 offset:6144
	ds_read_b128 v[214:217], v155 offset:7168
	global_load_lds_dwordx4 v[218:219], off
	v_lshl_add_u64 v[218:219], s[30:31], 0, v[138:139]
	s_add_i32 m0, s27, 0xe000
	s_nop 0
	global_load_lds_dwordx4 v[218:219], off
	s_waitcnt vmcnt(8)
	s_waitcnt lgkmcnt(0)
	s_barrier
	s_setprio 1
	v_mfma_f32_16x16x32_bf16 v[124:127], v[146:149], v[186:189], v[124:127]
	v_mfma_f32_16x16x32_bf16 v[108:111], v[146:149], v[194:197], v[108:111]
	v_mfma_f32_16x16x32_bf16 v[92:95], v[146:149], v[202:205], v[92:95]
	v_mfma_f32_16x16x32_bf16 v[76:79], v[146:149], v[210:213], v[76:79]
	v_mfma_f32_16x16x32_bf16 v[72:75], v[162:165], v[210:213], v[72:75]
	v_mfma_f32_16x16x32_bf16 v[88:91], v[162:165], v[202:205], v[88:91]
	v_mfma_f32_16x16x32_bf16 v[104:107], v[162:165], v[194:197], v[104:107]
	v_mfma_f32_16x16x32_bf16 v[120:123], v[162:165], v[186:189], v[120:123]
	v_mfma_f32_16x16x32_bf16 v[124:127], v[158:161], v[190:193], v[124:127]
	v_mfma_f32_16x16x32_bf16 v[108:111], v[158:161], v[198:201], v[108:111]
	v_mfma_f32_16x16x32_bf16 v[92:95], v[158:161], v[206:209], v[92:95]
	v_mfma_f32_16x16x32_bf16 v[76:79], v[158:161], v[214:217], v[76:79]
	v_mfma_f32_16x16x32_bf16 v[72:75], v[166:169], v[214:217], v[72:75]
	v_mfma_f32_16x16x32_bf16 v[88:91], v[166:169], v[206:209], v[88:91]
	v_mfma_f32_16x16x32_bf16 v[104:107], v[166:169], v[198:201], v[104:107]
	v_mfma_f32_16x16x32_bf16 v[120:123], v[166:169], v[190:193], v[120:123]
	v_mfma_f32_16x16x32_bf16 v[116:119], v[170:173], v[186:189], v[116:119]
	v_mfma_f32_16x16x32_bf16 v[100:103], v[170:173], v[194:197], v[100:103]
	v_mfma_f32_16x16x32_bf16 v[84:87], v[170:173], v[202:205], v[84:87]
	v_mfma_f32_16x16x32_bf16 v[68:71], v[170:173], v[210:213], v[68:71]
	v_mfma_f32_16x16x32_bf16 v[64:67], v[178:181], v[210:213], v[64:67]
	v_mfma_f32_16x16x32_bf16 v[80:83], v[178:181], v[202:205], v[80:83]
	v_mfma_f32_16x16x32_bf16 v[96:99], v[178:181], v[194:197], v[96:99]
	v_mfma_f32_16x16x32_bf16 v[112:115], v[178:181], v[186:189], v[112:115]
	v_mfma_f32_16x16x32_bf16 v[116:119], v[174:177], v[190:193], v[116:119]
	v_mfma_f32_16x16x32_bf16 v[100:103], v[174:177], v[198:201], v[100:103]
	v_mfma_f32_16x16x32_bf16 v[84:87], v[174:177], v[206:209], v[84:87]
	v_mfma_f32_16x16x32_bf16 v[68:71], v[174:177], v[214:217], v[68:71]
	v_mfma_f32_16x16x32_bf16 v[64:67], v[182:185], v[214:217], v[64:67]
	v_mfma_f32_16x16x32_bf16 v[80:83], v[182:185], v[206:209], v[80:83]
	v_mfma_f32_16x16x32_bf16 v[96:99], v[182:185], v[198:201], v[96:99]
	v_mfma_f32_16x16x32_bf16 v[112:115], v[182:185], v[190:193], v[112:115]
	s_setprio 0
	s_barrier
	s_add_i32 s62, s55, s48
	v_lshl_add_u64 v[218:219], s[34:35], 0, v[130:131]
	s_mov_b32 m0, s62
	ds_read_b128 v[186:189], v155 offset:16384
	ds_read_b128 v[190:193], v155 offset:17408
	ds_read_b128 v[194:197], v155 offset:18432
	ds_read_b128 v[198:201], v155 offset:19456
	ds_read_b128 v[202:205], v155 offset:20480
	ds_read_b128 v[206:209], v155 offset:21504
	ds_read_b128 v[210:213], v155 offset:22528
	ds_read_b128 v[214:217], v155 offset:23552
	global_load_lds_dwordx4 v[218:219], off
	s_add_i32 m0, s62, 0x2000
	s_add_u32 s62, s34, 0x80000
	v_lshl_add_u64 v[220:221], s[34:35], 0, v[134:135]
	s_addc_u32 s63, s35, 0
	s_add_i32 s64, s56, s48
	global_load_lds_dwordx4 v[220:221], off
	v_lshl_add_u64 v[222:223], s[62:63], 0, v[130:131]
	s_mov_b32 m0, s64
	v_lshl_add_u64 v[224:225], s[36:37], 0, v[132:133]
	global_load_lds_dwordx4 v[222:223], off
	v_lshl_add_u64 v[222:223], s[62:63], 0, v[134:135]
	s_add_i32 m0, s64, 0x2000
	s_nop 0
	global_load_lds_dwordx4 v[222:223], off
	v_lshl_add_u64 v[222:223], s[36:37], 0, v[128:129]
	s_mov_b32 m0, s27
	s_nop 0
	global_load_lds_dwordx4 v[222:223], off
	s_mov_b32 m0, s49
	s_nop 0
	global_load_lds_dwordx4 v[224:225], off
	s_waitcnt vmcnt(8)
	s_waitcnt lgkmcnt(0)
	s_barrier
	s_setprio 1
	v_mfma_f32_16x16x32_bf16 v[60:63], v[146:149], v[186:189], v[60:63]
	v_mfma_f32_16x16x32_bf16 v[44:47], v[146:149], v[194:197], v[44:47]
	v_mfma_f32_16x16x32_bf16 v[28:31], v[146:149], v[202:205], v[28:31]
	v_mfma_f32_16x16x32_bf16 v[12:15], v[146:149], v[210:213], v[12:15]
	v_mfma_f32_16x16x32_bf16 v[8:11], v[162:165], v[210:213], v[8:11]
	v_mfma_f32_16x16x32_bf16 v[24:27], v[162:165], v[202:205], v[24:27]
	v_mfma_f32_16x16x32_bf16 v[40:43], v[162:165], v[194:197], v[40:43]
	v_mfma_f32_16x16x32_bf16 v[56:59], v[162:165], v[186:189], v[56:59]
	v_mfma_f32_16x16x32_bf16 v[60:63], v[158:161], v[190:193], v[60:63]
	v_mfma_f32_16x16x32_bf16 v[44:47], v[158:161], v[198:201], v[44:47]
	v_mfma_f32_16x16x32_bf16 v[28:31], v[158:161], v[206:209], v[28:31]
	v_mfma_f32_16x16x32_bf16 v[12:15], v[158:161], v[214:217], v[12:15]
	v_mfma_f32_16x16x32_bf16 v[8:11], v[166:169], v[214:217], v[8:11]
	v_mfma_f32_16x16x32_bf16 v[24:27], v[166:169], v[206:209], v[24:27]
	v_mfma_f32_16x16x32_bf16 v[40:43], v[166:169], v[198:201], v[40:43]
	v_mfma_f32_16x16x32_bf16 v[56:59], v[166:169], v[190:193], v[56:59]
	v_mfma_f32_16x16x32_bf16 v[52:55], v[170:173], v[186:189], v[52:55]
	v_mfma_f32_16x16x32_bf16 v[36:39], v[170:173], v[194:197], v[36:39]
	v_mfma_f32_16x16x32_bf16 v[20:23], v[170:173], v[202:205], v[20:23]
	v_mfma_f32_16x16x32_bf16 v[4:7], v[170:173], v[210:213], v[4:7]
	v_mfma_f32_16x16x32_bf16 v[0:3], v[178:181], v[210:213], v[0:3]
	v_mfma_f32_16x16x32_bf16 v[16:19], v[178:181], v[202:205], v[16:19]
	v_mfma_f32_16x16x32_bf16 v[32:35], v[178:181], v[194:197], v[32:35]
	v_mfma_f32_16x16x32_bf16 v[48:51], v[178:181], v[186:189], v[48:51]
	v_mfma_f32_16x16x32_bf16 v[52:55], v[174:177], v[190:193], v[52:55]
	v_mfma_f32_16x16x32_bf16 v[36:39], v[174:177], v[198:201], v[36:39]
	v_mfma_f32_16x16x32_bf16 v[20:23], v[174:177], v[206:209], v[20:23]
	v_mfma_f32_16x16x32_bf16 v[4:7], v[174:177], v[214:217], v[4:7]
	v_mfma_f32_16x16x32_bf16 v[0:3], v[182:185], v[214:217], v[0:3]
	v_mfma_f32_16x16x32_bf16 v[16:19], v[182:185], v[206:209], v[16:19]
	v_mfma_f32_16x16x32_bf16 v[32:35], v[182:185], v[198:201], v[32:35]
	v_mfma_f32_16x16x32_bf16 v[48:51], v[182:185], v[190:193], v[48:51]
	s_setprio 0
	s_barrier
	s_add_i32 s62, 0, 0x18000
	s_add_i32 s63, 0, 0x1c000
	v_add_u32_e32 v166, s62, v151
	v_add_u32_e32 v182, s63, v151
	ds_read_b128 v[146:149], v166
	ds_read_b128 v[158:161], v166 offset:1024
	ds_read_b128 v[162:165], v166 offset:2048
	ds_read_b128 v[166:169], v166 offset:3072
	ds_read_b128 v[170:173], v182
	ds_read_b128 v[174:177], v182 offset:1024
	ds_read_b128 v[178:181], v182 offset:2048
	ds_read_b128 v[182:185], v182 offset:3072
	s_add_u32 s36, s36, 0x80000
	s_addc_u32 s37, s37, 0
	s_mov_b32 m0, s50
	v_lshl_add_u64 v[226:227], s[36:37], 0, v[128:129]
	ds_read_b128 v[186:189], v155 offset:32768
	ds_read_b128 v[190:193], v155 offset:33792
	ds_read_b128 v[194:197], v155 offset:34816
	ds_read_b128 v[198:201], v155 offset:35840
	ds_read_b128 v[202:205], v155 offset:36864
	ds_read_b128 v[206:209], v155 offset:37888
	ds_read_b128 v[210:213], v155 offset:38912
	ds_read_b128 v[214:217], v155 offset:39936
	global_load_lds_dwordx4 v[226:227], off
	v_lshl_add_u64 v[226:227], s[36:37], 0, v[132:133]
	s_mov_b32 m0, s51
	s_nop 0
	global_load_lds_dwordx4 v[226:227], off
	s_waitcnt vmcnt(8)
	s_waitcnt lgkmcnt(0)
	s_barrier
	s_setprio 1
	v_mfma_f32_16x16x32_bf16 v[124:127], v[146:149], v[186:189], v[124:127]
	v_mfma_f32_16x16x32_bf16 v[108:111], v[146:149], v[194:197], v[108:111]
	v_mfma_f32_16x16x32_bf16 v[92:95], v[146:149], v[202:205], v[92:95]
	v_mfma_f32_16x16x32_bf16 v[76:79], v[146:149], v[210:213], v[76:79]
	v_mfma_f32_16x16x32_bf16 v[72:75], v[162:165], v[210:213], v[72:75]
	v_mfma_f32_16x16x32_bf16 v[88:91], v[162:165], v[202:205], v[88:91]
	v_mfma_f32_16x16x32_bf16 v[104:107], v[162:165], v[194:197], v[104:107]
	v_mfma_f32_16x16x32_bf16 v[120:123], v[162:165], v[186:189], v[120:123]
	v_mfma_f32_16x16x32_bf16 v[124:127], v[158:161], v[190:193], v[124:127]
	v_mfma_f32_16x16x32_bf16 v[108:111], v[158:161], v[198:201], v[108:111]
	v_mfma_f32_16x16x32_bf16 v[92:95], v[158:161], v[206:209], v[92:95]
	v_mfma_f32_16x16x32_bf16 v[76:79], v[158:161], v[214:217], v[76:79]
	v_mfma_f32_16x16x32_bf16 v[72:75], v[166:169], v[214:217], v[72:75]
	v_mfma_f32_16x16x32_bf16 v[88:91], v[166:169], v[206:209], v[88:91]
	v_mfma_f32_16x16x32_bf16 v[104:107], v[166:169], v[198:201], v[104:107]
	v_mfma_f32_16x16x32_bf16 v[120:123], v[166:169], v[190:193], v[120:123]
	v_mfma_f32_16x16x32_bf16 v[116:119], v[170:173], v[186:189], v[116:119]
	v_mfma_f32_16x16x32_bf16 v[100:103], v[170:173], v[194:197], v[100:103]
	v_mfma_f32_16x16x32_bf16 v[84:87], v[170:173], v[202:205], v[84:87]
	v_mfma_f32_16x16x32_bf16 v[68:71], v[170:173], v[210:213], v[68:71]
	v_mfma_f32_16x16x32_bf16 v[64:67], v[178:181], v[210:213], v[64:67]
	v_mfma_f32_16x16x32_bf16 v[80:83], v[178:181], v[202:205], v[80:83]
	v_mfma_f32_16x16x32_bf16 v[96:99], v[178:181], v[194:197], v[96:99]
	v_mfma_f32_16x16x32_bf16 v[112:115], v[178:181], v[186:189], v[112:115]
	v_mfma_f32_16x16x32_bf16 v[116:119], v[174:177], v[190:193], v[116:119]
	v_mfma_f32_16x16x32_bf16 v[100:103], v[174:177], v[198:201], v[100:103]
	v_mfma_f32_16x16x32_bf16 v[84:87], v[174:177], v[206:209], v[84:87]
	v_mfma_f32_16x16x32_bf16 v[68:71], v[174:177], v[214:217], v[68:71]
	v_mfma_f32_16x16x32_bf16 v[64:67], v[182:185], v[214:217], v[64:67]
	v_mfma_f32_16x16x32_bf16 v[80:83], v[182:185], v[206:209], v[80:83]
	v_mfma_f32_16x16x32_bf16 v[96:99], v[182:185], v[198:201], v[96:99]
	v_mfma_f32_16x16x32_bf16 v[112:115], v[182:185], v[190:193], v[112:115]
	s_setprio 0
	s_barrier
	s_add_i32 s36, s62, s48
	v_lshl_add_u64 v[218:219], v[218:219], 0, s[14:15]
	s_mov_b32 m0, s36
	ds_read_b128 v[186:189], v155 offset:49152
	ds_read_b128 v[190:193], v155 offset:50176
	ds_read_b128 v[194:197], v155 offset:51200
	ds_read_b128 v[198:201], v155 offset:52224
	ds_read_b128 v[202:205], v155 offset:53248
	ds_read_b128 v[206:209], v155 offset:54272
	ds_read_b128 v[210:213], v155 offset:55296
	ds_read_b128 v[214:217], v155 offset:56320
	global_load_lds_dwordx4 v[218:219], off
	s_add_i32 m0, s36, 0x2000
	s_add_u32 s34, s34, 0x80080
	v_lshl_add_u64 v[218:219], v[220:221], 0, s[14:15]
	s_addc_u32 s35, s35, 0
	s_add_i32 s36, s63, s48
	global_load_lds_dwordx4 v[218:219], off
	v_lshl_add_u64 v[218:219], s[34:35], 0, v[130:131]
	s_mov_b32 m0, s36
	s_nop 0
	global_load_lds_dwordx4 v[218:219], off
	v_lshl_add_u64 v[218:219], s[34:35], 0, v[134:135]
	s_add_i32 m0, s36, 0x2000
	s_nop 0
	global_load_lds_dwordx4 v[218:219], off
	v_lshl_add_u64 v[218:219], v[222:223], 0, s[14:15]
	s_mov_b32 m0, s53
	s_nop 0
	global_load_lds_dwordx4 v[218:219], off
	v_lshl_add_u64 v[218:219], v[224:225], 0, s[14:15]
	s_mov_b32 m0, s54
	s_nop 0
	global_load_lds_dwordx4 v[218:219], off
	s_waitcnt vmcnt(8)
	s_waitcnt lgkmcnt(0)
	s_barrier
	s_setprio 1
	v_mfma_f32_16x16x32_bf16 v[60:63], v[146:149], v[186:189], v[60:63]
	v_mfma_f32_16x16x32_bf16 v[44:47], v[146:149], v[194:197], v[44:47]
	v_mfma_f32_16x16x32_bf16 v[28:31], v[146:149], v[202:205], v[28:31]
	v_mfma_f32_16x16x32_bf16 v[12:15], v[146:149], v[210:213], v[12:15]
	v_mfma_f32_16x16x32_bf16 v[8:11], v[162:165], v[210:213], v[8:11]
	v_mfma_f32_16x16x32_bf16 v[24:27], v[162:165], v[202:205], v[24:27]
	v_mfma_f32_16x16x32_bf16 v[40:43], v[162:165], v[194:197], v[40:43]
	v_mfma_f32_16x16x32_bf16 v[56:59], v[162:165], v[186:189], v[56:59]
	v_mfma_f32_16x16x32_bf16 v[60:63], v[158:161], v[190:193], v[60:63]
	v_mfma_f32_16x16x32_bf16 v[44:47], v[158:161], v[198:201], v[44:47]
	v_mfma_f32_16x16x32_bf16 v[28:31], v[158:161], v[206:209], v[28:31]
	v_mfma_f32_16x16x32_bf16 v[12:15], v[158:161], v[214:217], v[12:15]
	v_mfma_f32_16x16x32_bf16 v[8:11], v[166:169], v[214:217], v[8:11]
	v_mfma_f32_16x16x32_bf16 v[24:27], v[166:169], v[206:209], v[24:27]
	v_mfma_f32_16x16x32_bf16 v[40:43], v[166:169], v[198:201], v[40:43]
	v_mfma_f32_16x16x32_bf16 v[56:59], v[166:169], v[190:193], v[56:59]
	v_mfma_f32_16x16x32_bf16 v[52:55], v[170:173], v[186:189], v[52:55]
	v_mfma_f32_16x16x32_bf16 v[36:39], v[170:173], v[194:197], v[36:39]
	v_mfma_f32_16x16x32_bf16 v[20:23], v[170:173], v[202:205], v[20:23]
	v_mfma_f32_16x16x32_bf16 v[4:7], v[170:173], v[210:213], v[4:7]
	v_mfma_f32_16x16x32_bf16 v[0:3], v[178:181], v[210:213], v[0:3]
	v_mfma_f32_16x16x32_bf16 v[16:19], v[178:181], v[202:205], v[16:19]
	v_mfma_f32_16x16x32_bf16 v[32:35], v[178:181], v[194:197], v[32:35]
	v_mfma_f32_16x16x32_bf16 v[48:51], v[178:181], v[186:189], v[48:51]
	v_mfma_f32_16x16x32_bf16 v[52:55], v[174:177], v[190:193], v[52:55]
	v_mfma_f32_16x16x32_bf16 v[36:39], v[174:177], v[198:201], v[36:39]
	v_mfma_f32_16x16x32_bf16 v[20:23], v[174:177], v[206:209], v[20:23]
	v_mfma_f32_16x16x32_bf16 v[4:7], v[174:177], v[214:217], v[4:7]
	v_mfma_f32_16x16x32_bf16 v[0:3], v[182:185], v[214:217], v[0:3]
	v_mfma_f32_16x16x32_bf16 v[16:19], v[182:185], v[206:209], v[16:19]
	v_mfma_f32_16x16x32_bf16 v[32:35], v[182:185], v[198:201], v[32:35]
	v_mfma_f32_16x16x32_bf16 v[48:51], v[182:185], v[190:193], v[48:51]
	s_setprio 0
	s_barrier
	s_add_i32 s61, s61, 2
	s_add_u32 s59, s59, 0x100
	s_addc_u32 s60, s60, 0
	s_add_u32 s30, s30, 0x100
	s_addc_u32 s31, s31, 0
	s_cmp_gt_u32 s61, 29
	s_cbranch_scc0 .LBB0_731
	s_and_b64 vcc, exec, s[16:17]
	s_cbranch_vccz .LBB0_734
	s_barrier

.LBB0_952:
	ds_read_b128 v[144:147], v151
	ds_read_b128 v[156:159], v151 offset:1024
	ds_read_b128 v[160:163], v151 offset:2048
	ds_read_b128 v[164:167], v151 offset:3072
	ds_read_b128 v[168:171], v152
	ds_read_b128 v[172:175], v152 offset:1024
	ds_read_b128 v[176:179], v152 offset:2048
	ds_read_b128 v[180:183], v152 offset:3072
	s_add_u32 s54, s52, 0xfff80080
	s_addc_u32 s55, s53, -1
	s_cmp_eq_u32 s68, 28
	s_cselect_b32 s57, s27, s55
	s_cselect_b32 s56, s37, s54
	s_cselect_b32 s55, s25, s67
	s_cselect_b32 s54, s46, s47
	v_lshl_add_u64 v[216:217], s[52:53], 0, v[138:139]
	s_add_i32 m0, s59, 0xc000
	ds_read_b128 v[184:187], v153
	ds_read_b128 v[188:191], v153 offset:1024
	ds_read_b128 v[192:195], v153 offset:2048
	ds_read_b128 v[196:199], v153 offset:3072
	ds_read_b128 v[200:203], v153 offset:4096
	ds_read_b128 v[204:207], v153 offset:5120
	ds_read_b128 v[208:211], v153 offset:6144
	ds_read_b128 v[212:215], v153 offset:7168
	global_load_lds_dwordx4 v[216:217], off
	v_lshl_add_u64 v[216:217], s[52:53], 0, v[136:137]
	s_add_i32 m0, s59, 0xe000
	s_nop 0
	global_load_lds_dwordx4 v[216:217], off
	s_waitcnt vmcnt(8)
	s_waitcnt lgkmcnt(0)
	s_barrier
	s_setprio 1
	v_mfma_f32_16x16x32_bf16 v[116:119], v[144:147], v[184:187], v[116:119]
	v_mfma_f32_16x16x32_bf16 v[104:107], v[144:147], v[192:195], v[104:107]
	v_mfma_f32_16x16x32_bf16 v[88:91], v[144:147], v[200:203], v[88:91]
	v_mfma_f32_16x16x32_bf16 v[72:75], v[144:147], v[208:211], v[72:75]
	v_mfma_f32_16x16x32_bf16 v[64:67], v[160:163], v[208:211], v[64:67]
	v_mfma_f32_16x16x32_bf16 v[80:83], v[160:163], v[200:203], v[80:83]
	v_mfma_f32_16x16x32_bf16 v[96:99], v[160:163], v[192:195], v[96:99]
	v_mfma_f32_16x16x32_bf16 v[112:115], v[160:163], v[184:187], v[112:115]
	v_mfma_f32_16x16x32_bf16 v[116:119], v[156:159], v[188:191], v[116:119]
	v_mfma_f32_16x16x32_bf16 v[104:107], v[156:159], v[196:199], v[104:107]
	v_mfma_f32_16x16x32_bf16 v[88:91], v[156:159], v[204:207], v[88:91]
	v_mfma_f32_16x16x32_bf16 v[72:75], v[156:159], v[212:215], v[72:75]
	v_mfma_f32_16x16x32_bf16 v[64:67], v[164:167], v[212:215], v[64:67]
	v_mfma_f32_16x16x32_bf16 v[80:83], v[164:167], v[204:207], v[80:83]
	v_mfma_f32_16x16x32_bf16 v[96:99], v[164:167], v[196:199], v[96:99]
	v_mfma_f32_16x16x32_bf16 v[112:115], v[164:167], v[188:191], v[112:115]
	v_mfma_f32_16x16x32_bf16 v[124:127], v[168:171], v[184:187], v[124:127]
	v_mfma_f32_16x16x32_bf16 v[108:111], v[168:171], v[192:195], v[108:111]
	v_mfma_f32_16x16x32_bf16 v[92:95], v[168:171], v[200:203], v[92:95]
	v_mfma_f32_16x16x32_bf16 v[76:79], v[168:171], v[208:211], v[76:79]
	v_mfma_f32_16x16x32_bf16 v[68:71], v[176:179], v[208:211], v[68:71]
	v_mfma_f32_16x16x32_bf16 v[84:87], v[176:179], v[200:203], v[84:87]
	v_mfma_f32_16x16x32_bf16 v[100:103], v[176:179], v[192:195], v[100:103]
	v_mfma_f32_16x16x32_bf16 v[120:123], v[176:179], v[184:187], v[120:123]
	v_mfma_f32_16x16x32_bf16 v[124:127], v[172:175], v[188:191], v[124:127]
	v_mfma_f32_16x16x32_bf16 v[108:111], v[172:175], v[196:199], v[108:111]
	v_mfma_f32_16x16x32_bf16 v[92:95], v[172:175], v[204:207], v[92:95]
	v_mfma_f32_16x16x32_bf16 v[76:79], v[172:175], v[212:215], v[76:79]
	v_mfma_f32_16x16x32_bf16 v[68:71], v[180:183], v[212:215], v[68:71]
	v_mfma_f32_16x16x32_bf16 v[84:87], v[180:183], v[204:207], v[84:87]
	v_mfma_f32_16x16x32_bf16 v[100:103], v[180:183], v[196:199], v[100:103]
	v_mfma_f32_16x16x32_bf16 v[120:123], v[180:183], v[188:191], v[120:123]
	s_setprio 0
	s_barrier
	s_add_i32 s69, s64, s58
	v_lshl_add_u64 v[216:217], s[54:55], 0, v[130:131]
	s_mov_b32 m0, s69
	ds_read_b128 v[184:187], v153 offset:16384
	ds_read_b128 v[188:191], v153 offset:17408
	ds_read_b128 v[192:195], v153 offset:18432
	ds_read_b128 v[196:199], v153 offset:19456
	ds_read_b128 v[200:203], v153 offset:20480
	ds_read_b128 v[204:207], v153 offset:21504
	ds_read_b128 v[208:211], v153 offset:22528
	ds_read_b128 v[212:215], v153 offset:23552
	global_load_lds_dwordx4 v[216:217], off
	s_add_i32 m0, s69, 0x2000
	s_add_u32 s70, s54, 0x80000
	v_lshl_add_u64 v[218:219], s[54:55], 0, v[134:135]
	s_addc_u32 s71, s55, 0
	s_add_i32 s69, s65, s58
	global_load_lds_dwordx4 v[218:219], off
	v_lshl_add_u64 v[220:221], s[70:71], 0, v[130:131]
	s_mov_b32 m0, s69
	v_lshl_add_u64 v[222:223], s[56:57], 0, v[132:133]
	global_load_lds_dwordx4 v[220:221], off
	v_lshl_add_u64 v[220:221], s[70:71], 0, v[134:135]
	s_add_i32 m0, s69, 0x2000
	s_nop 0
	global_load_lds_dwordx4 v[220:221], off
	v_lshl_add_u64 v[220:221], s[56:57], 0, v[128:129]
	s_mov_b32 m0, s59
	s_nop 0
	global_load_lds_dwordx4 v[220:221], off
	s_mov_b32 m0, s50
	s_nop 0
	global_load_lds_dwordx4 v[222:223], off
	s_waitcnt vmcnt(8)
	s_waitcnt lgkmcnt(0)
	s_barrier
	s_setprio 1
	v_mfma_f32_16x16x32_bf16 v[56:59], v[144:147], v[184:187], v[56:59]
	v_mfma_f32_16x16x32_bf16 v[40:43], v[144:147], v[192:195], v[40:43]
	v_mfma_f32_16x16x32_bf16 v[24:27], v[144:147], v[200:203], v[24:27]
	v_mfma_f32_16x16x32_bf16 v[8:11], v[144:147], v[208:211], v[8:11]
	v_mfma_f32_16x16x32_bf16 v[0:3], v[160:163], v[208:211], v[0:3]
	v_mfma_f32_16x16x32_bf16 v[16:19], v[160:163], v[200:203], v[16:19]
	v_mfma_f32_16x16x32_bf16 v[32:35], v[160:163], v[192:195], v[32:35]
	v_mfma_f32_16x16x32_bf16 v[48:51], v[160:163], v[184:187], v[48:51]
	v_mfma_f32_16x16x32_bf16 v[56:59], v[156:159], v[188:191], v[56:59]
	v_mfma_f32_16x16x32_bf16 v[40:43], v[156:159], v[196:199], v[40:43]
	v_mfma_f32_16x16x32_bf16 v[24:27], v[156:159], v[204:207], v[24:27]
	v_mfma_f32_16x16x32_bf16 v[8:11], v[156:159], v[212:215], v[8:11]
	v_mfma_f32_16x16x32_bf16 v[0:3], v[164:167], v[212:215], v[0:3]
	v_mfma_f32_16x16x32_bf16 v[16:19], v[164:167], v[204:207], v[16:19]
	v_mfma_f32_16x16x32_bf16 v[32:35], v[164:167], v[196:199], v[32:35]
	v_mfma_f32_16x16x32_bf16 v[48:51], v[164:167], v[188:191], v[48:51]
	v_mfma_f32_16x16x32_bf16 v[60:63], v[168:171], v[184:187], v[60:63]
	v_mfma_f32_16x16x32_bf16 v[44:47], v[168:171], v[192:195], v[44:47]
	v_mfma_f32_16x16x32_bf16 v[28:31], v[168:171], v[200:203], v[28:31]
	v_mfma_f32_16x16x32_bf16 v[12:15], v[168:171], v[208:211], v[12:15]
	v_mfma_f32_16x16x32_bf16 v[4:7], v[176:179], v[208:211], v[4:7]
	v_mfma_f32_16x16x32_bf16 v[20:23], v[176:179], v[200:203], v[20:23]
	v_mfma_f32_16x16x32_bf16 v[36:39], v[176:179], v[192:195], v[36:39]
	v_mfma_f32_16x16x32_bf16 v[52:55], v[176:179], v[184:187], v[52:55]
	v_mfma_f32_16x16x32_bf16 v[60:63], v[172:175], v[188:191], v[60:63]
	v_mfma_f32_16x16x32_bf16 v[44:47], v[172:175], v[196:199], v[44:47]
	v_mfma_f32_16x16x32_bf16 v[28:31], v[172:175], v[204:207], v[28:31]
	v_mfma_f32_16x16x32_bf16 v[12:15], v[172:175], v[212:215], v[12:15]
	v_mfma_f32_16x16x32_bf16 v[4:7], v[180:183], v[212:215], v[4:7]
	v_mfma_f32_16x16x32_bf16 v[20:23], v[180:183], v[204:207], v[20:23]
	v_mfma_f32_16x16x32_bf16 v[36:39], v[180:183], v[196:199], v[36:39]
	v_mfma_f32_16x16x32_bf16 v[52:55], v[180:183], v[188:191], v[52:55]
	s_setprio 0
	s_barrier
	s_add_i32 s69, 0, 0x18000
	v_add_u32_e32 v155, s69, v149
	s_add_i32 s70, 0, 0x1c000
	ds_read_b128 v[144:147], v155
	ds_read_b128 v[156:159], v155 offset:1024
	ds_read_b128 v[160:163], v155 offset:2048
	ds_read_b128 v[164:167], v155 offset:3072
	v_add_u32_e32 v155, s70, v149
	ds_read_b128 v[168:171], v155
	ds_read_b128 v[172:175], v155 offset:1024
	ds_read_b128 v[176:179], v155 offset:2048
	ds_read_b128 v[180:183], v155 offset:3072
	s_add_u32 s56, s56, 0x80000
	s_addc_u32 s57, s57, 0
	s_mov_b32 m0, s51
	v_lshl_add_u64 v[224:225], s[56:57], 0, v[128:129]
	ds_read_b128 v[184:187], v153 offset:32768
	ds_read_b128 v[188:191], v153 offset:33792
	ds_read_b128 v[192:195], v153 offset:34816
	ds_read_b128 v[196:199], v153 offset:35840
	ds_read_b128 v[200:203], v153 offset:36864
	ds_read_b128 v[204:207], v153 offset:37888
	ds_read_b128 v[208:211], v153 offset:38912
	ds_read_b128 v[212:215], v153 offset:39936
	global_load_lds_dwordx4 v[224:225], off
	v_lshl_add_u64 v[224:225], s[56:57], 0, v[132:133]
	s_mov_b32 m0, s60
	s_nop 0
	global_load_lds_dwordx4 v[224:225], off
	s_waitcnt vmcnt(8)
	s_waitcnt lgkmcnt(0)
	s_barrier
	s_setprio 1
	v_mfma_f32_16x16x32_bf16 v[116:119], v[144:147], v[184:187], v[116:119]
	v_mfma_f32_16x16x32_bf16 v[104:107], v[144:147], v[192:195], v[104:107]
	v_mfma_f32_16x16x32_bf16 v[88:91], v[144:147], v[200:203], v[88:91]
	v_mfma_f32_16x16x32_bf16 v[72:75], v[144:147], v[208:211], v[72:75]
	v_mfma_f32_16x16x32_bf16 v[64:67], v[160:163], v[208:211], v[64:67]
	v_mfma_f32_16x16x32_bf16 v[80:83], v[160:163], v[200:203], v[80:83]
	v_mfma_f32_16x16x32_bf16 v[96:99], v[160:163], v[192:195], v[96:99]
	v_mfma_f32_16x16x32_bf16 v[112:115], v[160:163], v[184:187], v[112:115]
	v_mfma_f32_16x16x32_bf16 v[116:119], v[156:159], v[188:191], v[116:119]
	v_mfma_f32_16x16x32_bf16 v[104:107], v[156:159], v[196:199], v[104:107]
	v_mfma_f32_16x16x32_bf16 v[88:91], v[156:159], v[204:207], v[88:91]
	v_mfma_f32_16x16x32_bf16 v[72:75], v[156:159], v[212:215], v[72:75]
	v_mfma_f32_16x16x32_bf16 v[64:67], v[164:167], v[212:215], v[64:67]
	v_mfma_f32_16x16x32_bf16 v[80:83], v[164:167], v[204:207], v[80:83]
	v_mfma_f32_16x16x32_bf16 v[96:99], v[164:167], v[196:199], v[96:99]
	v_mfma_f32_16x16x32_bf16 v[112:115], v[164:167], v[188:191], v[112:115]
	v_mfma_f32_16x16x32_bf16 v[124:127], v[168:171], v[184:187], v[124:127]
	v_mfma_f32_16x16x32_bf16 v[108:111], v[168:171], v[192:195], v[108:111]
	v_mfma_f32_16x16x32_bf16 v[92:95], v[168:171], v[200:203], v[92:95]
	v_mfma_f32_16x16x32_bf16 v[76:79], v[168:171], v[208:211], v[76:79]
	v_mfma_f32_16x16x32_bf16 v[68:71], v[176:179], v[208:211], v[68:71]
	v_mfma_f32_16x16x32_bf16 v[84:87], v[176:179], v[200:203], v[84:87]
	v_mfma_f32_16x16x32_bf16 v[100:103], v[176:179], v[192:195], v[100:103]
	v_mfma_f32_16x16x32_bf16 v[120:123], v[176:179], v[184:187], v[120:123]
	v_mfma_f32_16x16x32_bf16 v[124:127], v[172:175], v[188:191], v[124:127]
	v_mfma_f32_16x16x32_bf16 v[108:111], v[172:175], v[196:199], v[108:111]
	v_mfma_f32_16x16x32_bf16 v[92:95], v[172:175], v[204:207], v[92:95]
	v_mfma_f32_16x16x32_bf16 v[76:79], v[172:175], v[212:215], v[76:79]
	v_mfma_f32_16x16x32_bf16 v[68:71], v[180:183], v[212:215], v[68:71]
	v_mfma_f32_16x16x32_bf16 v[84:87], v[180:183], v[204:207], v[84:87]
	v_mfma_f32_16x16x32_bf16 v[100:103], v[180:183], v[196:199], v[100:103]
	v_mfma_f32_16x16x32_bf16 v[120:123], v[180:183], v[188:191], v[120:123]
	s_setprio 0
	s_barrier
	s_add_i32 s56, s69, s58
	v_lshl_add_u64 v[216:217], v[216:217], 0, s[20:21]
	s_mov_b32 m0, s56
	ds_read_b128 v[184:187], v153 offset:49152
	ds_read_b128 v[188:191], v153 offset:50176
	ds_read_b128 v[192:195], v153 offset:51200
	ds_read_b128 v[196:199], v153 offset:52224
	ds_read_b128 v[200:203], v153 offset:53248
	ds_read_b128 v[204:207], v153 offset:54272
	ds_read_b128 v[208:211], v153 offset:55296
	ds_read_b128 v[212:215], v153 offset:56320
	global_load_lds_dwordx4 v[216:217], off
	s_add_i32 m0, s56, 0x2000
	s_add_u32 s54, s54, 0x80080
	v_lshl_add_u64 v[216:217], v[218:219], 0, s[20:21]
	s_addc_u32 s55, s55, 0
	s_add_i32 s56, s70, s58
	global_load_lds_dwordx4 v[216:217], off
	v_lshl_add_u64 v[216:217], s[54:55], 0, v[130:131]
	s_mov_b32 m0, s56
	s_nop 0
	global_load_lds_dwordx4 v[216:217], off
	v_lshl_add_u64 v[216:217], s[54:55], 0, v[134:135]
	s_add_i32 m0, s56, 0x2000
	s_nop 0
	global_load_lds_dwordx4 v[216:217], off
	v_lshl_add_u64 v[216:217], v[220:221], 0, s[20:21]
	s_mov_b32 m0, s62
	s_nop 0
	global_load_lds_dwordx4 v[216:217], off
	v_lshl_add_u64 v[216:217], v[222:223], 0, s[20:21]
	s_mov_b32 m0, s63
	s_nop 0
	global_load_lds_dwordx4 v[216:217], off
	s_waitcnt vmcnt(8)
	s_waitcnt lgkmcnt(0)
	s_barrier
	s_setprio 1
	v_mfma_f32_16x16x32_bf16 v[56:59], v[144:147], v[184:187], v[56:59]
	v_mfma_f32_16x16x32_bf16 v[40:43], v[144:147], v[192:195], v[40:43]
	v_mfma_f32_16x16x32_bf16 v[24:27], v[144:147], v[200:203], v[24:27]
	v_mfma_f32_16x16x32_bf16 v[8:11], v[144:147], v[208:211], v[8:11]
	v_mfma_f32_16x16x32_bf16 v[0:3], v[160:163], v[208:211], v[0:3]
	v_mfma_f32_16x16x32_bf16 v[16:19], v[160:163], v[200:203], v[16:19]
	v_mfma_f32_16x16x32_bf16 v[32:35], v[160:163], v[192:195], v[32:35]
	v_mfma_f32_16x16x32_bf16 v[48:51], v[160:163], v[184:187], v[48:51]
	v_mfma_f32_16x16x32_bf16 v[56:59], v[156:159], v[188:191], v[56:59]
	v_mfma_f32_16x16x32_bf16 v[40:43], v[156:159], v[196:199], v[40:43]
	v_mfma_f32_16x16x32_bf16 v[24:27], v[156:159], v[204:207], v[24:27]
	v_mfma_f32_16x16x32_bf16 v[8:11], v[156:159], v[212:215], v[8:11]
	v_mfma_f32_16x16x32_bf16 v[0:3], v[164:167], v[212:215], v[0:3]
	v_mfma_f32_16x16x32_bf16 v[16:19], v[164:167], v[204:207], v[16:19]
	v_mfma_f32_16x16x32_bf16 v[32:35], v[164:167], v[196:199], v[32:35]
	v_mfma_f32_16x16x32_bf16 v[48:51], v[164:167], v[188:191], v[48:51]
	v_mfma_f32_16x16x32_bf16 v[60:63], v[168:171], v[184:187], v[60:63]
	v_mfma_f32_16x16x32_bf16 v[44:47], v[168:171], v[192:195], v[44:47]
	v_mfma_f32_16x16x32_bf16 v[28:31], v[168:171], v[200:203], v[28:31]
	v_mfma_f32_16x16x32_bf16 v[12:15], v[168:171], v[208:211], v[12:15]
	v_mfma_f32_16x16x32_bf16 v[4:7], v[176:179], v[208:211], v[4:7]
	v_mfma_f32_16x16x32_bf16 v[20:23], v[176:179], v[200:203], v[20:23]
	v_mfma_f32_16x16x32_bf16 v[36:39], v[176:179], v[192:195], v[36:39]
	v_mfma_f32_16x16x32_bf16 v[52:55], v[176:179], v[184:187], v[52:55]
	v_mfma_f32_16x16x32_bf16 v[60:63], v[172:175], v[188:191], v[60:63]
	v_mfma_f32_16x16x32_bf16 v[44:47], v[172:175], v[196:199], v[44:47]
	v_mfma_f32_16x16x32_bf16 v[28:31], v[172:175], v[204:207], v[28:31]
	v_mfma_f32_16x16x32_bf16 v[12:15], v[172:175], v[212:215], v[12:15]
	v_mfma_f32_16x16x32_bf16 v[4:7], v[180:183], v[212:215], v[4:7]
	v_mfma_f32_16x16x32_bf16 v[20:23], v[180:183], v[204:207], v[20:23]
	v_mfma_f32_16x16x32_bf16 v[36:39], v[180:183], v[196:199], v[36:39]
	v_mfma_f32_16x16x32_bf16 v[52:55], v[180:183], v[188:191], v[52:55]
	s_setprio 0
	s_barrier
	s_add_i32 s68, s68, 2
	s_add_u32 s47, s47, 0x100
	s_addc_u32 s67, s67, 0
	s_add_u32 s52, s52, 0x100
	s_addc_u32 s53, s53, 0
	s_cmp_gt_u32 s68, 29
	s_cbranch_scc0 .LBB0_952
	s_and_b64 vcc, exec, s[22:23]
	s_cbranch_vccz .LBB0_955
	s_barrier

.LBB0_1049:
	ds_read_b128 v[148:151], v222
	ds_read_b128 v[152:155], v222 offset:1024
	ds_read_b128 v[156:159], v222 offset:2048
	ds_read_b128 v[160:163], v222 offset:3072
	ds_read_b128 v[132:135], v223
	ds_read_b128 v[136:139], v223 offset:1024
	ds_read_b128 v[140:143], v223 offset:2048
	ds_read_b128 v[144:147], v223 offset:3072
	s_add_u32 s8, s48, 0xfff80080
	s_addc_u32 s9, s49, -1
	s_cmp_eq_u32 s81, 28
	s_cselect_b32 s53, s23, s9
	s_cselect_b32 s52, s46, s8
	s_cselect_b32 s51, s21, s80
	s_cselect_b32 s50, s47, s79
	v_lshl_add_u64 v[2:3], s[48:49], 0, v[208:209]
	s_add_i32 m0, s35, 0xc000
	s_waitcnt lgkmcnt(0)
	ds_read_b128 v[164:167], v224
	ds_read_b128 v[168:171], v224 offset:1024
	ds_read_b128 v[172:175], v224 offset:2048
	ds_read_b128 v[176:179], v224 offset:3072
	ds_read_b128 v[180:183], v224 offset:4096
	ds_read_b128 v[184:187], v224 offset:5120
	ds_read_b128 v[188:191], v224 offset:6144
	ds_read_b128 v[192:195], v224 offset:7168
	global_load_lds_dwordx4 v[2:3], off
	v_lshl_add_u64 v[2:3], s[48:49], 0, v[206:207]
	s_add_i32 m0, s35, 0xe000
	s_nop 0
	global_load_lds_dwordx4 v[2:3], off
	s_waitcnt vmcnt(8)
	s_waitcnt lgkmcnt(0)
	s_barrier
	s_setprio 1
	v_mfma_f32_16x16x32_bf16 v[124:127], v[148:151], v[164:167], v[124:127]
	v_mfma_f32_16x16x32_bf16 v[104:107], v[148:151], v[172:175], v[104:107]
	v_mfma_f32_16x16x32_bf16 v[88:91], v[148:151], v[180:183], v[88:91]
	v_mfma_f32_16x16x32_bf16 v[76:79], v[148:151], v[188:191], v[76:79]
	v_mfma_f32_16x16x32_bf16 v[72:75], v[156:159], v[188:191], v[72:75]
	v_mfma_f32_16x16x32_bf16 v[84:87], v[156:159], v[180:183], v[84:87]
	v_mfma_f32_16x16x32_bf16 v[100:103], v[156:159], v[172:175], v[100:103]
	v_mfma_f32_16x16x32_bf16 v[120:123], v[156:159], v[164:167], v[120:123]
	v_mfma_f32_16x16x32_bf16 v[124:127], v[152:155], v[168:171], v[124:127]
	v_mfma_f32_16x16x32_bf16 v[104:107], v[152:155], v[176:179], v[104:107]
	v_mfma_f32_16x16x32_bf16 v[88:91], v[152:155], v[184:187], v[88:91]
	v_mfma_f32_16x16x32_bf16 v[76:79], v[152:155], v[192:195], v[76:79]
	v_mfma_f32_16x16x32_bf16 v[72:75], v[160:163], v[192:195], v[72:75]
	v_mfma_f32_16x16x32_bf16 v[84:87], v[160:163], v[184:187], v[84:87]
	v_mfma_f32_16x16x32_bf16 v[100:103], v[160:163], v[176:179], v[100:103]
	v_mfma_f32_16x16x32_bf16 v[120:123], v[160:163], v[168:171], v[120:123]
	v_mfma_f32_16x16x32_bf16 v[128:131], v[132:135], v[164:167], v[128:131]
	v_mfma_f32_16x16x32_bf16 v[112:115], v[132:135], v[172:175], v[112:115]
	v_mfma_f32_16x16x32_bf16 v[96:99], v[132:135], v[180:183], v[96:99]
	v_mfma_f32_16x16x32_bf16 v[80:83], v[132:135], v[188:191], v[80:83]
	v_mfma_f32_16x16x32_bf16 v[68:71], v[140:143], v[188:191], v[68:71]
	v_mfma_f32_16x16x32_bf16 v[92:95], v[140:143], v[180:183], v[92:95]
	v_mfma_f32_16x16x32_bf16 v[108:111], v[140:143], v[172:175], v[108:111]
	v_mfma_f32_16x16x32_bf16 v[116:119], v[140:143], v[164:167], v[116:119]
	v_mfma_f32_16x16x32_bf16 v[128:131], v[136:139], v[168:171], v[128:131]
	v_mfma_f32_16x16x32_bf16 v[112:115], v[136:139], v[176:179], v[112:115]
	v_mfma_f32_16x16x32_bf16 v[96:99], v[136:139], v[184:187], v[96:99]
	v_mfma_f32_16x16x32_bf16 v[80:83], v[136:139], v[192:195], v[80:83]
	v_mfma_f32_16x16x32_bf16 v[68:71], v[144:147], v[192:195], v[68:71]
	v_mfma_f32_16x16x32_bf16 v[92:95], v[144:147], v[184:187], v[92:95]
	v_mfma_f32_16x16x32_bf16 v[108:111], v[144:147], v[176:179], v[108:111]
	v_mfma_f32_16x16x32_bf16 v[116:119], v[144:147], v[168:171], v[116:119]
	s_setprio 0
	s_barrier
	s_add_i32 s8, s65, s56
	v_lshl_add_u64 v[2:3], s[50:51], 0, v[198:199]
	s_mov_b32 m0, s8
	ds_read_b128 v[188:191], v224 offset:16384
	ds_read_b128 v[192:195], v224 offset:17408
	ds_read_b128 v[180:183], v224 offset:18432
	ds_read_b128 v[184:187], v224 offset:19456
	ds_read_b128 v[172:175], v224 offset:20480
	ds_read_b128 v[176:179], v224 offset:21504
	ds_read_b128 v[164:167], v224 offset:22528
	ds_read_b128 v[168:171], v224 offset:23552
	global_load_lds_dwordx4 v[2:3], off
	s_add_i32 m0, s8, 0x2000
	s_add_u32 s8, s50, 0x80000
	v_lshl_add_u64 v[212:213], s[50:51], 0, v[202:203]
	s_addc_u32 s9, s51, 0
	s_add_i32 s78, s66, s56
	global_load_lds_dwordx4 v[212:213], off
	v_lshl_add_u64 v[214:215], s[8:9], 0, v[198:199]
	s_mov_b32 m0, s78
	v_lshl_add_u64 v[216:217], s[52:53], 0, v[200:201]
	global_load_lds_dwordx4 v[214:215], off
	v_lshl_add_u64 v[214:215], s[8:9], 0, v[202:203]
	s_add_i32 m0, s78, 0x2000
	v_cmp_ne_u32_e64 s[8:9], 1, v227
	global_load_lds_dwordx4 v[214:215], off
	v_lshl_add_u64 v[214:215], s[52:53], 0, v[196:197]
	s_mov_b32 m0, s35
	s_andn2_b64 vcc, exec, s[36:37]
	global_load_lds_dwordx4 v[214:215], off
	s_mov_b32 m0, s58
	s_nop 0
	global_load_lds_dwordx4 v[216:217], off
	s_waitcnt vmcnt(8)
	s_waitcnt lgkmcnt(0)
	s_barrier
	s_cbranch_vccnz .LBB0_1051
	s_setprio 1
	v_mfma_f32_16x16x32_bf16 v[56:59], v[148:151], v[188:191], v[56:59]
	v_mfma_f32_16x16x32_bf16 v[40:43], v[148:151], v[180:183], v[40:43]
	v_mfma_f32_16x16x32_bf16 v[24:27], v[148:151], v[172:175], v[24:27]
	v_mfma_f32_16x16x32_bf16 v[8:11], v[148:151], v[164:167], v[8:11]
	v_mfma_f32_16x16x32_bf16 v[4:7], v[156:159], v[164:167], v[4:7]
	v_mfma_f32_16x16x32_bf16 v[20:23], v[156:159], v[172:175], v[20:23]
	v_mfma_f32_16x16x32_bf16 v[36:39], v[156:159], v[180:183], v[36:39]
	v_mfma_f32_16x16x32_bf16 v[52:55], v[156:159], v[188:191], v[52:55]
	v_mfma_f32_16x16x32_bf16 v[56:59], v[152:155], v[192:195], v[56:59]
	v_mfma_f32_16x16x32_bf16 v[40:43], v[152:155], v[184:187], v[40:43]
	v_mfma_f32_16x16x32_bf16 v[24:27], v[152:155], v[176:179], v[24:27]
	v_mfma_f32_16x16x32_bf16 v[8:11], v[152:155], v[168:171], v[8:11]
	v_mfma_f32_16x16x32_bf16 v[4:7], v[160:163], v[168:171], v[4:7]
	v_mfma_f32_16x16x32_bf16 v[20:23], v[160:163], v[176:179], v[20:23]
	v_mfma_f32_16x16x32_bf16 v[36:39], v[160:163], v[184:187], v[36:39]
	v_mfma_f32_16x16x32_bf16 v[52:55], v[160:163], v[192:195], v[52:55]
	v_mfma_f32_16x16x32_bf16 v[64:67], v[132:135], v[188:191], v[64:67]
	v_mfma_f32_16x16x32_bf16 v[48:51], v[132:135], v[180:183], v[48:51]
	v_mfma_f32_16x16x32_bf16 v[32:35], v[132:135], v[172:175], v[32:35]
	v_mfma_f32_16x16x32_bf16 v[16:19], v[132:135], v[164:167], v[16:19]
	v_mfma_f32_16x16x32_bf16 v[12:15], v[140:143], v[164:167], v[12:15]
	v_mfma_f32_16x16x32_bf16 v[28:31], v[140:143], v[172:175], v[28:31]
	v_mfma_f32_16x16x32_bf16 v[44:47], v[140:143], v[180:183], v[44:47]
	v_mfma_f32_16x16x32_bf16 v[60:63], v[140:143], v[188:191], v[60:63]
	v_mfma_f32_16x16x32_bf16 v[64:67], v[136:139], v[192:195], v[64:67]
	v_mfma_f32_16x16x32_bf16 v[48:51], v[136:139], v[184:187], v[48:51]
	v_mfma_f32_16x16x32_bf16 v[32:35], v[136:139], v[176:179], v[32:35]
	v_mfma_f32_16x16x32_bf16 v[16:19], v[136:139], v[168:171], v[16:19]
	v_mfma_f32_16x16x32_bf16 v[12:15], v[144:147], v[168:171], v[12:15]
	v_mfma_f32_16x16x32_bf16 v[28:31], v[144:147], v[176:179], v[28:31]
	v_mfma_f32_16x16x32_bf16 v[44:47], v[144:147], v[184:187], v[44:47]
	v_mfma_f32_16x16x32_bf16 v[60:63], v[144:147], v[192:195], v[60:63]
	s_setprio 0
.LBB0_1051:
	s_barrier
	s_add_i32 s78, 0, 0x18000
	v_add_u32_e32 v1, s78, v220
	s_add_i32 s82, 0, 0x1c000
	ds_read_b128 v[148:151], v1
	ds_read_b128 v[152:155], v1 offset:1024
	ds_read_b128 v[156:159], v1 offset:2048
	ds_read_b128 v[160:163], v1 offset:3072
	v_add_u32_e32 v1, s82, v220
	ds_read_b128 v[132:135], v1
	ds_read_b128 v[136:139], v1 offset:1024
	ds_read_b128 v[140:143], v1 offset:2048
	ds_read_b128 v[144:147], v1 offset:3072
	s_add_u32 s52, s52, 0x80000
	s_addc_u32 s53, s53, 0
	s_mov_b32 m0, s59
	v_lshl_add_u64 v[228:229], s[52:53], 0, v[196:197]
	s_waitcnt lgkmcnt(0)
	ds_read_b128 v[164:167], v224 offset:32768
	ds_read_b128 v[168:171], v224 offset:33792
	ds_read_b128 v[172:175], v224 offset:34816
	ds_read_b128 v[176:179], v224 offset:35840
	ds_read_b128 v[180:183], v224 offset:36864
	ds_read_b128 v[184:187], v224 offset:37888
	ds_read_b128 v[188:191], v224 offset:38912
	ds_read_b128 v[192:195], v224 offset:39936
	global_load_lds_dwordx4 v[228:229], off
	v_lshl_add_u64 v[228:229], s[52:53], 0, v[200:201]
	s_mov_b32 m0, s60
	s_nop 0
	global_load_lds_dwordx4 v[228:229], off
	s_waitcnt vmcnt(8)
	s_waitcnt lgkmcnt(0)
	s_barrier
	s_setprio 1
	v_mfma_f32_16x16x32_bf16 v[124:127], v[148:151], v[164:167], v[124:127]
	v_mfma_f32_16x16x32_bf16 v[104:107], v[148:151], v[172:175], v[104:107]
	v_mfma_f32_16x16x32_bf16 v[88:91], v[148:151], v[180:183], v[88:91]
	v_mfma_f32_16x16x32_bf16 v[76:79], v[148:151], v[188:191], v[76:79]
	v_mfma_f32_16x16x32_bf16 v[72:75], v[156:159], v[188:191], v[72:75]
	v_mfma_f32_16x16x32_bf16 v[84:87], v[156:159], v[180:183], v[84:87]
	v_mfma_f32_16x16x32_bf16 v[100:103], v[156:159], v[172:175], v[100:103]
	v_mfma_f32_16x16x32_bf16 v[120:123], v[156:159], v[164:167], v[120:123]
	v_mfma_f32_16x16x32_bf16 v[124:127], v[152:155], v[168:171], v[124:127]
	v_mfma_f32_16x16x32_bf16 v[104:107], v[152:155], v[176:179], v[104:107]
	v_mfma_f32_16x16x32_bf16 v[88:91], v[152:155], v[184:187], v[88:91]
	v_mfma_f32_16x16x32_bf16 v[76:79], v[152:155], v[192:195], v[76:79]
	v_mfma_f32_16x16x32_bf16 v[72:75], v[160:163], v[192:195], v[72:75]
	v_mfma_f32_16x16x32_bf16 v[84:87], v[160:163], v[184:187], v[84:87]
	v_mfma_f32_16x16x32_bf16 v[100:103], v[160:163], v[176:179], v[100:103]
	v_mfma_f32_16x16x32_bf16 v[120:123], v[160:163], v[168:171], v[120:123]
	v_mfma_f32_16x16x32_bf16 v[128:131], v[132:135], v[164:167], v[128:131]
	v_mfma_f32_16x16x32_bf16 v[112:115], v[132:135], v[172:175], v[112:115]
	v_mfma_f32_16x16x32_bf16 v[96:99], v[132:135], v[180:183], v[96:99]
	v_mfma_f32_16x16x32_bf16 v[80:83], v[132:135], v[188:191], v[80:83]
	v_mfma_f32_16x16x32_bf16 v[68:71], v[140:143], v[188:191], v[68:71]
	v_mfma_f32_16x16x32_bf16 v[92:95], v[140:143], v[180:183], v[92:95]
	v_mfma_f32_16x16x32_bf16 v[108:111], v[140:143], v[172:175], v[108:111]
	v_mfma_f32_16x16x32_bf16 v[116:119], v[140:143], v[164:167], v[116:119]
	v_mfma_f32_16x16x32_bf16 v[128:131], v[136:139], v[168:171], v[128:131]
	v_mfma_f32_16x16x32_bf16 v[112:115], v[136:139], v[176:179], v[112:115]
	v_mfma_f32_16x16x32_bf16 v[96:99], v[136:139], v[184:187], v[96:99]
	v_mfma_f32_16x16x32_bf16 v[80:83], v[136:139], v[192:195], v[80:83]
	v_mfma_f32_16x16x32_bf16 v[68:71], v[144:147], v[192:195], v[68:71]
	v_mfma_f32_16x16x32_bf16 v[92:95], v[144:147], v[184:187], v[92:95]
	v_mfma_f32_16x16x32_bf16 v[108:111], v[144:147], v[176:179], v[108:111]
	v_mfma_f32_16x16x32_bf16 v[116:119], v[144:147], v[168:171], v[116:119]
	s_setprio 0
	s_barrier
	s_add_i32 s52, s78, s56
	v_lshl_add_u64 v[2:3], v[2:3], 0, s[14:15]
	s_mov_b32 m0, s52
	ds_read_b128 v[188:191], v224 offset:49152
	ds_read_b128 v[192:195], v224 offset:50176
	ds_read_b128 v[180:183], v224 offset:51200
	ds_read_b128 v[184:187], v224 offset:52224
	ds_read_b128 v[172:175], v224 offset:53248
	ds_read_b128 v[176:179], v224 offset:54272
	ds_read_b128 v[164:167], v224 offset:55296
	ds_read_b128 v[168:171], v224 offset:56320
	global_load_lds_dwordx4 v[2:3], off
	s_add_i32 m0, s52, 0x2000
	s_add_u32 s50, s50, 0x80080
	v_lshl_add_u64 v[2:3], v[212:213], 0, s[14:15]
	s_addc_u32 s51, s51, 0
	s_add_i32 s52, s82, s56
	global_load_lds_dwordx4 v[2:3], off
	v_lshl_add_u64 v[2:3], s[50:51], 0, v[198:199]
	s_mov_b32 m0, s52
	s_and_b64 vcc, exec, s[8:9]
	global_load_lds_dwordx4 v[2:3], off
	v_lshl_add_u64 v[2:3], s[50:51], 0, v[202:203]
	s_add_i32 m0, s52, 0x2000
	s_nop 0
	global_load_lds_dwordx4 v[2:3], off
	v_lshl_add_u64 v[2:3], v[214:215], 0, s[14:15]
	s_mov_b32 m0, s61
	s_nop 0
	global_load_lds_dwordx4 v[2:3], off
	v_lshl_add_u64 v[2:3], v[216:217], 0, s[14:15]
	s_mov_b32 m0, s62
	s_nop 0
	global_load_lds_dwordx4 v[2:3], off
	s_waitcnt vmcnt(8)
	s_waitcnt lgkmcnt(0)
	s_barrier
	s_cbranch_vccnz .LBB0_1048
	s_setprio 1
	v_mfma_f32_16x16x32_bf16 v[56:59], v[148:151], v[188:191], v[56:59]
	v_mfma_f32_16x16x32_bf16 v[52:55], v[156:159], v[188:191], v[52:55]
	v_mfma_f32_16x16x32_bf16 v[40:43], v[148:151], v[180:183], v[40:43]
	v_mfma_f32_16x16x32_bf16 v[36:39], v[156:159], v[180:183], v[36:39]
	v_mfma_f32_16x16x32_bf16 v[24:27], v[148:151], v[172:175], v[24:27]
	v_mfma_f32_16x16x32_bf16 v[20:23], v[156:159], v[172:175], v[20:23]
	v_mfma_f32_16x16x32_bf16 v[8:11], v[148:151], v[164:167], v[8:11]
	v_mfma_f32_16x16x32_bf16 v[2:5], v[156:159], v[164:167], v[4:7]
	v_mfma_f32_16x16x32_bf16 v[56:59], v[152:155], v[192:195], v[56:59]
	v_mfma_f32_16x16x32_bf16 v[52:55], v[160:163], v[192:195], v[52:55]
	v_mfma_f32_16x16x32_bf16 v[40:43], v[152:155], v[184:187], v[40:43]
	v_mfma_f32_16x16x32_bf16 v[36:39], v[160:163], v[184:187], v[36:39]
	v_mfma_f32_16x16x32_bf16 v[24:27], v[152:155], v[176:179], v[24:27]
	v_mfma_f32_16x16x32_bf16 v[20:23], v[160:163], v[176:179], v[20:23]
	v_mfma_f32_16x16x32_bf16 v[8:11], v[152:155], v[168:171], v[8:11]
	v_mfma_f32_16x16x32_bf16 v[4:7], v[160:163], v[168:171], v[2:5]
	v_mfma_f32_16x16x32_bf16 v[64:67], v[132:135], v[188:191], v[64:67]
	v_mfma_f32_16x16x32_bf16 v[48:51], v[132:135], v[180:183], v[48:51]
	v_mfma_f32_16x16x32_bf16 v[32:35], v[132:135], v[172:175], v[32:35]
	v_mfma_f32_16x16x32_bf16 v[16:19], v[132:135], v[164:167], v[16:19]
	v_mfma_f32_16x16x32_bf16 v[12:15], v[140:143], v[164:167], v[12:15]
	v_mfma_f32_16x16x32_bf16 v[28:31], v[140:143], v[172:175], v[28:31]
	v_mfma_f32_16x16x32_bf16 v[44:47], v[140:143], v[180:183], v[44:47]
	v_mfma_f32_16x16x32_bf16 v[60:63], v[140:143], v[188:191], v[60:63]
	v_mfma_f32_16x16x32_bf16 v[64:67], v[136:139], v[192:195], v[64:67]
	v_mfma_f32_16x16x32_bf16 v[48:51], v[136:139], v[184:187], v[48:51]
	v_mfma_f32_16x16x32_bf16 v[32:35], v[136:139], v[176:179], v[32:35]
	v_mfma_f32_16x16x32_bf16 v[16:19], v[136:139], v[168:171], v[16:19]
	v_mfma_f32_16x16x32_bf16 v[12:15], v[144:147], v[168:171], v[12:15]
	v_mfma_f32_16x16x32_bf16 v[28:31], v[144:147], v[176:179], v[28:31]
	v_mfma_f32_16x16x32_bf16 v[44:47], v[144:147], v[184:187], v[44:47]
	v_mfma_f32_16x16x32_bf16 v[60:63], v[144:147], v[192:195], v[60:63]
	s_setprio 0
	s_branch .LBB0_1048

.LBB0_1137:
	ds_read_b128 v[144:147], v151
	ds_read_b128 v[156:159], v151 offset:1024
	ds_read_b128 v[160:163], v151 offset:2048
	ds_read_b128 v[164:167], v151 offset:3072
	ds_read_b128 v[168:171], v152
	ds_read_b128 v[172:175], v152 offset:1024
	ds_read_b128 v[176:179], v152 offset:2048
	ds_read_b128 v[180:183], v152 offset:3072
	s_add_u32 s34, s30, 0x100
	s_addc_u32 s35, s31, 0
	s_cmpk_eq_i32 s66, 0x54
	s_cselect_b32 s49, s11, s35
	s_cselect_b32 s48, s10, s34
	s_cselect_b32 s37, s27, s47
	s_cselect_b32 s36, s26, s46
	v_lshl_add_u64 v[216:217], s[30:31], 0, v[138:139]
	s_add_i32 m0, s53, 0xc000
	ds_read_b128 v[184:187], v153
	ds_read_b128 v[188:191], v153 offset:1024
	ds_read_b128 v[192:195], v153 offset:2048
	ds_read_b128 v[196:199], v153 offset:3072
	ds_read_b128 v[200:203], v153 offset:4096
	ds_read_b128 v[204:207], v153 offset:5120
	ds_read_b128 v[208:211], v153 offset:6144
	ds_read_b128 v[212:215], v153 offset:7168
	global_load_lds_dwordx4 v[216:217], off
	v_lshl_add_u64 v[216:217], s[30:31], 0, v[136:137]
	s_add_i32 m0, s53, 0xe000
	s_nop 0
	global_load_lds_dwordx4 v[216:217], off
	s_waitcnt vmcnt(8)
	s_waitcnt lgkmcnt(0)
	s_barrier
	s_setprio 1
	v_mfma_f32_16x16x32_bf16 v[124:127], v[144:147], v[184:187], v[124:127]
	v_mfma_f32_16x16x32_bf16 v[108:111], v[144:147], v[192:195], v[108:111]
	v_mfma_f32_16x16x32_bf16 v[92:95], v[144:147], v[200:203], v[92:95]
	v_mfma_f32_16x16x32_bf16 v[76:79], v[144:147], v[208:211], v[76:79]
	v_mfma_f32_16x16x32_bf16 v[72:75], v[160:163], v[208:211], v[72:75]
	v_mfma_f32_16x16x32_bf16 v[88:91], v[160:163], v[200:203], v[88:91]
	v_mfma_f32_16x16x32_bf16 v[104:107], v[160:163], v[192:195], v[104:107]
	v_mfma_f32_16x16x32_bf16 v[120:123], v[160:163], v[184:187], v[120:123]
	v_mfma_f32_16x16x32_bf16 v[124:127], v[156:159], v[188:191], v[124:127]
	v_mfma_f32_16x16x32_bf16 v[108:111], v[156:159], v[196:199], v[108:111]
	v_mfma_f32_16x16x32_bf16 v[92:95], v[156:159], v[204:207], v[92:95]
	v_mfma_f32_16x16x32_bf16 v[76:79], v[156:159], v[212:215], v[76:79]
	v_mfma_f32_16x16x32_bf16 v[72:75], v[164:167], v[212:215], v[72:75]
	v_mfma_f32_16x16x32_bf16 v[88:91], v[164:167], v[204:207], v[88:91]
	v_mfma_f32_16x16x32_bf16 v[104:107], v[164:167], v[196:199], v[104:107]
	v_mfma_f32_16x16x32_bf16 v[120:123], v[164:167], v[188:191], v[120:123]
	v_mfma_f32_16x16x32_bf16 v[116:119], v[168:171], v[184:187], v[116:119]
	v_mfma_f32_16x16x32_bf16 v[100:103], v[168:171], v[192:195], v[100:103]
	v_mfma_f32_16x16x32_bf16 v[84:87], v[168:171], v[200:203], v[84:87]
	v_mfma_f32_16x16x32_bf16 v[68:71], v[168:171], v[208:211], v[68:71]
	v_mfma_f32_16x16x32_bf16 v[64:67], v[176:179], v[208:211], v[64:67]
	v_mfma_f32_16x16x32_bf16 v[80:83], v[176:179], v[200:203], v[80:83]
	v_mfma_f32_16x16x32_bf16 v[96:99], v[176:179], v[192:195], v[96:99]
	v_mfma_f32_16x16x32_bf16 v[112:115], v[176:179], v[184:187], v[112:115]
	v_mfma_f32_16x16x32_bf16 v[116:119], v[172:175], v[188:191], v[116:119]
	v_mfma_f32_16x16x32_bf16 v[100:103], v[172:175], v[196:199], v[100:103]
	v_mfma_f32_16x16x32_bf16 v[84:87], v[172:175], v[204:207], v[84:87]
	v_mfma_f32_16x16x32_bf16 v[68:71], v[172:175], v[212:215], v[68:71]
	v_mfma_f32_16x16x32_bf16 v[64:67], v[180:183], v[212:215], v[64:67]
	v_mfma_f32_16x16x32_bf16 v[80:83], v[180:183], v[204:207], v[80:83]
	v_mfma_f32_16x16x32_bf16 v[96:99], v[180:183], v[196:199], v[96:99]
	v_mfma_f32_16x16x32_bf16 v[112:115], v[180:183], v[188:191], v[112:115]
	s_setprio 0
	s_barrier
	s_add_i32 s30, s60, s52
	v_lshl_add_u64 v[216:217], s[36:37], 0, v[130:131]
	s_mov_b32 m0, s30
	ds_read_b128 v[184:187], v153 offset:16384
	ds_read_b128 v[188:191], v153 offset:17408
	ds_read_b128 v[192:195], v153 offset:18432
	ds_read_b128 v[196:199], v153 offset:19456
	ds_read_b128 v[200:203], v153 offset:20480
	ds_read_b128 v[204:207], v153 offset:21504
	ds_read_b128 v[208:211], v153 offset:22528
	ds_read_b128 v[212:215], v153 offset:23552
	global_load_lds_dwordx4 v[216:217], off
	s_add_i32 m0, s30, 0x2000
	s_add_u32 s30, s36, 0x160000
	v_lshl_add_u64 v[218:219], s[36:37], 0, v[134:135]
	s_addc_u32 s31, s37, 0
	s_add_i32 s67, s61, s52
	global_load_lds_dwordx4 v[218:219], off
	v_lshl_add_u64 v[220:221], s[30:31], 0, v[130:131]
	s_mov_b32 m0, s67
	v_lshl_add_u64 v[222:223], s[48:49], 0, v[132:133]
	global_load_lds_dwordx4 v[220:221], off
	v_lshl_add_u64 v[220:221], s[30:31], 0, v[134:135]
	s_add_i32 m0, s67, 0x2000
	s_nop 0
	global_load_lds_dwordx4 v[220:221], off
	v_lshl_add_u64 v[220:221], s[48:49], 0, v[128:129]
	s_mov_b32 m0, s53
	s_nop 0
	global_load_lds_dwordx4 v[220:221], off
	s_mov_b32 m0, s54
	s_nop 0
	global_load_lds_dwordx4 v[222:223], off
	s_waitcnt vmcnt(8)
	s_waitcnt lgkmcnt(0)
	s_barrier
	s_setprio 1
	v_mfma_f32_16x16x32_bf16 v[60:63], v[144:147], v[184:187], v[60:63]
	v_mfma_f32_16x16x32_bf16 v[44:47], v[144:147], v[192:195], v[44:47]
	v_mfma_f32_16x16x32_bf16 v[28:31], v[144:147], v[200:203], v[28:31]
	v_mfma_f32_16x16x32_bf16 v[12:15], v[144:147], v[208:211], v[12:15]
	v_mfma_f32_16x16x32_bf16 v[8:11], v[160:163], v[208:211], v[8:11]
	v_mfma_f32_16x16x32_bf16 v[24:27], v[160:163], v[200:203], v[24:27]
	v_mfma_f32_16x16x32_bf16 v[40:43], v[160:163], v[192:195], v[40:43]
	v_mfma_f32_16x16x32_bf16 v[56:59], v[160:163], v[184:187], v[56:59]
	v_mfma_f32_16x16x32_bf16 v[60:63], v[156:159], v[188:191], v[60:63]
	v_mfma_f32_16x16x32_bf16 v[44:47], v[156:159], v[196:199], v[44:47]
	v_mfma_f32_16x16x32_bf16 v[28:31], v[156:159], v[204:207], v[28:31]
	v_mfma_f32_16x16x32_bf16 v[12:15], v[156:159], v[212:215], v[12:15]
	v_mfma_f32_16x16x32_bf16 v[8:11], v[164:167], v[212:215], v[8:11]
	v_mfma_f32_16x16x32_bf16 v[24:27], v[164:167], v[204:207], v[24:27]
	v_mfma_f32_16x16x32_bf16 v[40:43], v[164:167], v[196:199], v[40:43]
	v_mfma_f32_16x16x32_bf16 v[56:59], v[164:167], v[188:191], v[56:59]
	v_mfma_f32_16x16x32_bf16 v[52:55], v[168:171], v[184:187], v[52:55]
	v_mfma_f32_16x16x32_bf16 v[36:39], v[168:171], v[192:195], v[36:39]
	v_mfma_f32_16x16x32_bf16 v[20:23], v[168:171], v[200:203], v[20:23]
	v_mfma_f32_16x16x32_bf16 v[4:7], v[168:171], v[208:211], v[4:7]
	v_mfma_f32_16x16x32_bf16 v[0:3], v[176:179], v[208:211], v[0:3]
	v_mfma_f32_16x16x32_bf16 v[16:19], v[176:179], v[200:203], v[16:19]
	v_mfma_f32_16x16x32_bf16 v[32:35], v[176:179], v[192:195], v[32:35]
	v_mfma_f32_16x16x32_bf16 v[48:51], v[176:179], v[184:187], v[48:51]
	v_mfma_f32_16x16x32_bf16 v[52:55], v[172:175], v[188:191], v[52:55]
	v_mfma_f32_16x16x32_bf16 v[36:39], v[172:175], v[196:199], v[36:39]
	v_mfma_f32_16x16x32_bf16 v[20:23], v[172:175], v[204:207], v[20:23]
	v_mfma_f32_16x16x32_bf16 v[4:7], v[172:175], v[212:215], v[4:7]
	v_mfma_f32_16x16x32_bf16 v[0:3], v[180:183], v[212:215], v[0:3]
	v_mfma_f32_16x16x32_bf16 v[16:19], v[180:183], v[204:207], v[16:19]
	v_mfma_f32_16x16x32_bf16 v[32:35], v[180:183], v[196:199], v[32:35]
	v_mfma_f32_16x16x32_bf16 v[48:51], v[180:183], v[188:191], v[48:51]
	s_setprio 0
	s_barrier
	s_add_i32 s67, 0, 0x18000
	v_add_u32_e32 v155, s67, v149
	s_add_i32 s68, 0, 0x1c000
	ds_read_b128 v[144:147], v155
	ds_read_b128 v[156:159], v155 offset:1024
	ds_read_b128 v[160:163], v155 offset:2048
	ds_read_b128 v[164:167], v155 offset:3072
	v_add_u32_e32 v155, s68, v149
	ds_read_b128 v[168:171], v155
	ds_read_b128 v[172:175], v155 offset:1024
	ds_read_b128 v[176:179], v155 offset:2048
	ds_read_b128 v[180:183], v155 offset:3072
	s_add_u32 s30, s48, 0x160000
	s_addc_u32 s31, s49, 0
	s_mov_b32 m0, s55
	v_lshl_add_u64 v[224:225], s[30:31], 0, v[128:129]
	ds_read_b128 v[184:187], v153 offset:32768
	ds_read_b128 v[188:191], v153 offset:33792
	ds_read_b128 v[192:195], v153 offset:34816
	ds_read_b128 v[196:199], v153 offset:35840
	ds_read_b128 v[200:203], v153 offset:36864
	ds_read_b128 v[204:207], v153 offset:37888
	ds_read_b128 v[208:211], v153 offset:38912
	ds_read_b128 v[212:215], v153 offset:39936
	global_load_lds_dwordx4 v[224:225], off
	v_lshl_add_u64 v[224:225], s[30:31], 0, v[132:133]
	s_mov_b32 m0, s56
	s_nop 0
	global_load_lds_dwordx4 v[224:225], off
	s_waitcnt vmcnt(8)
	s_waitcnt lgkmcnt(0)
	s_barrier
	s_setprio 1
	v_mfma_f32_16x16x32_bf16 v[124:127], v[144:147], v[184:187], v[124:127]
	v_mfma_f32_16x16x32_bf16 v[108:111], v[144:147], v[192:195], v[108:111]
	v_mfma_f32_16x16x32_bf16 v[92:95], v[144:147], v[200:203], v[92:95]
	v_mfma_f32_16x16x32_bf16 v[76:79], v[144:147], v[208:211], v[76:79]
	v_mfma_f32_16x16x32_bf16 v[72:75], v[160:163], v[208:211], v[72:75]
	v_mfma_f32_16x16x32_bf16 v[88:91], v[160:163], v[200:203], v[88:91]
	v_mfma_f32_16x16x32_bf16 v[104:107], v[160:163], v[192:195], v[104:107]
	v_mfma_f32_16x16x32_bf16 v[120:123], v[160:163], v[184:187], v[120:123]
	v_mfma_f32_16x16x32_bf16 v[124:127], v[156:159], v[188:191], v[124:127]
	v_mfma_f32_16x16x32_bf16 v[108:111], v[156:159], v[196:199], v[108:111]
	v_mfma_f32_16x16x32_bf16 v[92:95], v[156:159], v[204:207], v[92:95]
	v_mfma_f32_16x16x32_bf16 v[76:79], v[156:159], v[212:215], v[76:79]
	v_mfma_f32_16x16x32_bf16 v[72:75], v[164:167], v[212:215], v[72:75]
	v_mfma_f32_16x16x32_bf16 v[88:91], v[164:167], v[204:207], v[88:91]
	v_mfma_f32_16x16x32_bf16 v[104:107], v[164:167], v[196:199], v[104:107]
	v_mfma_f32_16x16x32_bf16 v[120:123], v[164:167], v[188:191], v[120:123]
	v_mfma_f32_16x16x32_bf16 v[116:119], v[168:171], v[184:187], v[116:119]
	v_mfma_f32_16x16x32_bf16 v[100:103], v[168:171], v[192:195], v[100:103]
	v_mfma_f32_16x16x32_bf16 v[84:87], v[168:171], v[200:203], v[84:87]
	v_mfma_f32_16x16x32_bf16 v[68:71], v[168:171], v[208:211], v[68:71]
	v_mfma_f32_16x16x32_bf16 v[64:67], v[176:179], v[208:211], v[64:67]
	v_mfma_f32_16x16x32_bf16 v[80:83], v[176:179], v[200:203], v[80:83]
	v_mfma_f32_16x16x32_bf16 v[96:99], v[176:179], v[192:195], v[96:99]
	v_mfma_f32_16x16x32_bf16 v[112:115], v[176:179], v[184:187], v[112:115]
	v_mfma_f32_16x16x32_bf16 v[116:119], v[172:175], v[188:191], v[116:119]
	v_mfma_f32_16x16x32_bf16 v[100:103], v[172:175], v[196:199], v[100:103]
	v_mfma_f32_16x16x32_bf16 v[84:87], v[172:175], v[204:207], v[84:87]
	v_mfma_f32_16x16x32_bf16 v[68:71], v[172:175], v[212:215], v[68:71]
	v_mfma_f32_16x16x32_bf16 v[64:67], v[180:183], v[212:215], v[64:67]
	v_mfma_f32_16x16x32_bf16 v[80:83], v[180:183], v[204:207], v[80:83]
	v_mfma_f32_16x16x32_bf16 v[96:99], v[180:183], v[196:199], v[96:99]
	v_mfma_f32_16x16x32_bf16 v[112:115], v[180:183], v[188:191], v[112:115]
	s_setprio 0
	s_barrier
	s_add_i32 s30, s67, s52
	v_lshl_add_u64 v[216:217], v[216:217], 0, s[22:23]
	s_mov_b32 m0, s30
	ds_read_b128 v[184:187], v153 offset:49152
	ds_read_b128 v[188:191], v153 offset:50176
	ds_read_b128 v[192:195], v153 offset:51200
	ds_read_b128 v[196:199], v153 offset:52224
	ds_read_b128 v[200:203], v153 offset:53248
	ds_read_b128 v[204:207], v153 offset:54272
	ds_read_b128 v[208:211], v153 offset:55296
	ds_read_b128 v[212:215], v153 offset:56320
	global_load_lds_dwordx4 v[216:217], off
	s_add_i32 m0, s30, 0x2000
	s_add_u32 s30, s36, 0x160080
	v_lshl_add_u64 v[216:217], v[218:219], 0, s[22:23]
	s_addc_u32 s31, s37, 0
	s_add_i32 s36, s68, s52
	global_load_lds_dwordx4 v[216:217], off
	v_lshl_add_u64 v[216:217], s[30:31], 0, v[130:131]
	s_mov_b32 m0, s36
	s_nop 0
	global_load_lds_dwordx4 v[216:217], off
	v_lshl_add_u64 v[216:217], s[30:31], 0, v[134:135]
	s_add_i32 m0, s36, 0x2000
	s_nop 0
	global_load_lds_dwordx4 v[216:217], off
	v_lshl_add_u64 v[216:217], v[220:221], 0, s[22:23]
	s_mov_b32 m0, s58
	s_nop 0
	global_load_lds_dwordx4 v[216:217], off
	v_lshl_add_u64 v[216:217], v[222:223], 0, s[22:23]
	s_mov_b32 m0, s59
	s_nop 0
	global_load_lds_dwordx4 v[216:217], off
	s_waitcnt vmcnt(8)
	s_waitcnt lgkmcnt(0)
	s_barrier
	s_setprio 1
	v_mfma_f32_16x16x32_bf16 v[60:63], v[144:147], v[184:187], v[60:63]
	v_mfma_f32_16x16x32_bf16 v[44:47], v[144:147], v[192:195], v[44:47]
	v_mfma_f32_16x16x32_bf16 v[28:31], v[144:147], v[200:203], v[28:31]
	v_mfma_f32_16x16x32_bf16 v[12:15], v[144:147], v[208:211], v[12:15]
	v_mfma_f32_16x16x32_bf16 v[8:11], v[160:163], v[208:211], v[8:11]
	v_mfma_f32_16x16x32_bf16 v[24:27], v[160:163], v[200:203], v[24:27]
	v_mfma_f32_16x16x32_bf16 v[40:43], v[160:163], v[192:195], v[40:43]
	v_mfma_f32_16x16x32_bf16 v[56:59], v[160:163], v[184:187], v[56:59]
	v_mfma_f32_16x16x32_bf16 v[60:63], v[156:159], v[188:191], v[60:63]
	v_mfma_f32_16x16x32_bf16 v[44:47], v[156:159], v[196:199], v[44:47]
	v_mfma_f32_16x16x32_bf16 v[28:31], v[156:159], v[204:207], v[28:31]
	v_mfma_f32_16x16x32_bf16 v[12:15], v[156:159], v[212:215], v[12:15]
	v_mfma_f32_16x16x32_bf16 v[8:11], v[164:167], v[212:215], v[8:11]
	v_mfma_f32_16x16x32_bf16 v[24:27], v[164:167], v[204:207], v[24:27]
	v_mfma_f32_16x16x32_bf16 v[40:43], v[164:167], v[196:199], v[40:43]
	v_mfma_f32_16x16x32_bf16 v[56:59], v[164:167], v[188:191], v[56:59]
	v_mfma_f32_16x16x32_bf16 v[52:55], v[168:171], v[184:187], v[52:55]
	v_mfma_f32_16x16x32_bf16 v[36:39], v[168:171], v[192:195], v[36:39]
	v_mfma_f32_16x16x32_bf16 v[20:23], v[168:171], v[200:203], v[20:23]
	v_mfma_f32_16x16x32_bf16 v[4:7], v[168:171], v[208:211], v[4:7]
	v_mfma_f32_16x16x32_bf16 v[0:3], v[176:179], v[208:211], v[0:3]
	v_mfma_f32_16x16x32_bf16 v[16:19], v[176:179], v[200:203], v[16:19]
	v_mfma_f32_16x16x32_bf16 v[32:35], v[176:179], v[192:195], v[32:35]
	v_mfma_f32_16x16x32_bf16 v[48:51], v[176:179], v[184:187], v[48:51]
	v_mfma_f32_16x16x32_bf16 v[52:55], v[172:175], v[188:191], v[52:55]
	v_mfma_f32_16x16x32_bf16 v[36:39], v[172:175], v[196:199], v[36:39]
	v_mfma_f32_16x16x32_bf16 v[20:23], v[172:175], v[204:207], v[20:23]
	v_mfma_f32_16x16x32_bf16 v[4:7], v[172:175], v[212:215], v[4:7]
	v_mfma_f32_16x16x32_bf16 v[0:3], v[180:183], v[212:215], v[0:3]
	v_mfma_f32_16x16x32_bf16 v[16:19], v[180:183], v[204:207], v[16:19]
	v_mfma_f32_16x16x32_bf16 v[32:35], v[180:183], v[196:199], v[32:35]
	v_mfma_f32_16x16x32_bf16 v[48:51], v[180:183], v[188:191], v[48:51]
	s_setprio 0
	s_barrier
	s_add_i32 s66, s66, 2
	s_add_u32 s46, s46, 0x100
	s_addc_u32 s47, s47, 0
	s_cmpk_gt_u32 s66, 0x55
	s_mov_b64 s[30:31], s[34:35]
	s_cbranch_scc0 .LBB0_1137
	s_and_b64 vcc, exec, s[24:25]
	s_cbranch_vccz .LBB0_1140
	s_barrier

.LBB0_1227:
	v_add_u32_e32 v164, s56, v150
	v_add_u32_e32 v180, s57, v150
	s_add_u32 s34, s16, s30
	ds_read_b128 v[152:155], v164
	ds_read_b128 v[156:159], v164 offset:1024
	ds_read_b128 v[160:163], v164 offset:2048
	ds_read_b128 v[164:167], v164 offset:3072
	ds_read_b128 v[168:171], v180
	ds_read_b128 v[172:175], v180 offset:1024
	ds_read_b128 v[176:179], v180 offset:2048
	ds_read_b128 v[180:183], v180 offset:3072
	s_addc_u32 s35, s17, s31
	s_add_u32 s34, s34, 0x100
	s_addc_u32 s35, s35, 0
	s_add_u32 s64, s59, s30
	s_addc_u32 s65, s60, s31
	s_cmpk_eq_i32 s30, 0xf00
	s_cselect_b32 s37, s23, s35
	s_cselect_b32 s36, s61, s34
	s_cselect_b32 s35, s21, s65
	s_cselect_b32 s34, s62, s64
	v_lshl_add_u64 v[216:217], v[146:147], 0, s[30:31]
	s_add_i32 m0, s48, 0xc000
	ds_read_b128 v[184:187], v151
	ds_read_b128 v[188:191], v151 offset:1024
	ds_read_b128 v[192:195], v151 offset:2048
	ds_read_b128 v[196:199], v151 offset:3072
	ds_read_b128 v[200:203], v151 offset:4096
	ds_read_b128 v[204:207], v151 offset:5120
	ds_read_b128 v[208:211], v151 offset:6144
	ds_read_b128 v[212:215], v151 offset:7168
	global_load_lds_dwordx4 v[216:217], off
	v_lshl_add_u64 v[216:217], v[144:145], 0, s[30:31]
	s_add_i32 m0, s48, 0xe000
	s_nop 0
	global_load_lds_dwordx4 v[216:217], off
	s_waitcnt vmcnt(8)
	s_waitcnt lgkmcnt(0)
	s_barrier
	s_setprio 1
	v_mfma_f32_16x16x32_bf16 v[124:127], v[152:155], v[184:187], v[124:127]
	v_mfma_f32_16x16x32_bf16 v[108:111], v[152:155], v[192:195], v[108:111]
	v_mfma_f32_16x16x32_bf16 v[92:95], v[152:155], v[200:203], v[92:95]
	v_mfma_f32_16x16x32_bf16 v[76:79], v[152:155], v[208:211], v[76:79]
	v_mfma_f32_16x16x32_bf16 v[72:75], v[160:163], v[208:211], v[72:75]
	v_mfma_f32_16x16x32_bf16 v[88:91], v[160:163], v[200:203], v[88:91]
	v_mfma_f32_16x16x32_bf16 v[104:107], v[160:163], v[192:195], v[104:107]
	v_mfma_f32_16x16x32_bf16 v[120:123], v[160:163], v[184:187], v[120:123]
	v_mfma_f32_16x16x32_bf16 v[124:127], v[156:159], v[188:191], v[124:127]
	v_mfma_f32_16x16x32_bf16 v[108:111], v[156:159], v[196:199], v[108:111]
	v_mfma_f32_16x16x32_bf16 v[92:95], v[156:159], v[204:207], v[92:95]
	v_mfma_f32_16x16x32_bf16 v[76:79], v[156:159], v[212:215], v[76:79]
	v_mfma_f32_16x16x32_bf16 v[72:75], v[164:167], v[212:215], v[72:75]
	v_mfma_f32_16x16x32_bf16 v[88:91], v[164:167], v[204:207], v[88:91]
	v_mfma_f32_16x16x32_bf16 v[104:107], v[164:167], v[196:199], v[104:107]
	v_mfma_f32_16x16x32_bf16 v[120:123], v[164:167], v[188:191], v[120:123]
	v_mfma_f32_16x16x32_bf16 v[116:119], v[168:171], v[184:187], v[116:119]
	v_mfma_f32_16x16x32_bf16 v[100:103], v[168:171], v[192:195], v[100:103]
	v_mfma_f32_16x16x32_bf16 v[84:87], v[168:171], v[200:203], v[84:87]
	v_mfma_f32_16x16x32_bf16 v[68:71], v[168:171], v[208:211], v[68:71]
	v_mfma_f32_16x16x32_bf16 v[64:67], v[176:179], v[208:211], v[64:67]
	v_mfma_f32_16x16x32_bf16 v[80:83], v[176:179], v[200:203], v[80:83]
	v_mfma_f32_16x16x32_bf16 v[96:99], v[176:179], v[192:195], v[96:99]
	v_mfma_f32_16x16x32_bf16 v[112:115], v[176:179], v[184:187], v[112:115]
	v_mfma_f32_16x16x32_bf16 v[116:119], v[172:175], v[188:191], v[116:119]
	v_mfma_f32_16x16x32_bf16 v[100:103], v[172:175], v[196:199], v[100:103]
	v_mfma_f32_16x16x32_bf16 v[84:87], v[172:175], v[204:207], v[84:87]
	v_mfma_f32_16x16x32_bf16 v[68:71], v[172:175], v[212:215], v[68:71]
	v_mfma_f32_16x16x32_bf16 v[64:67], v[180:183], v[212:215], v[64:67]
	v_mfma_f32_16x16x32_bf16 v[80:83], v[180:183], v[204:207], v[80:83]
	v_mfma_f32_16x16x32_bf16 v[96:99], v[180:183], v[196:199], v[96:99]
	v_mfma_f32_16x16x32_bf16 v[112:115], v[180:183], v[188:191], v[112:115]
	s_setprio 0
	s_barrier
	s_add_i32 s64, s56, s47
	v_lshl_add_u64 v[216:217], s[34:35], 0, v[130:131]
	s_mov_b32 m0, s64
	ds_read_b128 v[184:187], v151 offset:16384
	ds_read_b128 v[188:191], v151 offset:17408
	ds_read_b128 v[192:195], v151 offset:18432
	ds_read_b128 v[196:199], v151 offset:19456
	ds_read_b128 v[200:203], v151 offset:20480
	ds_read_b128 v[204:207], v151 offset:21504
	ds_read_b128 v[208:211], v151 offset:22528
	ds_read_b128 v[212:215], v151 offset:23552
	global_load_lds_dwordx4 v[216:217], off
	s_add_i32 m0, s64, 0x2000
	s_add_u32 s64, s34, 0x80000
	v_lshl_add_u64 v[218:219], s[34:35], 0, v[134:135]
	s_addc_u32 s65, s35, 0
	s_add_i32 s66, s57, s47
	global_load_lds_dwordx4 v[218:219], off
	v_lshl_add_u64 v[220:221], s[64:65], 0, v[130:131]
	s_mov_b32 m0, s66
	v_lshl_add_u64 v[222:223], s[36:37], 0, v[132:133]
	global_load_lds_dwordx4 v[220:221], off
	v_lshl_add_u64 v[220:221], s[64:65], 0, v[134:135]
	s_add_i32 m0, s66, 0x2000
	s_nop 0
	global_load_lds_dwordx4 v[220:221], off
	v_lshl_add_u64 v[220:221], s[36:37], 0, v[128:129]
	s_mov_b32 m0, s48
	s_nop 0
	global_load_lds_dwordx4 v[220:221], off
	s_mov_b32 m0, s49
	s_nop 0
	global_load_lds_dwordx4 v[222:223], off
	s_waitcnt vmcnt(8)
	s_waitcnt lgkmcnt(0)
	s_barrier
	s_setprio 1
	v_mfma_f32_16x16x32_bf16 v[60:63], v[152:155], v[184:187], v[60:63]
	v_mfma_f32_16x16x32_bf16 v[44:47], v[152:155], v[192:195], v[44:47]
	v_mfma_f32_16x16x32_bf16 v[28:31], v[152:155], v[200:203], v[28:31]
	v_mfma_f32_16x16x32_bf16 v[12:15], v[152:155], v[208:211], v[12:15]
	v_mfma_f32_16x16x32_bf16 v[8:11], v[160:163], v[208:211], v[8:11]
	v_mfma_f32_16x16x32_bf16 v[24:27], v[160:163], v[200:203], v[24:27]
	v_mfma_f32_16x16x32_bf16 v[40:43], v[160:163], v[192:195], v[40:43]
	v_mfma_f32_16x16x32_bf16 v[56:59], v[160:163], v[184:187], v[56:59]
	v_mfma_f32_16x16x32_bf16 v[60:63], v[156:159], v[188:191], v[60:63]
	v_mfma_f32_16x16x32_bf16 v[44:47], v[156:159], v[196:199], v[44:47]
	v_mfma_f32_16x16x32_bf16 v[28:31], v[156:159], v[204:207], v[28:31]
	v_mfma_f32_16x16x32_bf16 v[12:15], v[156:159], v[212:215], v[12:15]
	v_mfma_f32_16x16x32_bf16 v[8:11], v[164:167], v[212:215], v[8:11]
	v_mfma_f32_16x16x32_bf16 v[24:27], v[164:167], v[204:207], v[24:27]
	v_mfma_f32_16x16x32_bf16 v[40:43], v[164:167], v[196:199], v[40:43]
	v_mfma_f32_16x16x32_bf16 v[56:59], v[164:167], v[188:191], v[56:59]
	v_mfma_f32_16x16x32_bf16 v[52:55], v[168:171], v[184:187], v[52:55]
	v_mfma_f32_16x16x32_bf16 v[36:39], v[168:171], v[192:195], v[36:39]
	v_mfma_f32_16x16x32_bf16 v[20:23], v[168:171], v[200:203], v[20:23]
	v_mfma_f32_16x16x32_bf16 v[4:7], v[168:171], v[208:211], v[4:7]
	v_mfma_f32_16x16x32_bf16 v[0:3], v[176:179], v[208:211], v[0:3]
	v_mfma_f32_16x16x32_bf16 v[16:19], v[176:179], v[200:203], v[16:19]
	v_mfma_f32_16x16x32_bf16 v[32:35], v[176:179], v[192:195], v[32:35]
	v_mfma_f32_16x16x32_bf16 v[48:51], v[176:179], v[184:187], v[48:51]
	v_mfma_f32_16x16x32_bf16 v[52:55], v[172:175], v[188:191], v[52:55]
	v_mfma_f32_16x16x32_bf16 v[36:39], v[172:175], v[196:199], v[36:39]
	v_mfma_f32_16x16x32_bf16 v[20:23], v[172:175], v[204:207], v[20:23]
	v_mfma_f32_16x16x32_bf16 v[4:7], v[172:175], v[212:215], v[4:7]
	v_mfma_f32_16x16x32_bf16 v[0:3], v[180:183], v[212:215], v[0:3]
	v_mfma_f32_16x16x32_bf16 v[16:19], v[180:183], v[204:207], v[16:19]
	v_mfma_f32_16x16x32_bf16 v[32:35], v[180:183], v[196:199], v[32:35]
	v_mfma_f32_16x16x32_bf16 v[48:51], v[180:183], v[188:191], v[48:51]
	s_setprio 0
	s_barrier
	s_add_i32 s64, 0, 0x18000
	s_add_i32 s65, 0, 0x1c000
	v_add_u32_e32 v164, s64, v150
	v_add_u32_e32 v180, s65, v150
	ds_read_b128 v[152:155], v164
	ds_read_b128 v[156:159], v164 offset:1024
	ds_read_b128 v[160:163], v164 offset:2048
	ds_read_b128 v[164:167], v164 offset:3072
	ds_read_b128 v[168:171], v180
	ds_read_b128 v[172:175], v180 offset:1024
	ds_read_b128 v[176:179], v180 offset:2048
	ds_read_b128 v[180:183], v180 offset:3072
	s_add_u32 s36, s36, 0x80000
	s_addc_u32 s37, s37, 0
	s_mov_b32 m0, s50
	v_lshl_add_u64 v[224:225], s[36:37], 0, v[128:129]
	ds_read_b128 v[184:187], v151 offset:32768
	ds_read_b128 v[188:191], v151 offset:33792
	ds_read_b128 v[192:195], v151 offset:34816
	ds_read_b128 v[196:199], v151 offset:35840
	ds_read_b128 v[200:203], v151 offset:36864
	ds_read_b128 v[204:207], v151 offset:37888
	ds_read_b128 v[208:211], v151 offset:38912
	ds_read_b128 v[212:215], v151 offset:39936
	global_load_lds_dwordx4 v[224:225], off
	v_lshl_add_u64 v[224:225], s[36:37], 0, v[132:133]
	s_mov_b32 m0, s51
	s_nop 0
	global_load_lds_dwordx4 v[224:225], off
	s_waitcnt vmcnt(8)
	s_waitcnt lgkmcnt(0)
	s_barrier
	s_setprio 1
	v_mfma_f32_16x16x32_bf16 v[124:127], v[152:155], v[184:187], v[124:127]
	v_mfma_f32_16x16x32_bf16 v[108:111], v[152:155], v[192:195], v[108:111]
	v_mfma_f32_16x16x32_bf16 v[92:95], v[152:155], v[200:203], v[92:95]
	v_mfma_f32_16x16x32_bf16 v[76:79], v[152:155], v[208:211], v[76:79]
	v_mfma_f32_16x16x32_bf16 v[72:75], v[160:163], v[208:211], v[72:75]
	v_mfma_f32_16x16x32_bf16 v[88:91], v[160:163], v[200:203], v[88:91]
	v_mfma_f32_16x16x32_bf16 v[104:107], v[160:163], v[192:195], v[104:107]
	v_mfma_f32_16x16x32_bf16 v[120:123], v[160:163], v[184:187], v[120:123]
	v_mfma_f32_16x16x32_bf16 v[124:127], v[156:159], v[188:191], v[124:127]
	v_mfma_f32_16x16x32_bf16 v[108:111], v[156:159], v[196:199], v[108:111]
	v_mfma_f32_16x16x32_bf16 v[92:95], v[156:159], v[204:207], v[92:95]
	v_mfma_f32_16x16x32_bf16 v[76:79], v[156:159], v[212:215], v[76:79]
	v_mfma_f32_16x16x32_bf16 v[72:75], v[164:167], v[212:215], v[72:75]
	v_mfma_f32_16x16x32_bf16 v[88:91], v[164:167], v[204:207], v[88:91]
	v_mfma_f32_16x16x32_bf16 v[104:107], v[164:167], v[196:199], v[104:107]
	v_mfma_f32_16x16x32_bf16 v[120:123], v[164:167], v[188:191], v[120:123]
	v_mfma_f32_16x16x32_bf16 v[116:119], v[168:171], v[184:187], v[116:119]
	v_mfma_f32_16x16x32_bf16 v[100:103], v[168:171], v[192:195], v[100:103]
	v_mfma_f32_16x16x32_bf16 v[84:87], v[168:171], v[200:203], v[84:87]
	v_mfma_f32_16x16x32_bf16 v[68:71], v[168:171], v[208:211], v[68:71]
	v_mfma_f32_16x16x32_bf16 v[64:67], v[176:179], v[208:211], v[64:67]
	v_mfma_f32_16x16x32_bf16 v[80:83], v[176:179], v[200:203], v[80:83]
	v_mfma_f32_16x16x32_bf16 v[96:99], v[176:179], v[192:195], v[96:99]
	v_mfma_f32_16x16x32_bf16 v[112:115], v[176:179], v[184:187], v[112:115]
	v_mfma_f32_16x16x32_bf16 v[116:119], v[172:175], v[188:191], v[116:119]
	v_mfma_f32_16x16x32_bf16 v[100:103], v[172:175], v[196:199], v[100:103]
	v_mfma_f32_16x16x32_bf16 v[84:87], v[172:175], v[204:207], v[84:87]
	v_mfma_f32_16x16x32_bf16 v[68:71], v[172:175], v[212:215], v[68:71]
	v_mfma_f32_16x16x32_bf16 v[64:67], v[180:183], v[212:215], v[64:67]
	v_mfma_f32_16x16x32_bf16 v[80:83], v[180:183], v[204:207], v[80:83]
	v_mfma_f32_16x16x32_bf16 v[96:99], v[180:183], v[196:199], v[96:99]
	v_mfma_f32_16x16x32_bf16 v[112:115], v[180:183], v[188:191], v[112:115]
	s_setprio 0
	s_barrier
	s_add_i32 s36, s64, s47
	v_lshl_add_u64 v[216:217], v[216:217], 0, s[18:19]
	s_mov_b32 m0, s36
	ds_read_b128 v[184:187], v151 offset:49152
	ds_read_b128 v[188:191], v151 offset:50176
	ds_read_b128 v[192:195], v151 offset:51200
	ds_read_b128 v[196:199], v151 offset:52224
	ds_read_b128 v[200:203], v151 offset:53248
	ds_read_b128 v[204:207], v151 offset:54272
	ds_read_b128 v[208:211], v151 offset:55296
	ds_read_b128 v[212:215], v151 offset:56320
	global_load_lds_dwordx4 v[216:217], off
	s_add_i32 m0, s36, 0x2000
	s_add_u32 s34, s34, 0x80080
	v_lshl_add_u64 v[216:217], v[218:219], 0, s[18:19]
	s_addc_u32 s35, s35, 0
	s_add_i32 s36, s65, s47
	global_load_lds_dwordx4 v[216:217], off
	v_lshl_add_u64 v[216:217], s[34:35], 0, v[130:131]
	s_mov_b32 m0, s36
	s_nop 0
	global_load_lds_dwordx4 v[216:217], off
	v_lshl_add_u64 v[216:217], s[34:35], 0, v[134:135]
	s_add_i32 m0, s36, 0x2000
	s_nop 0
	global_load_lds_dwordx4 v[216:217], off
	v_lshl_add_u64 v[216:217], v[220:221], 0, s[18:19]
	s_mov_b32 m0, s54
	s_nop 0
	global_load_lds_dwordx4 v[216:217], off
	v_lshl_add_u64 v[216:217], v[222:223], 0, s[18:19]
	s_mov_b32 m0, s55
	s_nop 0
	global_load_lds_dwordx4 v[216:217], off
	s_waitcnt vmcnt(8)
	s_waitcnt lgkmcnt(0)
	s_barrier
	s_setprio 1
	v_mfma_f32_16x16x32_bf16 v[60:63], v[152:155], v[184:187], v[60:63]
	v_mfma_f32_16x16x32_bf16 v[44:47], v[152:155], v[192:195], v[44:47]
	v_mfma_f32_16x16x32_bf16 v[28:31], v[152:155], v[200:203], v[28:31]
	v_mfma_f32_16x16x32_bf16 v[12:15], v[152:155], v[208:211], v[12:15]
	v_mfma_f32_16x16x32_bf16 v[8:11], v[160:163], v[208:211], v[8:11]
	v_mfma_f32_16x16x32_bf16 v[24:27], v[160:163], v[200:203], v[24:27]
	v_mfma_f32_16x16x32_bf16 v[40:43], v[160:163], v[192:195], v[40:43]
	v_mfma_f32_16x16x32_bf16 v[56:59], v[160:163], v[184:187], v[56:59]
	v_mfma_f32_16x16x32_bf16 v[60:63], v[156:159], v[188:191], v[60:63]
	v_mfma_f32_16x16x32_bf16 v[44:47], v[156:159], v[196:199], v[44:47]
	v_mfma_f32_16x16x32_bf16 v[28:31], v[156:159], v[204:207], v[28:31]
	v_mfma_f32_16x16x32_bf16 v[12:15], v[156:159], v[212:215], v[12:15]
	v_mfma_f32_16x16x32_bf16 v[8:11], v[164:167], v[212:215], v[8:11]
	v_mfma_f32_16x16x32_bf16 v[24:27], v[164:167], v[204:207], v[24:27]
	v_mfma_f32_16x16x32_bf16 v[40:43], v[164:167], v[196:199], v[40:43]
	v_mfma_f32_16x16x32_bf16 v[56:59], v[164:167], v[188:191], v[56:59]
	v_mfma_f32_16x16x32_bf16 v[52:55], v[168:171], v[184:187], v[52:55]
	v_mfma_f32_16x16x32_bf16 v[36:39], v[168:171], v[192:195], v[36:39]
	v_mfma_f32_16x16x32_bf16 v[20:23], v[168:171], v[200:203], v[20:23]
	v_mfma_f32_16x16x32_bf16 v[4:7], v[168:171], v[208:211], v[4:7]
	v_mfma_f32_16x16x32_bf16 v[0:3], v[176:179], v[208:211], v[0:3]
	v_mfma_f32_16x16x32_bf16 v[16:19], v[176:179], v[200:203], v[16:19]
	v_mfma_f32_16x16x32_bf16 v[32:35], v[176:179], v[192:195], v[32:35]
	v_mfma_f32_16x16x32_bf16 v[48:51], v[176:179], v[184:187], v[48:51]
	v_mfma_f32_16x16x32_bf16 v[52:55], v[172:175], v[188:191], v[52:55]
	v_mfma_f32_16x16x32_bf16 v[36:39], v[172:175], v[196:199], v[36:39]
	v_mfma_f32_16x16x32_bf16 v[20:23], v[172:175], v[204:207], v[20:23]
	v_mfma_f32_16x16x32_bf16 v[4:7], v[172:175], v[212:215], v[4:7]
	v_mfma_f32_16x16x32_bf16 v[0:3], v[180:183], v[212:215], v[0:3]
	v_mfma_f32_16x16x32_bf16 v[16:19], v[180:183], v[204:207], v[16:19]
	v_mfma_f32_16x16x32_bf16 v[32:35], v[180:183], v[196:199], v[32:35]
	v_mfma_f32_16x16x32_bf16 v[48:51], v[180:183], v[188:191], v[48:51]
	s_setprio 0
	s_barrier
	s_add_i32 s63, s63, 2
	s_add_u32 s30, s30, 0x100
	s_addc_u32 s31, s31, 0
	s_cmp_gt_u32 s63, 29
	s_cbranch_scc0 .LBB0_1227
	s_add_u32 s30, s59, 0xffffff00
	s_addc_u32 s31, s60, -1
	s_andn2_b64 vcc, exec, s[4:5]
	s_cbranch_vccnz .LBB0_1230
	v_mov_b32_e32 v0, 0
	s_mov_b32 s15, s20
	s_mov_b32 s14, s22
	s_mov_b64 s[16:17], s[26:27]
	s_mov_b32 s53, s58
	v_mov_b32_e32 v1, v0
	v_mov_b32_e32 v2, v0
	v_mov_b32_e32 v3, v0
	v_mov_b32_e32 v4, v0
	v_mov_b32_e32 v5, v0
	v_mov_b32_e32 v6, v0
	v_mov_b32_e32 v7, v0
	v_mov_b32_e32 v16, v0
	v_mov_b32_e32 v17, v0
	v_mov_b32_e32 v18, v0
	v_mov_b32_e32 v19, v0
	v_mov_b32_e32 v20, v0
	v_mov_b32_e32 v21, v0
	v_mov_b32_e32 v22, v0
	v_mov_b32_e32 v23, v0
	v_mov_b32_e32 v32, v0
	v_mov_b32_e32 v33, v0
	v_mov_b32_e32 v34, v0
	v_mov_b32_e32 v35, v0
	v_mov_b32_e32 v36, v0
	v_mov_b32_e32 v37, v0
	v_mov_b32_e32 v38, v0
	v_mov_b32_e32 v39, v0
	v_mov_b32_e32 v48, v0
	v_mov_b32_e32 v49, v0
	v_mov_b32_e32 v50, v0
	v_mov_b32_e32 v51, v0
	v_mov_b32_e32 v52, v0
	v_mov_b32_e32 v53, v0
	v_mov_b32_e32 v54, v0
	v_mov_b32_e32 v55, v0
	v_mov_b32_e32 v8, v0
	v_mov_b32_e32 v9, v0
	v_mov_b32_e32 v10, v0
	v_mov_b32_e32 v11, v0
	v_mov_b32_e32 v12, v0
	v_mov_b32_e32 v13, v0
	v_mov_b32_e32 v14, v0
	v_mov_b32_e32 v15, v0
	v_mov_b32_e32 v24, v0
	v_mov_b32_e32 v25, v0
	v_mov_b32_e32 v26, v0
	v_mov_b32_e32 v27, v0
	v_mov_b32_e32 v28, v0
	v_mov_b32_e32 v29, v0
	v_mov_b32_e32 v30, v0
	v_mov_b32_e32 v31, v0
	v_mov_b32_e32 v40, v0
	v_mov_b32_e32 v41, v0
	v_mov_b32_e32 v42, v0
	v_mov_b32_e32 v43, v0
	v_mov_b32_e32 v44, v0
	v_mov_b32_e32 v45, v0
	v_mov_b32_e32 v46, v0
	v_mov_b32_e32 v47, v0
	v_mov_b32_e32 v56, v0
	v_mov_b32_e32 v57, v0
	v_mov_b32_e32 v58, v0
	v_mov_b32_e32 v59, v0
	v_mov_b32_e32 v60, v0
	v_mov_b32_e32 v61, v0
	v_mov_b32_e32 v62, v0
	v_mov_b32_e32 v63, v0
	v_mov_b32_e32 v64, v0
	v_mov_b32_e32 v65, v0
	v_mov_b32_e32 v66, v0
	v_mov_b32_e32 v67, v0
	v_mov_b32_e32 v68, v0
	v_mov_b32_e32 v69, v0
	v_mov_b32_e32 v70, v0
	v_mov_b32_e32 v71, v0
	v_mov_b32_e32 v80, v0
	v_mov_b32_e32 v81, v0
	v_mov_b32_e32 v82, v0
	v_mov_b32_e32 v83, v0
	v_mov_b32_e32 v84, v0
	v_mov_b32_e32 v85, v0
	v_mov_b32_e32 v86, v0
	v_mov_b32_e32 v87, v0
	v_mov_b32_e32 v96, v0
	v_mov_b32_e32 v97, v0
	v_mov_b32_e32 v98, v0
	v_mov_b32_e32 v99, v0
	v_mov_b32_e32 v100, v0
	v_mov_b32_e32 v101, v0
	v_mov_b32_e32 v102, v0
	v_mov_b32_e32 v103, v0
	v_mov_b32_e32 v112, v0
	v_mov_b32_e32 v113, v0
	v_mov_b32_e32 v114, v0
	v_mov_b32_e32 v115, v0
	v_mov_b32_e32 v116, v0
	v_mov_b32_e32 v117, v0
	v_mov_b32_e32 v118, v0
	v_mov_b32_e32 v119, v0
	v_mov_b32_e32 v72, v0
	v_mov_b32_e32 v73, v0
	v_mov_b32_e32 v74, v0
	v_mov_b32_e32 v75, v0
	v_mov_b32_e32 v76, v0
	v_mov_b32_e32 v77, v0
	v_mov_b32_e32 v78, v0
	v_mov_b32_e32 v79, v0
	v_mov_b32_e32 v88, v0
	v_mov_b32_e32 v89, v0
	v_mov_b32_e32 v90, v0
	v_mov_b32_e32 v91, v0
	v_mov_b32_e32 v92, v0
	v_mov_b32_e32 v93, v0
	v_mov_b32_e32 v94, v0
	v_mov_b32_e32 v95, v0
	v_mov_b32_e32 v104, v0
	v_mov_b32_e32 v105, v0
	v_mov_b32_e32 v106, v0
	v_mov_b32_e32 v107, v0
	v_mov_b32_e32 v108, v0
	v_mov_b32_e32 v109, v0
	v_mov_b32_e32 v110, v0
	v_mov_b32_e32 v111, v0
	v_mov_b32_e32 v120, v0
	v_mov_b32_e32 v121, v0
	v_mov_b32_e32 v122, v0
	v_mov_b32_e32 v123, v0
	v_mov_b32_e32 v124, v0
	v_mov_b32_e32 v125, v0
	v_mov_b32_e32 v126, v0
	v_mov_b32_e32 v127, v0
	s_andn2_b64 vcc, exec, s[0:1]
	s_cbranch_vccnz .LBB0_1231
	s_branch .LBB0_1232
